# epilogue rstd loads hoisted (one wait instead of 8 serialized load+vmcnt(0) round trips) in FFN2-up, uq, ukv and w_in gelu epilogues
# speedup vs baseline: 1.0447x; 1.0148x over previous
; __device__ __forceinline__ unsigned cvt_pk(float lo, float hi) { unsigned r; asm volatile("v_cvt_pk_bf16_f32 %0, %1, %2" : "=v"(r) : "v"(lo), "v"(hi)); return r; }
; __device__ __forceinline__ float gelu_f(float x) {
;     const float t = x * (1.f + 0.044715f * x * x);
;     return x * __builtin_amdgcn_rcpf(1.f + __builtin_amdgcn_exp2f(-2.3022081986f * t));
; }
; __device__ __forceinline__ float sq4(f32x4 a) { return (a.x * a.x + a.y * a.y) + (a.z * a.z + a.w * a.w); }
; __device__ __forceinline__ u32x4 pack8(f32x4 a, f32x4 b) { u32x4 o; o.x = cvt_pk(a.x, a.y); o.y = cvt_pk(a.z, a.w); o.z = cvt_pk(b.x, b.y); o.w = cvt_pk(b.z, b.w); return o; }
; __device__ __forceinline__ float rstd_of(const float* SS, int row, float invw) { return 1.0f / sqrtf(SS[row] * invw + EPS); }
;     __device__ __forceinline__ void operator()(const f32x4 (&acc)[2][2][4][2], const pg8::Unit& u, int wr, int wc, int fr, int fq) const {
;     ...
;         if (u.pn < 4) {
;             bf16_t* dst = (u.pn < 2 ? GU : GV) + (u.pn & 1) * 256 + colw;
; #pragma unroll
;             for (int ai = 0; ai < 2; ++ai)
; #pragma unroll
;                 for (int m = 0; m < 4; ++m) {
;                     const int row = row0 + ai * 128 + m * 16; const float r = rstd_of(SS1, row, 1.f / 1024.f);
; #pragma unroll
;                     for (int bj = 0; bj < 2; ++bj) {
;                         const f32x4 a = acc[ai][bj][m][0] * r, b = acc[ai][bj][m][1] * r;
;                         f32x4 ga, gb; ga.x = gelu_f(a.x); ga.y = gelu_f(a.y); ga.z = gelu_f(a.z); ga.w = gelu_f(a.w);
;                         gb.x = gelu_f(b.x); gb.y = gelu_f(b.y); gb.z = gelu_f(b.z); gb.w = gelu_f(b.w);
;                         *(u32x4*)(dst + (size_t)row * 512 + bj * 128) = pack8(ga, gb);
;                     }
;                 }
.LBB0_404:
	v_lshl_add_u64 v[156:157], v[152:153], 2, s[48:49]
	global_load_dword v200, v[156:157], off
	global_load_dword v201, v[156:157], off offset:64
	global_load_dword v202, v[156:157], off offset:128
	global_load_dword v203, v[156:157], off offset:192
	global_load_dword v204, v[156:157], off offset:512
	global_load_dword v205, v[156:157], off offset:576
	global_load_dword v206, v[156:157], off offset:640
	global_load_dword v207, v[156:157], off offset:704
	s_cmp_lt_i32 s58, 2
	s_cselect_b32 s1, s65, s23
	s_cselect_b32 s0, s64, s22
	s_lshl_b32 s4, s58, 9
	s_and_b32 s4, s4, 0x200
	s_add_u32 s0, s0, s4
	s_addc_u32 s1, s1, 0
	v_lshl_add_u64 v[158:159], s[0:1], 0, v[136:137]
	s_waitcnt vmcnt(0)
	v_mov_b32_e32 v154, v200
	v_fmamk_f32 v154, v154, 0x3a800000, v172
	v_cmp_gt_f32_e32 vcc, s82, v154
	s_waitcnt lgkmcnt(0)
	v_mul_f32_e32 v155, 0x4f800000, v154
	v_cndmask_b32_e32 v154, v154, v155, vcc
	v_sqrt_f32_e32 v155, v154
	s_nop 0
	v_add_u32_e32 v160, -1, v155
	v_fma_f32 v161, -v160, v155, v154
	v_cmp_ge_f32_e64 s[0:1], 0, v161
	v_add_u32_e32 v161, 1, v155
	s_nop 0
	v_cndmask_b32_e64 v160, v155, v160, s[0:1]
	v_fma_f32 v155, -v161, v155, v154
	v_cmp_lt_f32_e64 s[0:1], 0, v155
	s_nop 1
	v_cndmask_b32_e64 v155, v160, v161, s[0:1]
	v_mul_f32_e32 v160, 0x37800000, v155
	v_cndmask_b32_e32 v155, v155, v160, vcc
	v_cmp_class_f32_e32 vcc, v154, v173
	s_nop 1
	v_cndmask_b32_e32 v154, v155, v154, vcc
	v_div_scale_f32 v155, s[0:1], v154, v154, 1.0
	v_rcp_f32_e32 v160, v155
	s_nop 0
	v_fma_f32 v161, -v155, v160, 1.0
	v_fmac_f32_e32 v160, v161, v160
	v_div_scale_f32 v161, vcc, 1.0, v154, 1.0
	v_mul_f32_e32 v162, v161, v160
	v_fma_f32 v163, -v155, v162, v161
	v_fmac_f32_e32 v162, v163, v160
	v_fma_f32 v155, -v155, v162, v161
	v_div_fmas_f32 v155, v155, v160, v162
	v_div_fixup_f32 v160, v155, v154, 1.0
	v_pk_mul_f32 v[124:125], v[124:125], v[160:161] op_sel_hi:[1,0]
	v_lshlrev_b64 v[154:155], 10, v[152:153]
	v_mul_f32_e32 v153, 0x3d372713, v124
	v_fma_f32 v153, v124, v153, 1.0
	v_mul_f32_e32 v153, v124, v153
	v_mul_f32_e32 v153, 0xc0135761, v153
	v_exp_f32_e32 v153, v153
	v_pk_mul_f32 v[126:127], v[126:127], v[160:161] op_sel_hi:[1,0]
	v_pk_mul_f32 v[120:121], v[120:121], v[160:161] op_sel_hi:[1,0]
	v_pk_mul_f32 v[122:123], v[122:123], v[160:161] op_sel_hi:[1,0]
	v_add_f32_e32 v153, 1.0, v153
	v_rcp_f32_e32 v153, v153
	v_lshl_add_u64 v[154:155], v[158:159], 0, v[154:155]
	v_mul_f32_e32 v124, v124, v153
	v_mul_f32_e32 v153, 0x3d372713, v125
	v_fma_f32 v153, v125, v153, 1.0
	v_mul_f32_e32 v153, v125, v153
	v_mul_f32_e32 v153, 0xc0135761, v153
	v_exp_f32_e32 v153, v153
	s_nop 0
	v_add_f32_e32 v153, 1.0, v153
	v_rcp_f32_e32 v153, v153
	s_nop 0
	v_mul_f32_e32 v125, v125, v153
	v_mul_f32_e32 v153, 0x3d372713, v126
	v_fma_f32 v153, v126, v153, 1.0
	v_mul_f32_e32 v153, v126, v153
	v_mul_f32_e32 v153, 0xc0135761, v153
	v_exp_f32_e32 v153, v153
	s_nop 0
	v_add_f32_e32 v153, 1.0, v153
	v_rcp_f32_e32 v153, v153
	s_nop 0
	v_mul_f32_e32 v126, v126, v153
	v_mul_f32_e32 v153, 0x3d372713, v127
	v_fma_f32 v153, v127, v153, 1.0
	v_mul_f32_e32 v153, v127, v153
	v_mul_f32_e32 v153, 0xc0135761, v153
	v_exp_f32_e32 v153, v153
	s_nop 0
	v_add_f32_e32 v153, 1.0, v153
	v_rcp_f32_e32 v153, v153
	s_nop 0
	v_mul_f32_e32 v127, v127, v153
	v_mul_f32_e32 v153, 0x3d372713, v120
	v_fma_f32 v153, v120, v153, 1.0
	v_mul_f32_e32 v153, v120, v153
	v_mul_f32_e32 v153, 0xc0135761, v153
	v_exp_f32_e32 v153, v153
	s_nop 0
	v_add_f32_e32 v153, 1.0, v153
	v_rcp_f32_e32 v153, v153
	s_nop 0
	v_mul_f32_e32 v153, v120, v153
	v_mul_f32_e32 v120, 0x3d372713, v121
	v_fma_f32 v120, v121, v120, 1.0
	v_mul_f32_e32 v120, v121, v120
	v_mul_f32_e32 v120, 0xc0135761, v120
	v_exp_f32_e32 v120, v120
	s_nop 0
	v_add_f32_e32 v120, 1.0, v120
	v_rcp_f32_e32 v120, v120
	s_nop 0
	v_mul_f32_e32 v161, v121, v120
	v_mul_f32_e32 v120, 0x3d372713, v122
	v_fma_f32 v120, v122, v120, 1.0
	v_mul_f32_e32 v120, v122, v120
	v_mul_f32_e32 v120, 0xc0135761, v120
	v_exp_f32_e32 v120, v120
	v_pk_mul_f32 v[116:117], v[116:117], v[160:161] op_sel_hi:[1,0]
	v_pk_mul_f32 v[118:119], v[118:119], v[160:161] op_sel_hi:[1,0]
	v_pk_mul_f32 v[112:113], v[112:113], v[160:161] op_sel_hi:[1,0]
	v_add_f32_e32 v120, 1.0, v120
	v_rcp_f32_e32 v120, v120
	v_pk_mul_f32 v[114:115], v[114:115], v[160:161] op_sel_hi:[1,0]
	v_mul_f32_e32 v162, v122, v120
	v_mul_f32_e32 v120, 0x3d372713, v123
	v_fma_f32 v120, v123, v120, 1.0
	v_mul_f32_e32 v120, v123, v120
	v_mul_f32_e32 v120, 0xc0135761, v120
	v_exp_f32_e32 v120, v120
	s_nop 0
	v_add_f32_e32 v120, 1.0, v120
	v_rcp_f32_e32 v120, v120
	s_nop 0
	v_mul_f32_e32 v123, v123, v120
	v_cvt_pk_bf16_f32 v120, v124, v125
	v_cvt_pk_bf16_f32 v121, v126, v127
	v_cvt_pk_bf16_f32 v122, v153, v161
	v_cvt_pk_bf16_f32 v123, v162, v123
	global_store_dwordx4 v[154:155], v[120:123], off
	s_nop 1
	v_mul_f32_e32 v120, 0x3d372713, v116
	v_fma_f32 v120, v116, v120, 1.0
	v_mul_f32_e32 v120, v116, v120
	v_mul_f32_e32 v120, 0xc0135761, v120
	v_exp_f32_e32 v120, v120
	s_nop 0
	v_add_f32_e32 v120, 1.0, v120
	v_rcp_f32_e32 v120, v120
	s_nop 0
	v_mul_f32_e32 v116, v116, v120
	v_mul_f32_e32 v120, 0x3d372713, v117
	v_fma_f32 v120, v117, v120, 1.0
	v_mul_f32_e32 v120, v117, v120
	v_mul_f32_e32 v120, 0xc0135761, v120
	v_exp_f32_e32 v120, v120
	s_nop 0
	v_add_f32_e32 v120, 1.0, v120
	v_rcp_f32_e32 v120, v120
	s_nop 0
	v_mul_f32_e32 v117, v117, v120
	v_mul_f32_e32 v120, 0x3d372713, v118
	v_fma_f32 v120, v118, v120, 1.0
	v_mul_f32_e32 v120, v118, v120
	v_mul_f32_e32 v120, 0xc0135761, v120
	v_exp_f32_e32 v120, v120
	s_nop 0
	v_add_f32_e32 v120, 1.0, v120
	v_rcp_f32_e32 v120, v120
	s_nop 0
	v_mul_f32_e32 v118, v118, v120
	v_mul_f32_e32 v120, 0x3d372713, v119
; __device__ __forceinline__ u32x4 pack8(f32x4 a, f32x4 b) { u32x4 o; o.x = cvt_pk(a.x, a.y); o.y = cvt_pk(a.z, a.w); o.z = cvt_pk(b.x, b.y); o.w = cvt_pk(b.z, b.w); return o; }
; __device__ __forceinline__ float rstd_of(const float* SS, int row, float invw) { return 1.0f / sqrtf(SS[row] * invw + EPS); }
; __device__ __forceinline__ float gelu_f(float x) {
;     const float t = x * (1.f + 0.044715f * x * x);
;     return x * __builtin_amdgcn_rcpf(1.f + __builtin_amdgcn_exp2f(-2.3022081986f * t));
; }
;     __device__ __forceinline__ void operator()(const f32x4 (&acc)[2][2][4][2], const pg8::Unit& u, int wr, int wc, int fr, int fq) const {
;     ...
;             for (int ai = 0; ai < 2; ++ai)
; #pragma unroll
;                 for (int m = 0; m < 4; ++m) {
;                     const int row = row0 + ai * 128 + m * 16; const float r = rstd_of(SS1, row, 1.f / 1024.f);
; #pragma unroll
;                     for (int bj = 0; bj < 2; ++bj) {
;                         const f32x4 a = acc[ai][bj][m][0] * r, b = acc[ai][bj][m][1] * r;
;                         f32x4 ga, gb; ga.x = gelu_f(a.x); ga.y = gelu_f(a.y); ga.z = gelu_f(a.z); ga.w = gelu_f(a.w);
;                         gb.x = gelu_f(b.x); gb.y = gelu_f(b.y); gb.z = gelu_f(b.z); gb.w = gelu_f(b.w);
;                         *(u32x4*)(dst + (size_t)row * 512 + bj * 128) = pack8(ga, gb);
;                     }
;                 }
	v_fma_f32 v120, v119, v120, 1.0
	v_mul_f32_e32 v120, v119, v120
	v_mul_f32_e32 v120, 0xc0135761, v120
	v_exp_f32_e32 v120, v120
	s_nop 0
	v_add_f32_e32 v120, 1.0, v120
	v_rcp_f32_e32 v120, v120
	s_nop 0
	v_mul_f32_e32 v119, v119, v120
	v_mul_f32_e32 v120, 0x3d372713, v112
	v_fma_f32 v120, v112, v120, 1.0
	v_mul_f32_e32 v120, v112, v120
	v_mul_f32_e32 v120, 0xc0135761, v120
	v_exp_f32_e32 v120, v120
	s_nop 0
	v_add_f32_e32 v120, 1.0, v120
	v_rcp_f32_e32 v120, v120
	s_nop 0
	v_mul_f32_e32 v120, v112, v120
	v_mul_f32_e32 v112, 0x3d372713, v113
	v_fma_f32 v112, v113, v112, 1.0
	v_mul_f32_e32 v112, v113, v112
	v_mul_f32_e32 v112, 0xc0135761, v112
	v_exp_f32_e32 v112, v112
	s_nop 0
	v_add_f32_e32 v112, 1.0, v112
	v_rcp_f32_e32 v112, v112
	s_nop 0
	v_mul_f32_e32 v121, v113, v112
	v_mul_f32_e32 v112, 0x3d372713, v114
	v_fma_f32 v112, v114, v112, 1.0
	v_mul_f32_e32 v112, v114, v112
	v_mul_f32_e32 v112, 0xc0135761, v112
	v_exp_f32_e32 v112, v112
	s_nop 0
	v_add_f32_e32 v112, 1.0, v112
	v_rcp_f32_e32 v112, v112
	s_nop 0
	v_mul_f32_e32 v122, v114, v112
	v_mul_f32_e32 v112, 0x3d372713, v115
	v_fma_f32 v112, v115, v112, 1.0
	v_mul_f32_e32 v112, v115, v112
	v_mul_f32_e32 v112, 0xc0135761, v112
	v_exp_f32_e32 v112, v112
	s_nop 0
	v_add_f32_e32 v112, 1.0, v112
	v_rcp_f32_e32 v112, v112
	s_nop 0
	v_mul_f32_e32 v115, v115, v112
	v_cvt_pk_bf16_f32 v112, v116, v117
	v_cvt_pk_bf16_f32 v113, v118, v119
	v_cvt_pk_bf16_f32 v114, v120, v121
	v_cvt_pk_bf16_f32 v115, v122, v115
	global_store_dwordx4 v[154:155], v[112:115], off offset:256
	s_nop 1
	v_or_b32_e32 v112, 16, v152
	v_ashrrev_i32_e32 v113, 31, v112
	v_lshl_add_u64 v[114:115], v[112:113], 2, s[48:49]
	s_nop 1
	v_lshlrev_b64 v[112:113], 10, v[112:113]
	v_lshl_add_u64 v[112:113], v[158:159], 0, v[112:113]
	v_mov_b32_e32 v114, v201
	v_fmamk_f32 v114, v114, 0x3a800000, v172
	v_cmp_gt_f32_e32 vcc, s82, v114
	v_mul_f32_e32 v115, 0x4f800000, v114
	s_nop 0
	v_cndmask_b32_e32 v114, v114, v115, vcc
	v_sqrt_f32_e32 v115, v114
	s_nop 0
	v_add_u32_e32 v116, -1, v115
	v_fma_f32 v117, -v116, v115, v114
	v_cmp_ge_f32_e64 s[0:1], 0, v117
	v_add_u32_e32 v117, 1, v115
	s_nop 0
	v_cndmask_b32_e64 v116, v115, v116, s[0:1]
	v_fma_f32 v115, -v117, v115, v114
	v_cmp_lt_f32_e64 s[0:1], 0, v115
	s_nop 1
	v_cndmask_b32_e64 v115, v116, v117, s[0:1]
	v_mul_f32_e32 v116, 0x37800000, v115
	v_cndmask_b32_e32 v115, v115, v116, vcc
	v_cmp_class_f32_e32 vcc, v114, v173
	s_nop 1
	v_cndmask_b32_e32 v114, v115, v114, vcc
	v_div_scale_f32 v115, s[0:1], v114, v114, 1.0
	v_rcp_f32_e32 v116, v115
	s_nop 0
	v_fma_f32 v117, -v115, v116, 1.0
	v_fmac_f32_e32 v116, v117, v116
	v_div_scale_f32 v117, vcc, 1.0, v114, 1.0
	v_mul_f32_e32 v118, v117, v116
	v_fma_f32 v119, -v115, v118, v117
	v_fmac_f32_e32 v118, v119, v116
	v_fma_f32 v115, -v115, v118, v117
	v_div_fmas_f32 v115, v115, v116, v118
	v_div_fixup_f32 v114, v115, v114, 1.0
	v_pk_mul_f32 v[108:109], v[108:109], v[114:115] op_sel_hi:[1,0]
	v_pk_mul_f32 v[110:111], v[110:111], v[114:115] op_sel_hi:[1,0]
	v_pk_mul_f32 v[106:107], v[106:107], v[114:115] op_sel_hi:[1,0]
	v_pk_mul_f32 v[104:105], v[104:105], v[114:115] op_sel_hi:[1,0]
	v_mul_f32_e32 v115, 0x3d372713, v108
	v_fma_f32 v115, v108, v115, 1.0
	v_mul_f32_e32 v115, v108, v115
	v_mul_f32_e32 v115, 0xc0135761, v115
	v_exp_f32_e32 v115, v115
	s_nop 0
	v_add_f32_e32 v115, 1.0, v115
	v_rcp_f32_e32 v115, v115
	s_nop 0
	v_mul_f32_e32 v108, v108, v115
	v_mul_f32_e32 v115, 0x3d372713, v109
	v_fma_f32 v115, v109, v115, 1.0
	v_mul_f32_e32 v115, v109, v115
	v_mul_f32_e32 v115, 0xc0135761, v115
	v_exp_f32_e32 v115, v115
	s_nop 0
	v_add_f32_e32 v115, 1.0, v115
	v_rcp_f32_e32 v115, v115
	s_nop 0
	v_mul_f32_e32 v109, v109, v115
	v_mul_f32_e32 v115, 0x3d372713, v110
	v_fma_f32 v115, v110, v115, 1.0
	v_mul_f32_e32 v115, v110, v115
	v_mul_f32_e32 v115, 0xc0135761, v115
	v_exp_f32_e32 v115, v115
	s_nop 0
	v_add_f32_e32 v115, 1.0, v115
	v_rcp_f32_e32 v115, v115
	s_nop 0
	v_mul_f32_e32 v110, v110, v115
	v_mul_f32_e32 v115, 0x3d372713, v111
	v_fma_f32 v115, v111, v115, 1.0
	v_mul_f32_e32 v115, v111, v115
	v_mul_f32_e32 v115, 0xc0135761, v115
	v_exp_f32_e32 v115, v115
	s_nop 0
	v_add_f32_e32 v115, 1.0, v115
	v_rcp_f32_e32 v115, v115
	s_nop 0
	v_mul_f32_e32 v111, v111, v115
	v_mul_f32_e32 v115, 0x3d372713, v104
	v_fma_f32 v115, v104, v115, 1.0
	v_mul_f32_e32 v115, v104, v115
	v_mul_f32_e32 v115, 0xc0135761, v115
	v_exp_f32_e32 v115, v115
	s_nop 0
	v_add_f32_e32 v115, 1.0, v115
	v_rcp_f32_e32 v115, v115
	s_nop 0
	v_mul_f32_e32 v115, v104, v115
	v_mul_f32_e32 v104, 0x3d372713, v105
	v_fma_f32 v104, v105, v104, 1.0
	v_mul_f32_e32 v104, v105, v104
	v_mul_f32_e32 v104, 0xc0135761, v104
	v_exp_f32_e32 v104, v104
	v_pk_mul_f32 v[100:101], v[100:101], v[114:115] op_sel_hi:[1,0]
	v_pk_mul_f32 v[102:103], v[102:103], v[114:115] op_sel_hi:[1,0]
	v_pk_mul_f32 v[96:97], v[96:97], v[114:115] op_sel_hi:[1,0]
	v_add_f32_e32 v104, 1.0, v104
	v_rcp_f32_e32 v104, v104
	v_pk_mul_f32 v[98:99], v[98:99], v[114:115] op_sel_hi:[1,0]
	v_mul_f32_e32 v116, v105, v104
	v_mul_f32_e32 v104, 0x3d372713, v106
	v_fma_f32 v104, v106, v104, 1.0
	v_mul_f32_e32 v104, v106, v104
	v_mul_f32_e32 v104, 0xc0135761, v104
	v_exp_f32_e32 v104, v104
	s_nop 0
	v_add_f32_e32 v104, 1.0, v104
	v_rcp_f32_e32 v104, v104
	s_nop 0
	v_mul_f32_e32 v117, v106, v104
	v_mul_f32_e32 v104, 0x3d372713, v107
	v_fma_f32 v104, v107, v104, 1.0
	v_mul_f32_e32 v104, v107, v104
	v_mul_f32_e32 v104, 0xc0135761, v104
	v_exp_f32_e32 v104, v104
	s_nop 0
	v_add_f32_e32 v104, 1.0, v104
	v_rcp_f32_e32 v104, v104
	s_nop 0
	v_mul_f32_e32 v107, v107, v104
	v_cvt_pk_bf16_f32 v104, v108, v109
	v_cvt_pk_bf16_f32 v105, v110, v111
; __device__ __forceinline__ u32x4 pack8(f32x4 a, f32x4 b) { u32x4 o; o.x = cvt_pk(a.x, a.y); o.y = cvt_pk(a.z, a.w); o.z = cvt_pk(b.x, b.y); o.w = cvt_pk(b.z, b.w); return o; }
; __device__ __forceinline__ float rstd_of(const float* SS, int row, float invw) { return 1.0f / sqrtf(SS[row] * invw + EPS); }
; __device__ __forceinline__ float gelu_f(float x) {
;     const float t = x * (1.f + 0.044715f * x * x);
;     return x * __builtin_amdgcn_rcpf(1.f + __builtin_amdgcn_exp2f(-2.3022081986f * t));
; }
;     __device__ __forceinline__ void operator()(const f32x4 (&acc)[2][2][4][2], const pg8::Unit& u, int wr, int wc, int fr, int fq) const {
;     ...
;             for (int ai = 0; ai < 2; ++ai)
; #pragma unroll
;                 for (int m = 0; m < 4; ++m) {
;                     const int row = row0 + ai * 128 + m * 16; const float r = rstd_of(SS1, row, 1.f / 1024.f);
; #pragma unroll
;                     for (int bj = 0; bj < 2; ++bj) {
;                         const f32x4 a = acc[ai][bj][m][0] * r, b = acc[ai][bj][m][1] * r;
;                         f32x4 ga, gb; ga.x = gelu_f(a.x); ga.y = gelu_f(a.y); ga.z = gelu_f(a.z); ga.w = gelu_f(a.w);
;                         gb.x = gelu_f(b.x); gb.y = gelu_f(b.y); gb.z = gelu_f(b.z); gb.w = gelu_f(b.w);
;                         *(u32x4*)(dst + (size_t)row * 512 + bj * 128) = pack8(ga, gb);
;                     }
;                 }
	v_cvt_pk_bf16_f32 v106, v115, v116
	v_cvt_pk_bf16_f32 v107, v117, v107
	global_store_dwordx4 v[112:113], v[104:107], off
	s_nop 1
	v_mul_f32_e32 v104, 0x3d372713, v100
	v_fma_f32 v104, v100, v104, 1.0
	v_mul_f32_e32 v104, v100, v104
	v_mul_f32_e32 v104, 0xc0135761, v104
	v_exp_f32_e32 v104, v104
	s_nop 0
	v_add_f32_e32 v104, 1.0, v104
	v_rcp_f32_e32 v104, v104
	s_nop 0
	v_mul_f32_e32 v100, v100, v104
	v_mul_f32_e32 v104, 0x3d372713, v101
	v_fma_f32 v104, v101, v104, 1.0
	v_mul_f32_e32 v104, v101, v104
	v_mul_f32_e32 v104, 0xc0135761, v104
	v_exp_f32_e32 v104, v104
	s_nop 0
	v_add_f32_e32 v104, 1.0, v104
	v_rcp_f32_e32 v104, v104
	s_nop 0
	v_mul_f32_e32 v101, v101, v104
	v_mul_f32_e32 v104, 0x3d372713, v102
	v_fma_f32 v104, v102, v104, 1.0
	v_mul_f32_e32 v104, v102, v104
	v_mul_f32_e32 v104, 0xc0135761, v104
	v_exp_f32_e32 v104, v104
	s_nop 0
	v_add_f32_e32 v104, 1.0, v104
	v_rcp_f32_e32 v104, v104
	s_nop 0
	v_mul_f32_e32 v102, v102, v104
	v_mul_f32_e32 v104, 0x3d372713, v103
	v_fma_f32 v104, v103, v104, 1.0
	v_mul_f32_e32 v104, v103, v104
	v_mul_f32_e32 v104, 0xc0135761, v104
	v_exp_f32_e32 v104, v104
	s_nop 0
	v_add_f32_e32 v104, 1.0, v104
	v_rcp_f32_e32 v104, v104
	s_nop 0
	v_mul_f32_e32 v103, v103, v104
	v_mul_f32_e32 v104, 0x3d372713, v96
	v_fma_f32 v104, v96, v104, 1.0
	v_mul_f32_e32 v104, v96, v104
	v_mul_f32_e32 v104, 0xc0135761, v104
	v_exp_f32_e32 v104, v104
	s_nop 0
	v_add_f32_e32 v104, 1.0, v104
	v_rcp_f32_e32 v104, v104
	s_nop 0
	v_mul_f32_e32 v104, v96, v104
	v_mul_f32_e32 v96, 0x3d372713, v97
	v_fma_f32 v96, v97, v96, 1.0
	v_mul_f32_e32 v96, v97, v96
	v_mul_f32_e32 v96, 0xc0135761, v96
	v_exp_f32_e32 v96, v96
	s_nop 0
	v_add_f32_e32 v96, 1.0, v96
	v_rcp_f32_e32 v96, v96
	s_nop 0
	v_mul_f32_e32 v105, v97, v96
	v_mul_f32_e32 v96, 0x3d372713, v98
	v_fma_f32 v96, v98, v96, 1.0
	v_mul_f32_e32 v96, v98, v96
	v_mul_f32_e32 v96, 0xc0135761, v96
	v_exp_f32_e32 v96, v96
	s_nop 0
	v_add_f32_e32 v96, 1.0, v96
	v_rcp_f32_e32 v96, v96
	s_nop 0
	v_mul_f32_e32 v106, v98, v96
	v_mul_f32_e32 v96, 0x3d372713, v99
	v_fma_f32 v96, v99, v96, 1.0
	v_mul_f32_e32 v96, v99, v96
	v_mul_f32_e32 v96, 0xc0135761, v96
	v_exp_f32_e32 v96, v96
	s_nop 0
	v_add_f32_e32 v96, 1.0, v96
	v_rcp_f32_e32 v96, v96
	s_nop 0
	v_mul_f32_e32 v99, v99, v96
	v_cvt_pk_bf16_f32 v96, v100, v101
	v_cvt_pk_bf16_f32 v97, v102, v103
	v_cvt_pk_bf16_f32 v98, v104, v105
	v_cvt_pk_bf16_f32 v99, v106, v99
	global_store_dwordx4 v[112:113], v[96:99], off offset:256
	s_nop 1
	v_or_b32_e32 v96, 32, v152
	v_ashrrev_i32_e32 v97, 31, v96
	v_lshl_add_u64 v[98:99], v[96:97], 2, s[48:49]
	s_nop 1
	v_lshlrev_b64 v[96:97], 10, v[96:97]
	v_lshl_add_u64 v[96:97], v[158:159], 0, v[96:97]
	v_mov_b32_e32 v98, v202
	v_fmamk_f32 v98, v98, 0x3a800000, v172
	v_cmp_gt_f32_e32 vcc, s82, v98
	v_mul_f32_e32 v99, 0x4f800000, v98
	s_nop 0
	v_cndmask_b32_e32 v98, v98, v99, vcc
	v_sqrt_f32_e32 v99, v98
	s_nop 0
	v_add_u32_e32 v100, -1, v99
	v_fma_f32 v101, -v100, v99, v98
	v_cmp_ge_f32_e64 s[0:1], 0, v101
	v_add_u32_e32 v101, 1, v99
	s_nop 0
	v_cndmask_b32_e64 v100, v99, v100, s[0:1]
	v_fma_f32 v99, -v101, v99, v98
	v_cmp_lt_f32_e64 s[0:1], 0, v99
	s_nop 1
	v_cndmask_b32_e64 v99, v100, v101, s[0:1]
	v_mul_f32_e32 v100, 0x37800000, v99
	v_cndmask_b32_e32 v99, v99, v100, vcc
	v_cmp_class_f32_e32 vcc, v98, v173
	s_nop 1
	v_cndmask_b32_e32 v98, v99, v98, vcc
	v_div_scale_f32 v99, s[0:1], v98, v98, 1.0
	v_rcp_f32_e32 v100, v99
	s_nop 0
	v_fma_f32 v101, -v99, v100, 1.0
	v_fmac_f32_e32 v100, v101, v100
	v_div_scale_f32 v101, vcc, 1.0, v98, 1.0
	v_mul_f32_e32 v102, v101, v100
	v_fma_f32 v103, -v99, v102, v101
	v_fmac_f32_e32 v102, v103, v100
	v_fma_f32 v99, -v99, v102, v101
	v_div_fmas_f32 v99, v99, v100, v102
	v_div_fixup_f32 v98, v99, v98, 1.0
	v_pk_mul_f32 v[92:93], v[92:93], v[98:99] op_sel_hi:[1,0]
	v_pk_mul_f32 v[94:95], v[94:95], v[98:99] op_sel_hi:[1,0]
	v_pk_mul_f32 v[90:91], v[90:91], v[98:99] op_sel_hi:[1,0]
	v_pk_mul_f32 v[88:89], v[88:89], v[98:99] op_sel_hi:[1,0]
	v_mul_f32_e32 v99, 0x3d372713, v92
	v_fma_f32 v99, v92, v99, 1.0
	v_mul_f32_e32 v99, v92, v99
	v_mul_f32_e32 v99, 0xc0135761, v99
	v_exp_f32_e32 v99, v99
	s_nop 0
	v_add_f32_e32 v99, 1.0, v99
	v_rcp_f32_e32 v99, v99
	s_nop 0
	v_mul_f32_e32 v92, v92, v99
	v_mul_f32_e32 v99, 0x3d372713, v93
	v_fma_f32 v99, v93, v99, 1.0
	v_mul_f32_e32 v99, v93, v99
	v_mul_f32_e32 v99, 0xc0135761, v99
	v_exp_f32_e32 v99, v99
	s_nop 0
	v_add_f32_e32 v99, 1.0, v99
	v_rcp_f32_e32 v99, v99
	s_nop 0
	v_mul_f32_e32 v93, v93, v99
	v_mul_f32_e32 v99, 0x3d372713, v94
	v_fma_f32 v99, v94, v99, 1.0
	v_mul_f32_e32 v99, v94, v99
	v_mul_f32_e32 v99, 0xc0135761, v99
	v_exp_f32_e32 v99, v99
	s_nop 0
	v_add_f32_e32 v99, 1.0, v99
	v_rcp_f32_e32 v99, v99
	s_nop 0
	v_mul_f32_e32 v94, v94, v99
	v_mul_f32_e32 v99, 0x3d372713, v95
	v_fma_f32 v99, v95, v99, 1.0
	v_mul_f32_e32 v99, v95, v99
	v_mul_f32_e32 v99, 0xc0135761, v99
	v_exp_f32_e32 v99, v99
	s_nop 0
	v_add_f32_e32 v99, 1.0, v99
	v_rcp_f32_e32 v99, v99
	s_nop 0
	v_mul_f32_e32 v95, v95, v99
	v_mul_f32_e32 v99, 0x3d372713, v88
	v_fma_f32 v99, v88, v99, 1.0
	v_mul_f32_e32 v99, v88, v99
	v_mul_f32_e32 v99, 0xc0135761, v99
	v_exp_f32_e32 v99, v99
	s_nop 0
	v_add_f32_e32 v99, 1.0, v99
	v_rcp_f32_e32 v99, v99
	s_nop 0
	v_mul_f32_e32 v99, v88, v99
	v_mul_f32_e32 v88, 0x3d372713, v89
	v_fma_f32 v88, v89, v88, 1.0
	v_mul_f32_e32 v88, v89, v88
	v_mul_f32_e32 v88, 0xc0135761, v88
	v_exp_f32_e32 v88, v88
	v_pk_mul_f32 v[84:85], v[84:85], v[98:99] op_sel_hi:[1,0]
	v_pk_mul_f32 v[86:87], v[86:87], v[98:99] op_sel_hi:[1,0]
	v_pk_mul_f32 v[80:81], v[80:81], v[98:99] op_sel_hi:[1,0]
	v_add_f32_e32 v88, 1.0, v88
	v_rcp_f32_e32 v88, v88
; __device__ __forceinline__ u32x4 pack8(f32x4 a, f32x4 b) { u32x4 o; o.x = cvt_pk(a.x, a.y); o.y = cvt_pk(a.z, a.w); o.z = cvt_pk(b.x, b.y); o.w = cvt_pk(b.z, b.w); return o; }
; __device__ __forceinline__ float rstd_of(const float* SS, int row, float invw) { return 1.0f / sqrtf(SS[row] * invw + EPS); }
; __device__ __forceinline__ float gelu_f(float x) {
;     const float t = x * (1.f + 0.044715f * x * x);
;     return x * __builtin_amdgcn_rcpf(1.f + __builtin_amdgcn_exp2f(-2.3022081986f * t));
; }
;     __device__ __forceinline__ void operator()(const f32x4 (&acc)[2][2][4][2], const pg8::Unit& u, int wr, int wc, int fr, int fq) const {
;     ...
;             for (int ai = 0; ai < 2; ++ai)
; #pragma unroll
;                 for (int m = 0; m < 4; ++m) {
;                     const int row = row0 + ai * 128 + m * 16; const float r = rstd_of(SS1, row, 1.f / 1024.f);
; #pragma unroll
;                     for (int bj = 0; bj < 2; ++bj) {
;                         const f32x4 a = acc[ai][bj][m][0] * r, b = acc[ai][bj][m][1] * r;
;                         f32x4 ga, gb; ga.x = gelu_f(a.x); ga.y = gelu_f(a.y); ga.z = gelu_f(a.z); ga.w = gelu_f(a.w);
;                         gb.x = gelu_f(b.x); gb.y = gelu_f(b.y); gb.z = gelu_f(b.z); gb.w = gelu_f(b.w);
;                         *(u32x4*)(dst + (size_t)row * 512 + bj * 128) = pack8(ga, gb);
;                     }
;                 }
	v_pk_mul_f32 v[82:83], v[82:83], v[98:99] op_sel_hi:[1,0]
	v_mul_f32_e32 v100, v89, v88
	v_mul_f32_e32 v88, 0x3d372713, v90
	v_fma_f32 v88, v90, v88, 1.0
	v_mul_f32_e32 v88, v90, v88
	v_mul_f32_e32 v88, 0xc0135761, v88
	v_exp_f32_e32 v88, v88
	s_nop 0
	v_add_f32_e32 v88, 1.0, v88
	v_rcp_f32_e32 v88, v88
	s_nop 0
	v_mul_f32_e32 v101, v90, v88
	v_mul_f32_e32 v88, 0x3d372713, v91
	v_fma_f32 v88, v91, v88, 1.0
	v_mul_f32_e32 v88, v91, v88
	v_mul_f32_e32 v88, 0xc0135761, v88
	v_exp_f32_e32 v88, v88
	s_nop 0
	v_add_f32_e32 v88, 1.0, v88
	v_rcp_f32_e32 v88, v88
	s_nop 0
	v_mul_f32_e32 v91, v91, v88
	v_cvt_pk_bf16_f32 v88, v92, v93
	v_cvt_pk_bf16_f32 v89, v94, v95
	v_cvt_pk_bf16_f32 v90, v99, v100
	v_cvt_pk_bf16_f32 v91, v101, v91
	global_store_dwordx4 v[96:97], v[88:91], off
	s_nop 1
	v_mul_f32_e32 v88, 0x3d372713, v84
	v_fma_f32 v88, v84, v88, 1.0
	v_mul_f32_e32 v88, v84, v88
	v_mul_f32_e32 v88, 0xc0135761, v88
	v_exp_f32_e32 v88, v88
	s_nop 0
	v_add_f32_e32 v88, 1.0, v88
	v_rcp_f32_e32 v88, v88
	s_nop 0
	v_mul_f32_e32 v84, v84, v88
	v_mul_f32_e32 v88, 0x3d372713, v85
	v_fma_f32 v88, v85, v88, 1.0
	v_mul_f32_e32 v88, v85, v88
	v_mul_f32_e32 v88, 0xc0135761, v88
	v_exp_f32_e32 v88, v88
	s_nop 0
	v_add_f32_e32 v88, 1.0, v88
	v_rcp_f32_e32 v88, v88
	s_nop 0
	v_mul_f32_e32 v85, v85, v88
	v_mul_f32_e32 v88, 0x3d372713, v86
	v_fma_f32 v88, v86, v88, 1.0
	v_mul_f32_e32 v88, v86, v88
	v_mul_f32_e32 v88, 0xc0135761, v88
	v_exp_f32_e32 v88, v88
	s_nop 0
	v_add_f32_e32 v88, 1.0, v88
	v_rcp_f32_e32 v88, v88
	s_nop 0
	v_mul_f32_e32 v86, v86, v88
	v_mul_f32_e32 v88, 0x3d372713, v87
	v_fma_f32 v88, v87, v88, 1.0
	v_mul_f32_e32 v88, v87, v88
	v_mul_f32_e32 v88, 0xc0135761, v88
	v_exp_f32_e32 v88, v88
	s_nop 0
	v_add_f32_e32 v88, 1.0, v88
	v_rcp_f32_e32 v88, v88
	s_nop 0
	v_mul_f32_e32 v87, v87, v88
	v_mul_f32_e32 v88, 0x3d372713, v80
	v_fma_f32 v88, v80, v88, 1.0
	v_mul_f32_e32 v88, v80, v88
	v_mul_f32_e32 v88, 0xc0135761, v88
	v_exp_f32_e32 v88, v88
	s_nop 0
	v_add_f32_e32 v88, 1.0, v88
	v_rcp_f32_e32 v88, v88
	s_nop 0
	v_mul_f32_e32 v88, v80, v88
	v_mul_f32_e32 v80, 0x3d372713, v81
	v_fma_f32 v80, v81, v80, 1.0
	v_mul_f32_e32 v80, v81, v80
	v_mul_f32_e32 v80, 0xc0135761, v80
	v_exp_f32_e32 v80, v80
	s_nop 0
	v_add_f32_e32 v80, 1.0, v80
	v_rcp_f32_e32 v80, v80
	s_nop 0
	v_mul_f32_e32 v89, v81, v80
	v_mul_f32_e32 v80, 0x3d372713, v82
	v_fma_f32 v80, v82, v80, 1.0
	v_mul_f32_e32 v80, v82, v80
	v_mul_f32_e32 v80, 0xc0135761, v80
	v_exp_f32_e32 v80, v80
	s_nop 0
	v_add_f32_e32 v80, 1.0, v80
	v_rcp_f32_e32 v80, v80
	s_nop 0
	v_mul_f32_e32 v90, v82, v80
	v_mul_f32_e32 v80, 0x3d372713, v83
	v_fma_f32 v80, v83, v80, 1.0
	v_mul_f32_e32 v80, v83, v80
	v_mul_f32_e32 v80, 0xc0135761, v80
	v_exp_f32_e32 v80, v80
	s_nop 0
	v_add_f32_e32 v80, 1.0, v80
	v_rcp_f32_e32 v80, v80
	s_nop 0
	v_mul_f32_e32 v83, v83, v80
	v_cvt_pk_bf16_f32 v80, v84, v85
	v_cvt_pk_bf16_f32 v81, v86, v87
	v_cvt_pk_bf16_f32 v82, v88, v89
	v_cvt_pk_bf16_f32 v83, v90, v83
	global_store_dwordx4 v[96:97], v[80:83], off offset:256
	s_nop 1
	v_or_b32_e32 v80, 48, v152
	v_ashrrev_i32_e32 v81, 31, v80
	v_lshl_add_u64 v[82:83], v[80:81], 2, s[48:49]
	s_nop 1
	v_lshlrev_b64 v[80:81], 10, v[80:81]
	v_lshl_add_u64 v[80:81], v[158:159], 0, v[80:81]
	v_mov_b32_e32 v82, v203
	v_fmamk_f32 v82, v82, 0x3a800000, v172
	v_cmp_gt_f32_e32 vcc, s82, v82
	v_mul_f32_e32 v83, 0x4f800000, v82
	s_nop 0
	v_cndmask_b32_e32 v82, v82, v83, vcc
	v_sqrt_f32_e32 v83, v82
	s_nop 0
	v_add_u32_e32 v84, -1, v83
	v_fma_f32 v85, -v84, v83, v82
	v_cmp_ge_f32_e64 s[0:1], 0, v85
	v_add_u32_e32 v85, 1, v83
	s_nop 0
	v_cndmask_b32_e64 v84, v83, v84, s[0:1]
	v_fma_f32 v83, -v85, v83, v82
	v_cmp_lt_f32_e64 s[0:1], 0, v83
	s_nop 1
	v_cndmask_b32_e64 v83, v84, v85, s[0:1]
	v_mul_f32_e32 v84, 0x37800000, v83
	v_cndmask_b32_e32 v83, v83, v84, vcc
	v_cmp_class_f32_e32 vcc, v82, v173
	s_nop 1
	v_cndmask_b32_e32 v82, v83, v82, vcc
	v_div_scale_f32 v83, s[0:1], v82, v82, 1.0
	v_rcp_f32_e32 v84, v83
	s_nop 0
	v_fma_f32 v85, -v83, v84, 1.0
	v_fmac_f32_e32 v84, v85, v84
	v_div_scale_f32 v85, vcc, 1.0, v82, 1.0
	v_mul_f32_e32 v86, v85, v84
	v_fma_f32 v87, -v83, v86, v85
	v_fmac_f32_e32 v86, v87, v84
	v_fma_f32 v83, -v83, v86, v85
	v_div_fmas_f32 v83, v83, v84, v86
	v_div_fixup_f32 v82, v83, v82, 1.0
	v_pk_mul_f32 v[76:77], v[76:77], v[82:83] op_sel_hi:[1,0]
	v_pk_mul_f32 v[78:79], v[78:79], v[82:83] op_sel_hi:[1,0]
	v_pk_mul_f32 v[74:75], v[74:75], v[82:83] op_sel_hi:[1,0]
	v_pk_mul_f32 v[72:73], v[72:73], v[82:83] op_sel_hi:[1,0]
	v_mul_f32_e32 v83, 0x3d372713, v76
	v_fma_f32 v83, v76, v83, 1.0
	v_mul_f32_e32 v83, v76, v83
	v_mul_f32_e32 v83, 0xc0135761, v83
	v_exp_f32_e32 v83, v83
	s_nop 0
	v_add_f32_e32 v83, 1.0, v83
	v_rcp_f32_e32 v83, v83
	s_nop 0
	v_mul_f32_e32 v76, v76, v83
	v_mul_f32_e32 v83, 0x3d372713, v77
	v_fma_f32 v83, v77, v83, 1.0
	v_mul_f32_e32 v83, v77, v83
	v_mul_f32_e32 v83, 0xc0135761, v83
	v_exp_f32_e32 v83, v83
	s_nop 0
	v_add_f32_e32 v83, 1.0, v83
	v_rcp_f32_e32 v83, v83
	s_nop 0
	v_mul_f32_e32 v77, v77, v83
	v_mul_f32_e32 v83, 0x3d372713, v78
	v_fma_f32 v83, v78, v83, 1.0
	v_mul_f32_e32 v83, v78, v83
	v_mul_f32_e32 v83, 0xc0135761, v83
	v_exp_f32_e32 v83, v83
	s_nop 0
	v_add_f32_e32 v83, 1.0, v83
	v_rcp_f32_e32 v83, v83
	s_nop 0
	v_mul_f32_e32 v78, v78, v83
	v_mul_f32_e32 v83, 0x3d372713, v79
	v_fma_f32 v83, v79, v83, 1.0
	v_mul_f32_e32 v83, v79, v83
	v_mul_f32_e32 v83, 0xc0135761, v83
	v_exp_f32_e32 v83, v83
	s_nop 0
	v_add_f32_e32 v83, 1.0, v83
	v_rcp_f32_e32 v83, v83
	s_nop 0
	v_mul_f32_e32 v79, v79, v83
	v_mul_f32_e32 v83, 0x3d372713, v72
	v_fma_f32 v83, v72, v83, 1.0
	v_mul_f32_e32 v83, v72, v83
	v_mul_f32_e32 v83, 0xc0135761, v83
; __device__ __forceinline__ u32x4 pack8(f32x4 a, f32x4 b) { u32x4 o; o.x = cvt_pk(a.x, a.y); o.y = cvt_pk(a.z, a.w); o.z = cvt_pk(b.x, b.y); o.w = cvt_pk(b.z, b.w); return o; }
; __device__ __forceinline__ float rstd_of(const float* SS, int row, float invw) { return 1.0f / sqrtf(SS[row] * invw + EPS); }
; __device__ __forceinline__ float gelu_f(float x) {
;     const float t = x * (1.f + 0.044715f * x * x);
;     return x * __builtin_amdgcn_rcpf(1.f + __builtin_amdgcn_exp2f(-2.3022081986f * t));
; }
;     __device__ __forceinline__ void operator()(const f32x4 (&acc)[2][2][4][2], const pg8::Unit& u, int wr, int wc, int fr, int fq) const {
;     ...
;             for (int ai = 0; ai < 2; ++ai)
; #pragma unroll
;                 for (int m = 0; m < 4; ++m) {
;                     const int row = row0 + ai * 128 + m * 16; const float r = rstd_of(SS1, row, 1.f / 1024.f);
; #pragma unroll
;                     for (int bj = 0; bj < 2; ++bj) {
;                         const f32x4 a = acc[ai][bj][m][0] * r, b = acc[ai][bj][m][1] * r;
;                         f32x4 ga, gb; ga.x = gelu_f(a.x); ga.y = gelu_f(a.y); ga.z = gelu_f(a.z); ga.w = gelu_f(a.w);
;                         gb.x = gelu_f(b.x); gb.y = gelu_f(b.y); gb.z = gelu_f(b.z); gb.w = gelu_f(b.w);
;                         *(u32x4*)(dst + (size_t)row * 512 + bj * 128) = pack8(ga, gb);
;                     }
;                 }
	v_exp_f32_e32 v83, v83
	s_nop 0
	v_add_f32_e32 v83, 1.0, v83
	v_rcp_f32_e32 v83, v83
	s_nop 0
	v_mul_f32_e32 v83, v72, v83
	v_mul_f32_e32 v72, 0x3d372713, v73
	v_fma_f32 v72, v73, v72, 1.0
	v_mul_f32_e32 v72, v73, v72
	v_mul_f32_e32 v72, 0xc0135761, v72
	v_exp_f32_e32 v72, v72
	v_pk_mul_f32 v[68:69], v[68:69], v[82:83] op_sel_hi:[1,0]
	v_pk_mul_f32 v[70:71], v[70:71], v[82:83] op_sel_hi:[1,0]
	v_pk_mul_f32 v[64:65], v[64:65], v[82:83] op_sel_hi:[1,0]
	v_add_f32_e32 v72, 1.0, v72
	v_rcp_f32_e32 v72, v72
	v_pk_mul_f32 v[66:67], v[66:67], v[82:83] op_sel_hi:[1,0]
	v_mul_f32_e32 v84, v73, v72
	v_mul_f32_e32 v72, 0x3d372713, v74
	v_fma_f32 v72, v74, v72, 1.0
	v_mul_f32_e32 v72, v74, v72
	v_mul_f32_e32 v72, 0xc0135761, v72
	v_exp_f32_e32 v72, v72
	s_nop 0
	v_add_f32_e32 v72, 1.0, v72
	v_rcp_f32_e32 v72, v72
	s_nop 0
	v_mul_f32_e32 v85, v74, v72
	v_mul_f32_e32 v72, 0x3d372713, v75
	v_fma_f32 v72, v75, v72, 1.0
	v_mul_f32_e32 v72, v75, v72
	v_mul_f32_e32 v72, 0xc0135761, v72
	v_exp_f32_e32 v72, v72
	s_nop 0
	v_add_f32_e32 v72, 1.0, v72
	v_rcp_f32_e32 v72, v72
	s_nop 0
	v_mul_f32_e32 v75, v75, v72
	v_cvt_pk_bf16_f32 v72, v76, v77
	v_cvt_pk_bf16_f32 v73, v78, v79
	v_cvt_pk_bf16_f32 v74, v83, v84
	v_cvt_pk_bf16_f32 v75, v85, v75
	global_store_dwordx4 v[80:81], v[72:75], off
	s_nop 1
	v_mul_f32_e32 v72, 0x3d372713, v68
	v_fma_f32 v72, v68, v72, 1.0
	v_mul_f32_e32 v72, v68, v72
	v_mul_f32_e32 v72, 0xc0135761, v72
	v_exp_f32_e32 v72, v72
	s_nop 0
	v_add_f32_e32 v72, 1.0, v72
	v_rcp_f32_e32 v72, v72
	s_nop 0
	v_mul_f32_e32 v68, v68, v72
	v_mul_f32_e32 v72, 0x3d372713, v69
	v_fma_f32 v72, v69, v72, 1.0
	v_mul_f32_e32 v72, v69, v72
	v_mul_f32_e32 v72, 0xc0135761, v72
	v_exp_f32_e32 v72, v72
	s_nop 0
	v_add_f32_e32 v72, 1.0, v72
	v_rcp_f32_e32 v72, v72
	s_nop 0
	v_mul_f32_e32 v69, v69, v72
	v_mul_f32_e32 v72, 0x3d372713, v70
	v_fma_f32 v72, v70, v72, 1.0
	v_mul_f32_e32 v72, v70, v72
	v_mul_f32_e32 v72, 0xc0135761, v72
	v_exp_f32_e32 v72, v72
	s_nop 0
	v_add_f32_e32 v72, 1.0, v72
	v_rcp_f32_e32 v72, v72
	s_nop 0
	v_mul_f32_e32 v70, v70, v72
	v_mul_f32_e32 v72, 0x3d372713, v71
	v_fma_f32 v72, v71, v72, 1.0
	v_mul_f32_e32 v72, v71, v72
	v_mul_f32_e32 v72, 0xc0135761, v72
	v_exp_f32_e32 v72, v72
	s_nop 0
	v_add_f32_e32 v72, 1.0, v72
	v_rcp_f32_e32 v72, v72
	s_nop 0
	v_mul_f32_e32 v71, v71, v72
	v_mul_f32_e32 v72, 0x3d372713, v64
	v_fma_f32 v72, v64, v72, 1.0
	v_mul_f32_e32 v72, v64, v72
	v_mul_f32_e32 v72, 0xc0135761, v72
	v_exp_f32_e32 v72, v72
	s_nop 0
	v_add_f32_e32 v72, 1.0, v72
	v_rcp_f32_e32 v72, v72
	s_nop 0
	v_mul_f32_e32 v72, v64, v72
	v_mul_f32_e32 v64, 0x3d372713, v65
	v_fma_f32 v64, v65, v64, 1.0
	v_mul_f32_e32 v64, v65, v64
	v_mul_f32_e32 v64, 0xc0135761, v64
	v_exp_f32_e32 v64, v64
	s_nop 0
	v_add_f32_e32 v64, 1.0, v64
	v_rcp_f32_e32 v64, v64
	s_nop 0
	v_mul_f32_e32 v73, v65, v64
	v_mul_f32_e32 v64, 0x3d372713, v66
	v_fma_f32 v64, v66, v64, 1.0
	v_mul_f32_e32 v64, v66, v64
	v_mul_f32_e32 v64, 0xc0135761, v64
	v_exp_f32_e32 v64, v64
	s_nop 0
	v_add_f32_e32 v64, 1.0, v64
	v_rcp_f32_e32 v64, v64
	s_nop 0
	v_mul_f32_e32 v74, v66, v64
	v_mul_f32_e32 v64, 0x3d372713, v67
	v_fma_f32 v64, v67, v64, 1.0
	v_mul_f32_e32 v64, v67, v64
	v_mul_f32_e32 v64, 0xc0135761, v64
	v_exp_f32_e32 v64, v64
	s_nop 0
	v_add_f32_e32 v64, 1.0, v64
	v_rcp_f32_e32 v64, v64
	s_nop 0
	v_mul_f32_e32 v67, v67, v64
	v_cvt_pk_bf16_f32 v64, v68, v69
	v_cvt_pk_bf16_f32 v65, v70, v71
	v_cvt_pk_bf16_f32 v66, v72, v73
	v_cvt_pk_bf16_f32 v67, v74, v67
	global_store_dwordx4 v[80:81], v[64:67], off offset:256
	s_nop 1
	v_mov_b32_e32 v64, v204
	v_fmamk_f32 v64, v64, 0x3a800000, v172
	v_cmp_gt_f32_e32 vcc, s82, v64
	v_mul_f32_e32 v65, 0x4f800000, v64
	s_nop 0
	v_cndmask_b32_e32 v64, v64, v65, vcc
	v_sqrt_f32_e32 v65, v64
	s_nop 0
	v_add_u32_e32 v66, -1, v65
	v_fma_f32 v67, -v66, v65, v64
	v_cmp_ge_f32_e64 s[0:1], 0, v67
	v_add_u32_e32 v67, 1, v65
	s_nop 0
	v_cndmask_b32_e64 v66, v65, v66, s[0:1]
	v_fma_f32 v65, -v67, v65, v64
	v_cmp_lt_f32_e64 s[0:1], 0, v65
	s_nop 1
	v_cndmask_b32_e64 v65, v66, v67, s[0:1]
	v_mul_f32_e32 v66, 0x37800000, v65
	v_cndmask_b32_e32 v65, v65, v66, vcc
	v_cmp_class_f32_e32 vcc, v64, v173
	s_nop 1
	v_cndmask_b32_e32 v64, v65, v64, vcc
	v_div_scale_f32 v65, s[0:1], v64, v64, 1.0
	v_rcp_f32_e32 v66, v65
	s_mov_b64 s[0:1], 0x20000
	v_fma_f32 v67, -v65, v66, 1.0
	v_fmac_f32_e32 v66, v67, v66
	v_div_scale_f32 v67, vcc, 1.0, v64, 1.0
	v_mul_f32_e32 v68, v67, v66
	v_fma_f32 v69, -v65, v68, v67
	v_fmac_f32_e32 v68, v69, v66
	v_fma_f32 v65, -v65, v68, v67
	v_div_fmas_f32 v65, v65, v66, v68
	v_div_fixup_f32 v66, v65, v64, 1.0
	v_pk_mul_f32 v[60:61], v[60:61], v[66:67] op_sel_hi:[1,0]
	v_pk_mul_f32 v[62:63], v[62:63], v[66:67] op_sel_hi:[1,0]
	v_pk_mul_f32 v[58:59], v[58:59], v[66:67] op_sel_hi:[1,0]
	v_pk_mul_f32 v[56:57], v[56:57], v[66:67] op_sel_hi:[1,0]
	v_mul_f32_e32 v67, 0x3d372713, v60
	v_fma_f32 v67, v60, v67, 1.0
	v_mul_f32_e32 v67, v60, v67
	v_mul_f32_e32 v67, 0xc0135761, v67
	v_exp_f32_e32 v67, v67
	v_lshl_add_u64 v[64:65], v[154:155], 0, s[0:1]
	s_mov_b32 s0, 0x20000
	v_add_f32_e32 v67, 1.0, v67
	v_rcp_f32_e32 v67, v67
	s_nop 0
	v_mul_f32_e32 v60, v60, v67
	v_mul_f32_e32 v67, 0x3d372713, v61
	v_fma_f32 v67, v61, v67, 1.0
	v_mul_f32_e32 v67, v61, v67
	v_mul_f32_e32 v67, 0xc0135761, v67
	v_exp_f32_e32 v67, v67
	s_nop 0
	v_add_f32_e32 v67, 1.0, v67
	v_rcp_f32_e32 v67, v67
	s_nop 0
	v_mul_f32_e32 v61, v61, v67
	v_mul_f32_e32 v67, 0x3d372713, v62
	v_fma_f32 v67, v62, v67, 1.0
	v_mul_f32_e32 v67, v62, v67
	v_mul_f32_e32 v67, 0xc0135761, v67
	v_exp_f32_e32 v67, v67
	s_nop 0
	v_add_f32_e32 v67, 1.0, v67
	v_rcp_f32_e32 v67, v67
	s_nop 0
	v_mul_f32_e32 v62, v62, v67
; __device__ __forceinline__ u32x4 pack8(f32x4 a, f32x4 b) { u32x4 o; o.x = cvt_pk(a.x, a.y); o.y = cvt_pk(a.z, a.w); o.z = cvt_pk(b.x, b.y); o.w = cvt_pk(b.z, b.w); return o; }
; __device__ __forceinline__ float rstd_of(const float* SS, int row, float invw) { return 1.0f / sqrtf(SS[row] * invw + EPS); }
; __device__ __forceinline__ float gelu_f(float x) {
;     const float t = x * (1.f + 0.044715f * x * x);
;     return x * __builtin_amdgcn_rcpf(1.f + __builtin_amdgcn_exp2f(-2.3022081986f * t));
; }
;     __device__ __forceinline__ void operator()(const f32x4 (&acc)[2][2][4][2], const pg8::Unit& u, int wr, int wc, int fr, int fq) const {
;     ...
;             for (int ai = 0; ai < 2; ++ai)
; #pragma unroll
;                 for (int m = 0; m < 4; ++m) {
;                     const int row = row0 + ai * 128 + m * 16; const float r = rstd_of(SS1, row, 1.f / 1024.f);
; #pragma unroll
;                     for (int bj = 0; bj < 2; ++bj) {
;                         const f32x4 a = acc[ai][bj][m][0] * r, b = acc[ai][bj][m][1] * r;
;                         f32x4 ga, gb; ga.x = gelu_f(a.x); ga.y = gelu_f(a.y); ga.z = gelu_f(a.z); ga.w = gelu_f(a.w);
;                         gb.x = gelu_f(b.x); gb.y = gelu_f(b.y); gb.z = gelu_f(b.z); gb.w = gelu_f(b.w);
;                         *(u32x4*)(dst + (size_t)row * 512 + bj * 128) = pack8(ga, gb);
;                     }
;                 }
	v_mul_f32_e32 v67, 0x3d372713, v63
	v_fma_f32 v67, v63, v67, 1.0
	v_mul_f32_e32 v67, v63, v67
	v_mul_f32_e32 v67, 0xc0135761, v67
	v_exp_f32_e32 v67, v67
	s_nop 0
	v_add_f32_e32 v67, 1.0, v67
	v_rcp_f32_e32 v67, v67
	s_nop 0
	v_mul_f32_e32 v63, v63, v67
	v_mul_f32_e32 v67, 0x3d372713, v56
	v_fma_f32 v67, v56, v67, 1.0
	v_mul_f32_e32 v67, v56, v67
	v_mul_f32_e32 v67, 0xc0135761, v67
	v_exp_f32_e32 v67, v67
	s_nop 0
	v_add_f32_e32 v67, 1.0, v67
	v_rcp_f32_e32 v67, v67
	s_nop 0
	v_mul_f32_e32 v67, v56, v67
	v_mul_f32_e32 v56, 0x3d372713, v57
	v_fma_f32 v56, v57, v56, 1.0
	v_mul_f32_e32 v56, v57, v56
	v_mul_f32_e32 v56, 0xc0135761, v56
	v_exp_f32_e32 v56, v56
	v_pk_mul_f32 v[52:53], v[52:53], v[66:67] op_sel_hi:[1,0]
	v_pk_mul_f32 v[54:55], v[54:55], v[66:67] op_sel_hi:[1,0]
	v_pk_mul_f32 v[48:49], v[48:49], v[66:67] op_sel_hi:[1,0]
	v_add_f32_e32 v56, 1.0, v56
	v_rcp_f32_e32 v56, v56
	v_pk_mul_f32 v[50:51], v[50:51], v[66:67] op_sel_hi:[1,0]
	v_mul_f32_e32 v68, v57, v56
	v_mul_f32_e32 v56, 0x3d372713, v58
	v_fma_f32 v56, v58, v56, 1.0
	v_mul_f32_e32 v56, v58, v56
	v_mul_f32_e32 v56, 0xc0135761, v56
	v_exp_f32_e32 v56, v56
	s_nop 0
	v_add_f32_e32 v56, 1.0, v56
	v_rcp_f32_e32 v56, v56
	s_nop 0
	v_mul_f32_e32 v69, v58, v56
	v_mul_f32_e32 v56, 0x3d372713, v59
	v_fma_f32 v56, v59, v56, 1.0
	v_mul_f32_e32 v56, v59, v56
	v_mul_f32_e32 v56, 0xc0135761, v56
	v_exp_f32_e32 v56, v56
	s_nop 0
	v_add_f32_e32 v56, 1.0, v56
	v_rcp_f32_e32 v56, v56
	s_nop 0
	v_mul_f32_e32 v59, v59, v56
	v_cvt_pk_bf16_f32 v56, v60, v61
	v_add_co_u32_e32 v60, vcc, s0, v154
	v_cvt_pk_bf16_f32 v57, v62, v63
	v_cvt_pk_bf16_f32 v58, v67, v68
	v_cvt_pk_bf16_f32 v59, v69, v59
	s_nop 1
	v_addc_co_u32_e32 v61, vcc, 0, v155, vcc
	global_store_dwordx4 v[60:61], v[56:59], off
	s_nop 1
	v_mul_f32_e32 v56, 0x3d372713, v52
	v_fma_f32 v56, v52, v56, 1.0
	v_mul_f32_e32 v56, v52, v56
	v_mul_f32_e32 v56, 0xc0135761, v56
	v_exp_f32_e32 v56, v56
	s_nop 0
	v_add_f32_e32 v56, 1.0, v56
	v_rcp_f32_e32 v56, v56
	s_nop 0
	v_mul_f32_e32 v52, v52, v56
	v_mul_f32_e32 v56, 0x3d372713, v53
	v_fma_f32 v56, v53, v56, 1.0
	v_mul_f32_e32 v56, v53, v56
	v_mul_f32_e32 v56, 0xc0135761, v56
	v_exp_f32_e32 v56, v56
	s_nop 0
	v_add_f32_e32 v56, 1.0, v56
	v_rcp_f32_e32 v56, v56
	s_nop 0
	v_mul_f32_e32 v53, v53, v56
	v_mul_f32_e32 v56, 0x3d372713, v54
	v_fma_f32 v56, v54, v56, 1.0
	v_mul_f32_e32 v56, v54, v56
	v_mul_f32_e32 v56, 0xc0135761, v56
	v_exp_f32_e32 v56, v56
	s_nop 0
	v_add_f32_e32 v56, 1.0, v56
	v_rcp_f32_e32 v56, v56
	s_nop 0
	v_mul_f32_e32 v54, v54, v56
	v_mul_f32_e32 v56, 0x3d372713, v55
	v_fma_f32 v56, v55, v56, 1.0
	v_mul_f32_e32 v56, v55, v56
	v_mul_f32_e32 v56, 0xc0135761, v56
	v_exp_f32_e32 v56, v56
	s_nop 0
	v_add_f32_e32 v56, 1.0, v56
	v_rcp_f32_e32 v56, v56
	s_nop 0
	v_mul_f32_e32 v55, v55, v56
	v_mul_f32_e32 v56, 0x3d372713, v48
	v_fma_f32 v56, v48, v56, 1.0
	v_mul_f32_e32 v56, v48, v56
	v_mul_f32_e32 v56, 0xc0135761, v56
	v_exp_f32_e32 v56, v56
	s_nop 0
	v_add_f32_e32 v56, 1.0, v56
	v_rcp_f32_e32 v56, v56
	s_nop 0
	v_mul_f32_e32 v56, v48, v56
	v_mul_f32_e32 v48, 0x3d372713, v49
	v_fma_f32 v48, v49, v48, 1.0
	v_mul_f32_e32 v48, v49, v48
	v_mul_f32_e32 v48, 0xc0135761, v48
	v_exp_f32_e32 v48, v48
	s_nop 0
	v_add_f32_e32 v48, 1.0, v48
	v_rcp_f32_e32 v48, v48
	s_nop 0
	v_mul_f32_e32 v57, v49, v48
	v_mul_f32_e32 v48, 0x3d372713, v50
	v_fma_f32 v48, v50, v48, 1.0
	v_mul_f32_e32 v48, v50, v48
	v_mul_f32_e32 v48, 0xc0135761, v48
	v_exp_f32_e32 v48, v48
	s_nop 0
	v_add_f32_e32 v48, 1.0, v48
	v_rcp_f32_e32 v48, v48
	s_nop 0
	v_mul_f32_e32 v58, v50, v48
	v_mul_f32_e32 v48, 0x3d372713, v51
	v_fma_f32 v48, v51, v48, 1.0
	v_mul_f32_e32 v48, v51, v48
	v_mul_f32_e32 v48, 0xc0135761, v48
	v_exp_f32_e32 v48, v48
	s_nop 0
	v_add_f32_e32 v48, 1.0, v48
	v_rcp_f32_e32 v48, v48
	s_nop 0
	v_mul_f32_e32 v51, v51, v48
	v_cvt_pk_bf16_f32 v48, v52, v53
	v_cvt_pk_bf16_f32 v49, v54, v55
	v_cvt_pk_bf16_f32 v50, v56, v57
	v_cvt_pk_bf16_f32 v51, v58, v51
	global_store_dwordx4 v[64:65], v[48:51], off offset:256
	s_nop 1
	v_mov_b32_e32 v48, v205
	v_fmamk_f32 v48, v48, 0x3a800000, v172
	v_cmp_gt_f32_e32 vcc, s82, v48
	v_mul_f32_e32 v49, 0x4f800000, v48
	s_nop 0
	v_cndmask_b32_e32 v48, v48, v49, vcc
	v_sqrt_f32_e32 v49, v48
	s_nop 0
	v_add_u32_e32 v50, -1, v49
	v_fma_f32 v51, -v50, v49, v48
	v_cmp_ge_f32_e64 s[0:1], 0, v51
	v_add_u32_e32 v51, 1, v49
	s_nop 0
	v_cndmask_b32_e64 v50, v49, v50, s[0:1]
	v_fma_f32 v49, -v51, v49, v48
	v_cmp_lt_f32_e64 s[0:1], 0, v49
	s_nop 1
	v_cndmask_b32_e64 v49, v50, v51, s[0:1]
	v_mul_f32_e32 v50, 0x37800000, v49
	v_cndmask_b32_e32 v49, v49, v50, vcc
	v_cmp_class_f32_e32 vcc, v48, v173
	s_nop 1
	v_cndmask_b32_e32 v48, v49, v48, vcc
	v_div_scale_f32 v49, s[0:1], v48, v48, 1.0
	v_rcp_f32_e32 v50, v49
	s_mov_b64 s[0:1], 0x24000
	v_fma_f32 v51, -v49, v50, 1.0
	v_fmac_f32_e32 v50, v51, v50
	v_div_scale_f32 v51, vcc, 1.0, v48, 1.0
	v_mul_f32_e32 v52, v51, v50
	v_fma_f32 v53, -v49, v52, v51
	v_fmac_f32_e32 v52, v53, v50
	v_fma_f32 v49, -v49, v52, v51
	v_div_fmas_f32 v49, v49, v50, v52
	v_div_fixup_f32 v50, v49, v48, 1.0
	v_pk_mul_f32 v[44:45], v[44:45], v[50:51] op_sel_hi:[1,0]
	v_pk_mul_f32 v[46:47], v[46:47], v[50:51] op_sel_hi:[1,0]
	v_pk_mul_f32 v[42:43], v[42:43], v[50:51] op_sel_hi:[1,0]
	v_pk_mul_f32 v[40:41], v[40:41], v[50:51] op_sel_hi:[1,0]
	v_mul_f32_e32 v51, 0x3d372713, v44
	v_fma_f32 v51, v44, v51, 1.0
	v_mul_f32_e32 v51, v44, v51
	v_mul_f32_e32 v51, 0xc0135761, v51
	v_exp_f32_e32 v51, v51
	v_lshl_add_u64 v[48:49], v[154:155], 0, s[0:1]
	s_mov_b32 s0, 0x24000
	v_add_f32_e32 v51, 1.0, v51
	v_rcp_f32_e32 v51, v51
	s_nop 0
	v_mul_f32_e32 v44, v44, v51
	v_mul_f32_e32 v51, 0x3d372713, v45
; __device__ __forceinline__ u32x4 pack8(f32x4 a, f32x4 b) { u32x4 o; o.x = cvt_pk(a.x, a.y); o.y = cvt_pk(a.z, a.w); o.z = cvt_pk(b.x, b.y); o.w = cvt_pk(b.z, b.w); return o; }
; __device__ __forceinline__ float rstd_of(const float* SS, int row, float invw) { return 1.0f / sqrtf(SS[row] * invw + EPS); }
; __device__ __forceinline__ float gelu_f(float x) {
;     const float t = x * (1.f + 0.044715f * x * x);
;     return x * __builtin_amdgcn_rcpf(1.f + __builtin_amdgcn_exp2f(-2.3022081986f * t));
; }
;     __device__ __forceinline__ void operator()(const f32x4 (&acc)[2][2][4][2], const pg8::Unit& u, int wr, int wc, int fr, int fq) const {
;     ...
;             for (int ai = 0; ai < 2; ++ai)
; #pragma unroll
;                 for (int m = 0; m < 4; ++m) {
;                     const int row = row0 + ai * 128 + m * 16; const float r = rstd_of(SS1, row, 1.f / 1024.f);
; #pragma unroll
;                     for (int bj = 0; bj < 2; ++bj) {
;                         const f32x4 a = acc[ai][bj][m][0] * r, b = acc[ai][bj][m][1] * r;
;                         f32x4 ga, gb; ga.x = gelu_f(a.x); ga.y = gelu_f(a.y); ga.z = gelu_f(a.z); ga.w = gelu_f(a.w);
;                         gb.x = gelu_f(b.x); gb.y = gelu_f(b.y); gb.z = gelu_f(b.z); gb.w = gelu_f(b.w);
;                         *(u32x4*)(dst + (size_t)row * 512 + bj * 128) = pack8(ga, gb);
;                     }
	v_fma_f32 v51, v45, v51, 1.0
	v_mul_f32_e32 v51, v45, v51
	v_mul_f32_e32 v51, 0xc0135761, v51
	v_exp_f32_e32 v51, v51
	s_nop 0
	v_add_f32_e32 v51, 1.0, v51
	v_rcp_f32_e32 v51, v51
	s_nop 0
	v_mul_f32_e32 v45, v45, v51
	v_mul_f32_e32 v51, 0x3d372713, v46
	v_fma_f32 v51, v46, v51, 1.0
	v_mul_f32_e32 v51, v46, v51
	v_mul_f32_e32 v51, 0xc0135761, v51
	v_exp_f32_e32 v51, v51
	s_nop 0
	v_add_f32_e32 v51, 1.0, v51
	v_rcp_f32_e32 v51, v51
	s_nop 0
	v_mul_f32_e32 v46, v46, v51
	v_mul_f32_e32 v51, 0x3d372713, v47
	v_fma_f32 v51, v47, v51, 1.0
	v_mul_f32_e32 v51, v47, v51
	v_mul_f32_e32 v51, 0xc0135761, v51
	v_exp_f32_e32 v51, v51
	s_nop 0
	v_add_f32_e32 v51, 1.0, v51
	v_rcp_f32_e32 v51, v51
	s_nop 0
	v_mul_f32_e32 v47, v47, v51
	v_mul_f32_e32 v51, 0x3d372713, v40
	v_fma_f32 v51, v40, v51, 1.0
	v_mul_f32_e32 v51, v40, v51
	v_mul_f32_e32 v51, 0xc0135761, v51
	v_exp_f32_e32 v51, v51
	s_nop 0
	v_add_f32_e32 v51, 1.0, v51
	v_rcp_f32_e32 v51, v51
	s_nop 0
	v_mul_f32_e32 v51, v40, v51
	v_mul_f32_e32 v40, 0x3d372713, v41
	v_fma_f32 v40, v41, v40, 1.0
	v_mul_f32_e32 v40, v41, v40
	v_mul_f32_e32 v40, 0xc0135761, v40
	v_exp_f32_e32 v40, v40
	v_pk_mul_f32 v[36:37], v[36:37], v[50:51] op_sel_hi:[1,0]
	v_pk_mul_f32 v[38:39], v[38:39], v[50:51] op_sel_hi:[1,0]
	v_pk_mul_f32 v[32:33], v[32:33], v[50:51] op_sel_hi:[1,0]
	v_add_f32_e32 v40, 1.0, v40
	v_rcp_f32_e32 v40, v40
	v_pk_mul_f32 v[34:35], v[34:35], v[50:51] op_sel_hi:[1,0]
	v_mul_f32_e32 v52, v41, v40
	v_mul_f32_e32 v40, 0x3d372713, v42
	v_fma_f32 v40, v42, v40, 1.0
	v_mul_f32_e32 v40, v42, v40
	v_mul_f32_e32 v40, 0xc0135761, v40
	v_exp_f32_e32 v40, v40
	s_nop 0
	v_add_f32_e32 v40, 1.0, v40
	v_rcp_f32_e32 v40, v40
	s_nop 0
	v_mul_f32_e32 v53, v42, v40
	v_mul_f32_e32 v40, 0x3d372713, v43
	v_fma_f32 v40, v43, v40, 1.0
	v_mul_f32_e32 v40, v43, v40
	v_mul_f32_e32 v40, 0xc0135761, v40
	v_exp_f32_e32 v40, v40
	s_nop 0
	v_add_f32_e32 v40, 1.0, v40
	v_rcp_f32_e32 v40, v40
	s_nop 0
	v_mul_f32_e32 v43, v43, v40
	v_cvt_pk_bf16_f32 v40, v44, v45
	v_add_co_u32_e32 v44, vcc, s0, v154
	v_cvt_pk_bf16_f32 v41, v46, v47
	v_cvt_pk_bf16_f32 v42, v51, v52
	v_cvt_pk_bf16_f32 v43, v53, v43
	s_nop 1
	v_addc_co_u32_e32 v45, vcc, 0, v155, vcc
	global_store_dwordx4 v[44:45], v[40:43], off
	s_nop 1
	v_mul_f32_e32 v40, 0x3d372713, v36
	v_fma_f32 v40, v36, v40, 1.0
	v_mul_f32_e32 v40, v36, v40
	v_mul_f32_e32 v40, 0xc0135761, v40
	v_exp_f32_e32 v40, v40
	s_nop 0
	v_add_f32_e32 v40, 1.0, v40
	v_rcp_f32_e32 v40, v40
	s_nop 0
	v_mul_f32_e32 v36, v36, v40
	v_mul_f32_e32 v40, 0x3d372713, v37
	v_fma_f32 v40, v37, v40, 1.0
	v_mul_f32_e32 v40, v37, v40
	v_mul_f32_e32 v40, 0xc0135761, v40
	v_exp_f32_e32 v40, v40
	s_nop 0
	v_add_f32_e32 v40, 1.0, v40
	v_rcp_f32_e32 v40, v40
	s_nop 0
	v_mul_f32_e32 v37, v37, v40
	v_mul_f32_e32 v40, 0x3d372713, v38
	v_fma_f32 v40, v38, v40, 1.0
	v_mul_f32_e32 v40, v38, v40
	v_mul_f32_e32 v40, 0xc0135761, v40
	v_exp_f32_e32 v40, v40
	s_nop 0
	v_add_f32_e32 v40, 1.0, v40
	v_rcp_f32_e32 v40, v40
	s_nop 0
	v_mul_f32_e32 v38, v38, v40
	v_mul_f32_e32 v40, 0x3d372713, v39
	v_fma_f32 v40, v39, v40, 1.0
	v_mul_f32_e32 v40, v39, v40
	v_mul_f32_e32 v40, 0xc0135761, v40
	v_exp_f32_e32 v40, v40
	s_nop 0
	v_add_f32_e32 v40, 1.0, v40
	v_rcp_f32_e32 v40, v40
	s_nop 0
	v_mul_f32_e32 v39, v39, v40
	v_mul_f32_e32 v40, 0x3d372713, v32
	v_fma_f32 v40, v32, v40, 1.0
	v_mul_f32_e32 v40, v32, v40
	v_mul_f32_e32 v40, 0xc0135761, v40
	v_exp_f32_e32 v40, v40
	s_nop 0
	v_add_f32_e32 v40, 1.0, v40
	v_rcp_f32_e32 v40, v40
	s_nop 0
	v_mul_f32_e32 v40, v32, v40
	v_mul_f32_e32 v32, 0x3d372713, v33
	v_fma_f32 v32, v33, v32, 1.0
	v_mul_f32_e32 v32, v33, v32
	v_mul_f32_e32 v32, 0xc0135761, v32
	v_exp_f32_e32 v32, v32
	s_nop 0
	v_add_f32_e32 v32, 1.0, v32
	v_rcp_f32_e32 v32, v32
	s_nop 0
	v_mul_f32_e32 v41, v33, v32
	v_mul_f32_e32 v32, 0x3d372713, v34
	v_fma_f32 v32, v34, v32, 1.0
	v_mul_f32_e32 v32, v34, v32
	v_mul_f32_e32 v32, 0xc0135761, v32
	v_exp_f32_e32 v32, v32
	s_nop 0
	v_add_f32_e32 v32, 1.0, v32
	v_rcp_f32_e32 v32, v32
	s_nop 0
	v_mul_f32_e32 v42, v34, v32
	v_mul_f32_e32 v32, 0x3d372713, v35
	v_fma_f32 v32, v35, v32, 1.0
	v_mul_f32_e32 v32, v35, v32
	v_mul_f32_e32 v32, 0xc0135761, v32
	v_exp_f32_e32 v32, v32
	s_nop 0
	v_add_f32_e32 v32, 1.0, v32
	v_rcp_f32_e32 v32, v32
	s_nop 0
	v_mul_f32_e32 v35, v35, v32
	v_cvt_pk_bf16_f32 v32, v36, v37
	v_cvt_pk_bf16_f32 v33, v38, v39
	v_cvt_pk_bf16_f32 v34, v40, v41
	v_cvt_pk_bf16_f32 v35, v42, v35
	global_store_dwordx4 v[48:49], v[32:35], off offset:256
	s_nop 1
	v_mov_b32_e32 v32, v206
	v_fmamk_f32 v32, v32, 0x3a800000, v172
	v_cmp_gt_f32_e32 vcc, s82, v32
	v_mul_f32_e32 v33, 0x4f800000, v32
	s_nop 0
	v_cndmask_b32_e32 v32, v32, v33, vcc
	v_sqrt_f32_e32 v33, v32
	s_nop 0
	v_add_u32_e32 v34, -1, v33
	v_fma_f32 v35, -v34, v33, v32
	v_cmp_ge_f32_e64 s[0:1], 0, v35
	v_add_u32_e32 v35, 1, v33
	s_nop 0
	v_cndmask_b32_e64 v34, v33, v34, s[0:1]
	v_fma_f32 v33, -v35, v33, v32
	v_cmp_lt_f32_e64 s[0:1], 0, v33
	s_nop 1
	v_cndmask_b32_e64 v33, v34, v35, s[0:1]
	v_mul_f32_e32 v34, 0x37800000, v33
	v_cndmask_b32_e32 v33, v33, v34, vcc
	v_cmp_class_f32_e32 vcc, v32, v173
	s_nop 1
	v_cndmask_b32_e32 v32, v33, v32, vcc
	v_div_scale_f32 v33, s[0:1], v32, v32, 1.0
	v_rcp_f32_e32 v34, v33
	s_mov_b64 s[0:1], 0x28000
	v_fma_f32 v35, -v33, v34, 1.0
	v_fmac_f32_e32 v34, v35, v34
	v_div_scale_f32 v35, vcc, 1.0, v32, 1.0
	v_mul_f32_e32 v36, v35, v34
	v_fma_f32 v37, -v33, v36, v35
	v_fmac_f32_e32 v36, v37, v34
	v_fma_f32 v33, -v33, v36, v35
	v_div_fmas_f32 v33, v33, v34, v36
	v_div_fixup_f32 v34, v33, v32, 1.0
	v_pk_mul_f32 v[28:29], v[28:29], v[34:35] op_sel_hi:[1,0]
	v_pk_mul_f32 v[30:31], v[30:31], v[34:35] op_sel_hi:[1,0]
; __device__ __forceinline__ u32x4 pack8(f32x4 a, f32x4 b) { u32x4 o; o.x = cvt_pk(a.x, a.y); o.y = cvt_pk(a.z, a.w); o.z = cvt_pk(b.x, b.y); o.w = cvt_pk(b.z, b.w); return o; }
; __device__ __forceinline__ float rstd_of(const float* SS, int row, float invw) { return 1.0f / sqrtf(SS[row] * invw + EPS); }
; __device__ __forceinline__ float gelu_f(float x) {
;     const float t = x * (1.f + 0.044715f * x * x);
;     return x * __builtin_amdgcn_rcpf(1.f + __builtin_amdgcn_exp2f(-2.3022081986f * t));
; }
;     __device__ __forceinline__ void operator()(const f32x4 (&acc)[2][2][4][2], const pg8::Unit& u, int wr, int wc, int fr, int fq) const {
;     ...
;             for (int ai = 0; ai < 2; ++ai)
; #pragma unroll
;                 for (int m = 0; m < 4; ++m) {
;                     const int row = row0 + ai * 128 + m * 16; const float r = rstd_of(SS1, row, 1.f / 1024.f);
; #pragma unroll
;                     for (int bj = 0; bj < 2; ++bj) {
;                         const f32x4 a = acc[ai][bj][m][0] * r, b = acc[ai][bj][m][1] * r;
;                         f32x4 ga, gb; ga.x = gelu_f(a.x); ga.y = gelu_f(a.y); ga.z = gelu_f(a.z); ga.w = gelu_f(a.w);
;                         gb.x = gelu_f(b.x); gb.y = gelu_f(b.y); gb.z = gelu_f(b.z); gb.w = gelu_f(b.w);
;                         *(u32x4*)(dst + (size_t)row * 512 + bj * 128) = pack8(ga, gb);
;                     }
	v_pk_mul_f32 v[26:27], v[26:27], v[34:35] op_sel_hi:[1,0]
	v_pk_mul_f32 v[24:25], v[24:25], v[34:35] op_sel_hi:[1,0]
	v_mul_f32_e32 v35, 0x3d372713, v28
	v_fma_f32 v35, v28, v35, 1.0
	v_mul_f32_e32 v35, v28, v35
	v_mul_f32_e32 v35, 0xc0135761, v35
	v_exp_f32_e32 v35, v35
	v_lshl_add_u64 v[32:33], v[154:155], 0, s[0:1]
	s_mov_b32 s0, 0x28000
	v_add_f32_e32 v35, 1.0, v35
	v_rcp_f32_e32 v35, v35
	s_nop 0
	v_mul_f32_e32 v28, v28, v35
	v_mul_f32_e32 v35, 0x3d372713, v29
	v_fma_f32 v35, v29, v35, 1.0
	v_mul_f32_e32 v35, v29, v35
	v_mul_f32_e32 v35, 0xc0135761, v35
	v_exp_f32_e32 v35, v35
	s_nop 0
	v_add_f32_e32 v35, 1.0, v35
	v_rcp_f32_e32 v35, v35
	s_nop 0
	v_mul_f32_e32 v29, v29, v35
	v_mul_f32_e32 v35, 0x3d372713, v30
	v_fma_f32 v35, v30, v35, 1.0
	v_mul_f32_e32 v35, v30, v35
	v_mul_f32_e32 v35, 0xc0135761, v35
	v_exp_f32_e32 v35, v35
	s_nop 0
	v_add_f32_e32 v35, 1.0, v35
	v_rcp_f32_e32 v35, v35
	s_nop 0
	v_mul_f32_e32 v30, v30, v35
	v_mul_f32_e32 v35, 0x3d372713, v31
	v_fma_f32 v35, v31, v35, 1.0
	v_mul_f32_e32 v35, v31, v35
	v_mul_f32_e32 v35, 0xc0135761, v35
	v_exp_f32_e32 v35, v35
	s_nop 0
	v_add_f32_e32 v35, 1.0, v35
	v_rcp_f32_e32 v35, v35
	s_nop 0
	v_mul_f32_e32 v31, v31, v35
	v_mul_f32_e32 v35, 0x3d372713, v24
	v_fma_f32 v35, v24, v35, 1.0
	v_mul_f32_e32 v35, v24, v35
	v_mul_f32_e32 v35, 0xc0135761, v35
	v_exp_f32_e32 v35, v35
	s_nop 0
	v_add_f32_e32 v35, 1.0, v35
	v_rcp_f32_e32 v35, v35
	s_nop 0
	v_mul_f32_e32 v35, v24, v35
	v_mul_f32_e32 v24, 0x3d372713, v25
	v_fma_f32 v24, v25, v24, 1.0
	v_mul_f32_e32 v24, v25, v24
	v_mul_f32_e32 v24, 0xc0135761, v24
	v_exp_f32_e32 v24, v24
	v_pk_mul_f32 v[20:21], v[20:21], v[34:35] op_sel_hi:[1,0]
	v_pk_mul_f32 v[22:23], v[22:23], v[34:35] op_sel_hi:[1,0]
	v_pk_mul_f32 v[16:17], v[16:17], v[34:35] op_sel_hi:[1,0]
	v_add_f32_e32 v24, 1.0, v24
	v_rcp_f32_e32 v24, v24
	v_pk_mul_f32 v[18:19], v[18:19], v[34:35] op_sel_hi:[1,0]
	v_mul_f32_e32 v36, v25, v24
	v_mul_f32_e32 v24, 0x3d372713, v26
	v_fma_f32 v24, v26, v24, 1.0
	v_mul_f32_e32 v24, v26, v24
	v_mul_f32_e32 v24, 0xc0135761, v24
	v_exp_f32_e32 v24, v24
	s_nop 0
	v_add_f32_e32 v24, 1.0, v24
	v_rcp_f32_e32 v24, v24
	s_nop 0
	v_mul_f32_e32 v37, v26, v24
	v_mul_f32_e32 v24, 0x3d372713, v27
	v_fma_f32 v24, v27, v24, 1.0
	v_mul_f32_e32 v24, v27, v24
	v_mul_f32_e32 v24, 0xc0135761, v24
	v_exp_f32_e32 v24, v24
	s_nop 0
	v_add_f32_e32 v24, 1.0, v24
	v_rcp_f32_e32 v24, v24
	s_nop 0
	v_mul_f32_e32 v27, v27, v24
	v_cvt_pk_bf16_f32 v24, v28, v29
	v_add_co_u32_e32 v28, vcc, s0, v154
	v_cvt_pk_bf16_f32 v25, v30, v31
	v_cvt_pk_bf16_f32 v26, v35, v36
	v_cvt_pk_bf16_f32 v27, v37, v27
	s_nop 1
	v_addc_co_u32_e32 v29, vcc, 0, v155, vcc
	global_store_dwordx4 v[28:29], v[24:27], off
	s_nop 1
	v_mul_f32_e32 v24, 0x3d372713, v20
	v_fma_f32 v24, v20, v24, 1.0
	v_mul_f32_e32 v24, v20, v24
	v_mul_f32_e32 v24, 0xc0135761, v24
	v_exp_f32_e32 v24, v24
	s_nop 0
	v_add_f32_e32 v24, 1.0, v24
	v_rcp_f32_e32 v24, v24
	s_nop 0
	v_mul_f32_e32 v20, v20, v24
	v_mul_f32_e32 v24, 0x3d372713, v21
	v_fma_f32 v24, v21, v24, 1.0
	v_mul_f32_e32 v24, v21, v24
	v_mul_f32_e32 v24, 0xc0135761, v24
	v_exp_f32_e32 v24, v24
	s_nop 0
	v_add_f32_e32 v24, 1.0, v24
	v_rcp_f32_e32 v24, v24
	s_nop 0
	v_mul_f32_e32 v21, v21, v24
	v_mul_f32_e32 v24, 0x3d372713, v22
	v_fma_f32 v24, v22, v24, 1.0
	v_mul_f32_e32 v24, v22, v24
	v_mul_f32_e32 v24, 0xc0135761, v24
	v_exp_f32_e32 v24, v24
	s_nop 0
	v_add_f32_e32 v24, 1.0, v24
	v_rcp_f32_e32 v24, v24
	s_nop 0
	v_mul_f32_e32 v22, v22, v24
	v_mul_f32_e32 v24, 0x3d372713, v23
	v_fma_f32 v24, v23, v24, 1.0
	v_mul_f32_e32 v24, v23, v24
	v_mul_f32_e32 v24, 0xc0135761, v24
	v_exp_f32_e32 v24, v24
	s_nop 0
	v_add_f32_e32 v24, 1.0, v24
	v_rcp_f32_e32 v24, v24
	s_nop 0
	v_mul_f32_e32 v23, v23, v24
	v_mul_f32_e32 v24, 0x3d372713, v16
	v_fma_f32 v24, v16, v24, 1.0
	v_mul_f32_e32 v24, v16, v24
	v_mul_f32_e32 v24, 0xc0135761, v24
	v_exp_f32_e32 v24, v24
	s_nop 0
	v_add_f32_e32 v24, 1.0, v24
	v_rcp_f32_e32 v24, v24
	s_nop 0
	v_mul_f32_e32 v24, v16, v24
	v_mul_f32_e32 v16, 0x3d372713, v17
	v_fma_f32 v16, v17, v16, 1.0
	v_mul_f32_e32 v16, v17, v16
	v_mul_f32_e32 v16, 0xc0135761, v16
	v_exp_f32_e32 v16, v16
	s_nop 0
	v_add_f32_e32 v16, 1.0, v16
	v_rcp_f32_e32 v16, v16
	s_nop 0
	v_mul_f32_e32 v25, v17, v16
	v_mul_f32_e32 v16, 0x3d372713, v18
	v_fma_f32 v16, v18, v16, 1.0
	v_mul_f32_e32 v16, v18, v16
	v_mul_f32_e32 v16, 0xc0135761, v16
	v_exp_f32_e32 v16, v16
	s_nop 0
	v_add_f32_e32 v16, 1.0, v16
	v_rcp_f32_e32 v16, v16
	s_nop 0
	v_mul_f32_e32 v26, v18, v16
	v_mul_f32_e32 v16, 0x3d372713, v19
	v_fma_f32 v16, v19, v16, 1.0
	v_mul_f32_e32 v16, v19, v16
	v_mul_f32_e32 v16, 0xc0135761, v16
	v_exp_f32_e32 v16, v16
	s_nop 0
	v_add_f32_e32 v16, 1.0, v16
	v_rcp_f32_e32 v16, v16
	s_nop 0
	v_mul_f32_e32 v19, v19, v16
	v_cvt_pk_bf16_f32 v16, v20, v21
	v_cvt_pk_bf16_f32 v17, v22, v23
	v_cvt_pk_bf16_f32 v18, v24, v25
	v_cvt_pk_bf16_f32 v19, v26, v19
	global_store_dwordx4 v[32:33], v[16:19], off offset:256
	s_nop 1
	v_mov_b32_e32 v16, v207
	v_fmamk_f32 v16, v16, 0x3a800000, v172
	v_cmp_gt_f32_e32 vcc, s82, v16
	v_mul_f32_e32 v17, 0x4f800000, v16
	s_nop 0
	v_cndmask_b32_e32 v16, v16, v17, vcc
	v_sqrt_f32_e32 v17, v16
	s_nop 0
	v_add_u32_e32 v18, -1, v17
	v_fma_f32 v19, -v18, v17, v16
	v_cmp_ge_f32_e64 s[0:1], 0, v19
	v_add_u32_e32 v19, 1, v17
	s_nop 0
	v_cndmask_b32_e64 v18, v17, v18, s[0:1]
	v_fma_f32 v17, -v19, v17, v16
	v_cmp_lt_f32_e64 s[0:1], 0, v17
	s_nop 1
	v_cndmask_b32_e64 v17, v18, v19, s[0:1]
; __device__ __forceinline__ u32x4 pack8(f32x4 a, f32x4 b) { u32x4 o; o.x = cvt_pk(a.x, a.y); o.y = cvt_pk(a.z, a.w); o.z = cvt_pk(b.x, b.y); o.w = cvt_pk(b.z, b.w); return o; }
; __device__ __forceinline__ float rstd_of(const float* SS, int row, float invw) { return 1.0f / sqrtf(SS[row] * invw + EPS); }
; template <class Epi, class Sched, bool ALIGN_EPI = false, bool SP2 = false, bool ABLK = false>
; __device__ __forceinline__ void gemm_phase(PG8_LAS unsigned char* lds, const Gemm g, const Sched& S, const Epi& E) {
;     ...
;         if (!has_next) break;
; #pragma unroll
;         for (int a = 0; a < 2; ++a)
; #pragma unroll
;             for (int b = 0; b < 2; ++b)
; #pragma unroll
;                 for (int m = 0; m < 4; ++m)
; #pragma unroll
;                     for (int n = 0; n < 2; ++n) acc[a][b][m][n] = (f32x4){0.f, 0.f, 0.f, 0.f};
;         cur = nxt; cA = nA; cB = nB; ++ui;
; __device__ __forceinline__ float gelu_f(float x) {
;     const float t = x * (1.f + 0.044715f * x * x);
;     return x * __builtin_amdgcn_rcpf(1.f + __builtin_amdgcn_exp2f(-2.3022081986f * t));
; }
;     __device__ __forceinline__ void operator()(const f32x4 (&acc)[2][2][4][2], const pg8::Unit& u, int wr, int wc, int fr, int fq) const {
;     ...
;             for (int ai = 0; ai < 2; ++ai)
; #pragma unroll
;                 for (int m = 0; m < 4; ++m) {
;                     const int row = row0 + ai * 128 + m * 16; const float r = rstd_of(SS1, row, 1.f / 1024.f);
; #pragma unroll
;                     for (int bj = 0; bj < 2; ++bj) {
;                         const f32x4 a = acc[ai][bj][m][0] * r, b = acc[ai][bj][m][1] * r;
;                         f32x4 ga, gb; ga.x = gelu_f(a.x); ga.y = gelu_f(a.y); ga.z = gelu_f(a.z); ga.w = gelu_f(a.w);
;                         gb.x = gelu_f(b.x); gb.y = gelu_f(b.y); gb.z = gelu_f(b.z); gb.w = gelu_f(b.w);
;                         *(u32x4*)(dst + (size_t)row * 512 + bj * 128) = pack8(ga, gb);
;                     }
	v_mul_f32_e32 v18, 0x37800000, v17
	v_cndmask_b32_e32 v17, v17, v18, vcc
	v_cmp_class_f32_e32 vcc, v16, v173
	s_nop 1
	v_cndmask_b32_e32 v16, v17, v16, vcc
	v_div_scale_f32 v17, s[0:1], v16, v16, 1.0
	v_rcp_f32_e32 v18, v17
	s_mov_b64 s[0:1], 0x2c000
	v_fma_f32 v19, -v17, v18, 1.0
	v_fmac_f32_e32 v18, v19, v18
	v_div_scale_f32 v19, vcc, 1.0, v16, 1.0
	v_mul_f32_e32 v20, v19, v18
	v_fma_f32 v21, -v17, v20, v19
	v_fmac_f32_e32 v20, v21, v18
	v_fma_f32 v17, -v17, v20, v19
	v_div_fmas_f32 v17, v17, v18, v20
	v_div_fixup_f32 v18, v17, v16, 1.0
	v_pk_mul_f32 v[12:13], v[12:13], v[18:19] op_sel_hi:[1,0]
	v_pk_mul_f32 v[14:15], v[14:15], v[18:19] op_sel_hi:[1,0]
	v_pk_mul_f32 v[10:11], v[10:11], v[18:19] op_sel_hi:[1,0]
	v_pk_mul_f32 v[8:9], v[8:9], v[18:19] op_sel_hi:[1,0]
	v_mul_f32_e32 v19, 0x3d372713, v12
	v_fma_f32 v19, v12, v19, 1.0
	v_mul_f32_e32 v19, v12, v19
	v_mul_f32_e32 v19, 0xc0135761, v19
	v_exp_f32_e32 v19, v19
	v_lshl_add_u64 v[16:17], v[154:155], 0, s[0:1]
	s_mov_b32 s0, 0x2c000
	v_add_f32_e32 v19, 1.0, v19
	v_rcp_f32_e32 v19, v19
	s_nop 0
	v_mul_f32_e32 v12, v12, v19
	v_mul_f32_e32 v19, 0x3d372713, v13
	v_fma_f32 v19, v13, v19, 1.0
	v_mul_f32_e32 v19, v13, v19
	v_mul_f32_e32 v19, 0xc0135761, v19
	v_exp_f32_e32 v19, v19
	s_nop 0
	v_add_f32_e32 v19, 1.0, v19
	v_rcp_f32_e32 v19, v19
	s_nop 0
	v_mul_f32_e32 v13, v13, v19
	v_mul_f32_e32 v19, 0x3d372713, v14
	v_fma_f32 v19, v14, v19, 1.0
	v_mul_f32_e32 v19, v14, v19
	v_mul_f32_e32 v19, 0xc0135761, v19
	v_exp_f32_e32 v19, v19
	s_nop 0
	v_add_f32_e32 v19, 1.0, v19
	v_rcp_f32_e32 v19, v19
	s_nop 0
	v_mul_f32_e32 v14, v14, v19
	v_mul_f32_e32 v19, 0x3d372713, v15
	v_fma_f32 v19, v15, v19, 1.0
	v_mul_f32_e32 v19, v15, v19
	v_mul_f32_e32 v19, 0xc0135761, v19
	v_exp_f32_e32 v19, v19
	s_nop 0
	v_add_f32_e32 v19, 1.0, v19
	v_rcp_f32_e32 v19, v19
	s_nop 0
	v_mul_f32_e32 v15, v15, v19
	v_mul_f32_e32 v19, 0x3d372713, v8
	v_fma_f32 v19, v8, v19, 1.0
	v_mul_f32_e32 v19, v8, v19
	v_mul_f32_e32 v19, 0xc0135761, v19
	v_exp_f32_e32 v19, v19
	s_nop 0
	v_add_f32_e32 v19, 1.0, v19
	v_rcp_f32_e32 v19, v19
	s_nop 0
	v_mul_f32_e32 v19, v8, v19
	v_mul_f32_e32 v8, 0x3d372713, v9
	v_fma_f32 v8, v9, v8, 1.0
	v_mul_f32_e32 v8, v9, v8
	v_mul_f32_e32 v8, 0xc0135761, v8
	v_exp_f32_e32 v8, v8
	v_pk_mul_f32 v[4:5], v[4:5], v[18:19] op_sel_hi:[1,0]
	v_pk_mul_f32 v[6:7], v[6:7], v[18:19] op_sel_hi:[1,0]
	v_pk_mul_f32 v[0:1], v[0:1], v[18:19] op_sel_hi:[1,0]
	v_add_f32_e32 v8, 1.0, v8
	v_rcp_f32_e32 v8, v8
	v_pk_mul_f32 v[2:3], v[2:3], v[18:19] op_sel_hi:[1,0]
	v_mul_f32_e32 v20, v9, v8
	v_mul_f32_e32 v8, 0x3d372713, v10
	v_fma_f32 v8, v10, v8, 1.0
	v_mul_f32_e32 v8, v10, v8
	v_mul_f32_e32 v8, 0xc0135761, v8
	v_exp_f32_e32 v8, v8
	s_nop 0
	v_add_f32_e32 v8, 1.0, v8
	v_rcp_f32_e32 v8, v8
	s_nop 0
	v_mul_f32_e32 v21, v10, v8
	v_mul_f32_e32 v8, 0x3d372713, v11
	v_fma_f32 v8, v11, v8, 1.0
	v_mul_f32_e32 v8, v11, v8
	v_mul_f32_e32 v8, 0xc0135761, v8
	v_exp_f32_e32 v8, v8
	s_nop 0
	v_add_f32_e32 v8, 1.0, v8
	v_rcp_f32_e32 v8, v8
	s_nop 0
	v_mul_f32_e32 v11, v11, v8
	v_cvt_pk_bf16_f32 v8, v12, v13
	v_add_co_u32_e32 v12, vcc, s0, v154
	v_cvt_pk_bf16_f32 v9, v14, v15
	v_cvt_pk_bf16_f32 v10, v19, v20
	v_cvt_pk_bf16_f32 v11, v21, v11
	s_nop 1
	v_addc_co_u32_e32 v13, vcc, 0, v155, vcc
	global_store_dwordx4 v[12:13], v[8:11], off
	s_nop 1
	v_mul_f32_e32 v8, 0x3d372713, v4
	v_fma_f32 v8, v4, v8, 1.0
	v_mul_f32_e32 v8, v4, v8
	v_mul_f32_e32 v8, 0xc0135761, v8
	v_exp_f32_e32 v8, v8
	s_nop 0
	v_add_f32_e32 v8, 1.0, v8
	v_rcp_f32_e32 v8, v8
	s_nop 0
	v_mul_f32_e32 v4, v4, v8
	v_mul_f32_e32 v8, 0x3d372713, v5
	v_fma_f32 v8, v5, v8, 1.0
	v_mul_f32_e32 v8, v5, v8
	v_mul_f32_e32 v8, 0xc0135761, v8
	v_exp_f32_e32 v8, v8
	s_nop 0
	v_add_f32_e32 v8, 1.0, v8
	v_rcp_f32_e32 v8, v8
	s_nop 0
	v_mul_f32_e32 v5, v5, v8
	v_mul_f32_e32 v8, 0x3d372713, v6
	v_fma_f32 v8, v6, v8, 1.0
	v_mul_f32_e32 v8, v6, v8
	v_mul_f32_e32 v8, 0xc0135761, v8
	v_exp_f32_e32 v8, v8
	s_nop 0
	v_add_f32_e32 v8, 1.0, v8
	v_rcp_f32_e32 v8, v8
	s_nop 0
	v_mul_f32_e32 v6, v6, v8
	v_mul_f32_e32 v8, 0x3d372713, v7
	v_fma_f32 v8, v7, v8, 1.0
	v_mul_f32_e32 v8, v7, v8
	v_mul_f32_e32 v8, 0xc0135761, v8
	v_exp_f32_e32 v8, v8
	s_nop 0
	v_add_f32_e32 v8, 1.0, v8
	v_rcp_f32_e32 v8, v8
	s_nop 0
	v_mul_f32_e32 v7, v7, v8
	v_mul_f32_e32 v8, 0x3d372713, v0
	v_fma_f32 v8, v0, v8, 1.0
	v_mul_f32_e32 v8, v0, v8
	v_mul_f32_e32 v8, 0xc0135761, v8
	v_exp_f32_e32 v8, v8
	s_nop 0
	v_add_f32_e32 v8, 1.0, v8
	v_rcp_f32_e32 v8, v8
	s_nop 0
	v_mul_f32_e32 v8, v0, v8
	v_mul_f32_e32 v0, 0x3d372713, v1
	v_fma_f32 v0, v1, v0, 1.0
	v_mul_f32_e32 v0, v1, v0
	v_mul_f32_e32 v0, 0xc0135761, v0
	v_exp_f32_e32 v0, v0
	s_nop 0
	v_add_f32_e32 v0, 1.0, v0
	v_rcp_f32_e32 v0, v0
	s_nop 0
	v_mul_f32_e32 v9, v1, v0
	v_mul_f32_e32 v0, 0x3d372713, v2
	v_fma_f32 v0, v2, v0, 1.0
	v_mul_f32_e32 v0, v2, v0
	v_mul_f32_e32 v0, 0xc0135761, v0
	v_exp_f32_e32 v0, v0
	s_nop 0
	v_add_f32_e32 v0, 1.0, v0
	v_rcp_f32_e32 v0, v0
	s_nop 0
	v_mul_f32_e32 v10, v2, v0
	v_mul_f32_e32 v0, 0x3d372713, v3
	v_fma_f32 v0, v3, v0, 1.0
	v_mul_f32_e32 v0, v3, v0
	v_mul_f32_e32 v0, 0xc0135761, v0
	v_exp_f32_e32 v0, v0
	s_nop 0
	v_add_f32_e32 v0, 1.0, v0
	v_rcp_f32_e32 v0, v0
	s_nop 0
	v_mul_f32_e32 v3, v3, v0
	v_cvt_pk_bf16_f32 v0, v4, v5
	v_cvt_pk_bf16_f32 v1, v6, v7
	v_cvt_pk_bf16_f32 v2, v8, v9
	v_cvt_pk_bf16_f32 v3, v10, v3
	global_store_dwordx4 v[16:17], v[0:3], off offset:256
	s_andn2_b64 vcc, exec, s[40:41]
	s_mov_b64 s[0:1], -1
	s_cbranch_vccnz .LBB0_341

; __device__ __forceinline__ u32x4 pack8(f32x4 a, f32x4 b) { u32x4 o; o.x = cvt_pk(a.x, a.y); o.y = cvt_pk(a.z, a.w); o.z = cvt_pk(b.x, b.y); o.w = cvt_pk(b.z, b.w); return o; }
; __device__ __forceinline__ float rstd_of(const float* SS, int row, float invw) { return 1.0f / sqrtf(SS[row] * invw + EPS); }
;     __device__ __forceinline__ void operator()(const f32x4 (&acc)[2][2][4][2], const pg8::Unit& u, int wr, int wc, int fr, int fq) const {
;     ...
; #pragma unroll
;         for (int ai = 0; ai < 2; ++ai)
; #pragma unroll
;             for (int m = 0; m < 4; ++m) {
;                 const int row = row0 + ai * 128 + m * 16; const float r = rstd_of(SS, row, invw);
; #pragma unroll
;                 for (int bj = 0; bj < 2; ++bj)
;                     *(u32x4*)(O + (size_t)row * ldc + col0 + bj * 128) = pack8(acc[ai][bj][m][0] * r, acc[ai][bj][m][1] * r);
;             }
.LBB0_475:
	v_lshl_add_u32 v140, s0, 8, v144
	v_ashrrev_i32_e32 v141, 31, v140
	v_lshl_add_u64 v[142:143], v[140:141], 2, s[46:47]
	global_load_dword v200, v[142:143], off
	global_load_dword v201, v[142:143], off offset:64
	global_load_dword v202, v[142:143], off offset:128
	global_load_dword v203, v[142:143], off offset:192
	global_load_dword v204, v[142:143], off offset:512
	global_load_dword v205, v[142:143], off offset:576
	global_load_dword v206, v[142:143], off offset:640
	global_load_dword v207, v[142:143], off offset:704
	v_lshl_or_b32 v152, s1, 8, v146
	v_ashrrev_i32_e32 v153, 31, v152
	s_waitcnt vmcnt(0)
	v_mov_b32_e32 v141, v200
	v_fmamk_f32 v141, v141, 0x3b800000, v150
	v_cmp_gt_f32_e32 vcc, s9, v141
	v_mul_f32_e32 v154, 0x4f800000, v141
	s_nop 0
	v_cndmask_b32_e32 v141, v141, v154, vcc
	v_sqrt_f32_e32 v154, v141
	s_nop 0
	v_add_u32_e32 v155, -1, v154
	v_fma_f32 v156, -v155, v154, v141
	v_cmp_ge_f32_e64 s[0:1], 0, v156
	v_add_u32_e32 v156, 1, v154
	s_nop 0
	v_cndmask_b32_e64 v155, v154, v155, s[0:1]
	v_fma_f32 v154, -v156, v154, v141
	v_cmp_lt_f32_e64 s[0:1], 0, v154
	s_nop 1
	v_cndmask_b32_e64 v154, v155, v156, s[0:1]
	v_mul_f32_e32 v155, 0x37800000, v154
	v_cndmask_b32_e32 v154, v154, v155, vcc
	v_cmp_class_f32_e32 vcc, v141, v151
	s_nop 1
	v_cndmask_b32_e32 v141, v154, v141, vcc
	v_div_scale_f32 v154, s[0:1], v141, v141, 1.0
	v_rcp_f32_e32 v155, v154
	s_nop 0
	v_fma_f32 v156, -v154, v155, 1.0
	v_fmac_f32_e32 v155, v156, v155
	v_div_scale_f32 v156, vcc, 1.0, v141, 1.0
	v_mul_f32_e32 v157, v156, v155
	v_fma_f32 v158, -v154, v157, v156
	v_fmac_f32_e32 v157, v158, v155
	v_fma_f32 v154, -v154, v157, v156
	v_div_fmas_f32 v154, v154, v155, v157
	v_div_fixup_f32 v154, v154, v141, 1.0
	v_pk_mul_f32 v[126:127], v[126:127], v[154:155] op_sel_hi:[1,0]
	v_pk_mul_f32 v[124:125], v[124:125], v[154:155] op_sel_hi:[1,0]
	v_pk_mul_f32 v[120:121], v[120:121], v[154:155] op_sel_hi:[1,0]
	v_pk_mul_f32 v[122:123], v[122:123], v[154:155] op_sel_hi:[1,0]
	v_cvt_pk_bf16_f32 v124, v124, v125
	v_cvt_pk_bf16_f32 v125, v126, v127
	v_cvt_pk_bf16_f32 v126, v120, v121
	v_mov_b64_e32 v[120:121], s[34:35]
	v_cvt_pk_bf16_f32 v127, v122, v123
	v_mad_i64_i32 v[156:157], s[0:1], v140, s10, v[120:121]
	v_lshlrev_b64 v[122:123], 1, v[152:153]
	v_lshl_add_u64 v[152:153], v[156:157], 0, v[122:123]
	global_store_dwordx4 v[152:153], v[124:127], off
	v_pk_mul_f32 v[116:117], v[116:117], v[154:155] op_sel_hi:[1,0]
	v_pk_mul_f32 v[118:119], v[118:119], v[154:155] op_sel_hi:[1,0]
	v_pk_mul_f32 v[124:125], v[114:115], v[154:155] op_sel_hi:[1,0]
	v_pk_mul_f32 v[114:115], v[112:113], v[154:155] op_sel_hi:[1,0]
	v_cvt_pk_bf16_f32 v112, v116, v117
	v_cvt_pk_bf16_f32 v113, v118, v119
	s_nop 0
	v_cvt_pk_bf16_f32 v114, v114, v115
	v_cvt_pk_bf16_f32 v115, v124, v125
	global_store_dwordx4 v[152:153], v[112:115], off offset:256
	s_nop 1
	v_or_b32_e32 v112, 16, v140
	v_ashrrev_i32_e32 v113, 31, v112
	v_lshl_add_u64 v[114:115], v[112:113], 2, s[46:47]
	s_nop 1
	v_mov_b32_e32 v113, v201
	v_fmamk_f32 v113, v113, 0x3b800000, v150
	v_cmp_gt_f32_e32 vcc, s9, v113
	v_mul_f32_e32 v114, 0x4f800000, v113
	s_nop 0
	v_cndmask_b32_e32 v113, v113, v114, vcc
	v_sqrt_f32_e32 v114, v113
	s_nop 0
	v_add_u32_e32 v115, -1, v114
	v_fma_f32 v116, -v115, v114, v113
	v_cmp_ge_f32_e64 s[0:1], 0, v116
	v_add_u32_e32 v116, 1, v114
	s_nop 0
	v_cndmask_b32_e64 v115, v114, v115, s[0:1]
	v_fma_f32 v114, -v116, v114, v113
	v_cmp_lt_f32_e64 s[0:1], 0, v114
	s_nop 1
	v_cndmask_b32_e64 v114, v115, v116, s[0:1]
	v_mul_f32_e32 v115, 0x37800000, v114
	v_cndmask_b32_e32 v114, v114, v115, vcc
	v_cmp_class_f32_e32 vcc, v113, v151
	s_nop 1
	v_cndmask_b32_e32 v113, v114, v113, vcc
	v_div_scale_f32 v114, s[0:1], v113, v113, 1.0
	v_rcp_f32_e32 v115, v114
	s_nop 0
	v_fma_f32 v116, -v114, v115, 1.0
	v_fmac_f32_e32 v115, v116, v115
	v_div_scale_f32 v116, vcc, 1.0, v113, 1.0
	v_mul_f32_e32 v117, v116, v115
	v_fma_f32 v118, -v114, v117, v116
	v_fmac_f32_e32 v117, v118, v115
	v_fma_f32 v114, -v114, v117, v116
	v_div_fmas_f32 v114, v114, v115, v117
	v_div_fixup_f32 v114, v114, v113, 1.0
	v_pk_mul_f32 v[108:109], v[108:109], v[114:115] op_sel_hi:[1,0]
	v_pk_mul_f32 v[116:117], v[106:107], v[114:115] op_sel_hi:[1,0]
	v_pk_mul_f32 v[106:107], v[104:105], v[114:115] op_sel_hi:[1,0]
	v_cvt_pk_bf16_f32 v104, v108, v109
	v_mad_i64_i32 v[108:109], s[0:1], v112, s10, v[120:121]
	v_pk_mul_f32 v[110:111], v[110:111], v[114:115] op_sel_hi:[1,0]
	v_lshl_add_u64 v[108:109], v[108:109], 0, v[122:123]
	v_cvt_pk_bf16_f32 v105, v110, v111
	v_cvt_pk_bf16_f32 v106, v106, v107
	v_cvt_pk_bf16_f32 v107, v116, v117
	global_store_dwordx4 v[108:109], v[104:107], off
	v_pk_mul_f32 v[100:101], v[100:101], v[114:115] op_sel_hi:[1,0]
	v_pk_mul_f32 v[102:103], v[102:103], v[114:115] op_sel_hi:[1,0]
	v_pk_mul_f32 v[104:105], v[98:99], v[114:115] op_sel_hi:[1,0]
	v_pk_mul_f32 v[98:99], v[96:97], v[114:115] op_sel_hi:[1,0]
	v_cvt_pk_bf16_f32 v96, v100, v101
	v_cvt_pk_bf16_f32 v97, v102, v103
	s_nop 0
	v_cvt_pk_bf16_f32 v98, v98, v99
	v_cvt_pk_bf16_f32 v99, v104, v105
	global_store_dwordx4 v[108:109], v[96:99], off offset:256
	s_nop 1
	v_or_b32_e32 v96, 32, v140
	v_ashrrev_i32_e32 v97, 31, v96
	v_lshl_add_u64 v[98:99], v[96:97], 2, s[46:47]
	s_nop 1
	v_mov_b32_e32 v97, v202
	v_fmamk_f32 v97, v97, 0x3b800000, v150
	v_cmp_gt_f32_e32 vcc, s9, v97
	v_mul_f32_e32 v98, 0x4f800000, v97
	s_nop 0
	v_cndmask_b32_e32 v97, v97, v98, vcc
	v_sqrt_f32_e32 v98, v97
	s_nop 0
	v_add_u32_e32 v99, -1, v98
	v_fma_f32 v100, -v99, v98, v97
	v_cmp_ge_f32_e64 s[0:1], 0, v100
	v_add_u32_e32 v100, 1, v98
	s_nop 0
	v_cndmask_b32_e64 v99, v98, v99, s[0:1]
	v_fma_f32 v98, -v100, v98, v97
; __device__ __forceinline__ u32x4 pack8(f32x4 a, f32x4 b) { u32x4 o; o.x = cvt_pk(a.x, a.y); o.y = cvt_pk(a.z, a.w); o.z = cvt_pk(b.x, b.y); o.w = cvt_pk(b.z, b.w); return o; }
; __device__ __forceinline__ float rstd_of(const float* SS, int row, float invw) { return 1.0f / sqrtf(SS[row] * invw + EPS); }
;     __device__ __forceinline__ void operator()(const f32x4 (&acc)[2][2][4][2], const pg8::Unit& u, int wr, int wc, int fr, int fq) const {
;     ...
; #pragma unroll
;         for (int ai = 0; ai < 2; ++ai)
; #pragma unroll
;             for (int m = 0; m < 4; ++m) {
;                 const int row = row0 + ai * 128 + m * 16; const float r = rstd_of(SS, row, invw);
; #pragma unroll
;                 for (int bj = 0; bj < 2; ++bj)
;                     *(u32x4*)(O + (size_t)row * ldc + col0 + bj * 128) = pack8(acc[ai][bj][m][0] * r, acc[ai][bj][m][1] * r);
;             }
	v_cmp_lt_f32_e64 s[0:1], 0, v98
	s_nop 1
	v_cndmask_b32_e64 v98, v99, v100, s[0:1]
	v_mul_f32_e32 v99, 0x37800000, v98
	v_cndmask_b32_e32 v98, v98, v99, vcc
	v_cmp_class_f32_e32 vcc, v97, v151
	s_nop 1
	v_cndmask_b32_e32 v97, v98, v97, vcc
	v_div_scale_f32 v98, s[0:1], v97, v97, 1.0
	v_rcp_f32_e32 v99, v98
	s_nop 0
	v_fma_f32 v100, -v98, v99, 1.0
	v_fmac_f32_e32 v99, v100, v99
	v_div_scale_f32 v100, vcc, 1.0, v97, 1.0
	v_mul_f32_e32 v101, v100, v99
	v_fma_f32 v102, -v98, v101, v100
	v_fmac_f32_e32 v101, v102, v99
	v_fma_f32 v98, -v98, v101, v100
	v_div_fmas_f32 v98, v98, v99, v101
	v_div_fixup_f32 v98, v98, v97, 1.0
	v_pk_mul_f32 v[92:93], v[92:93], v[98:99] op_sel_hi:[1,0]
	v_pk_mul_f32 v[100:101], v[90:91], v[98:99] op_sel_hi:[1,0]
	v_pk_mul_f32 v[90:91], v[88:89], v[98:99] op_sel_hi:[1,0]
	v_cvt_pk_bf16_f32 v88, v92, v93
	v_mad_i64_i32 v[92:93], s[0:1], v96, s10, v[120:121]
	v_pk_mul_f32 v[94:95], v[94:95], v[98:99] op_sel_hi:[1,0]
	v_lshl_add_u64 v[92:93], v[92:93], 0, v[122:123]
	v_cvt_pk_bf16_f32 v89, v94, v95
	v_cvt_pk_bf16_f32 v90, v90, v91
	v_cvt_pk_bf16_f32 v91, v100, v101
	global_store_dwordx4 v[92:93], v[88:91], off
	v_pk_mul_f32 v[84:85], v[84:85], v[98:99] op_sel_hi:[1,0]
	v_pk_mul_f32 v[86:87], v[86:87], v[98:99] op_sel_hi:[1,0]
	v_pk_mul_f32 v[88:89], v[82:83], v[98:99] op_sel_hi:[1,0]
	v_pk_mul_f32 v[82:83], v[80:81], v[98:99] op_sel_hi:[1,0]
	v_cvt_pk_bf16_f32 v80, v84, v85
	v_cvt_pk_bf16_f32 v81, v86, v87
	s_nop 0
	v_cvt_pk_bf16_f32 v82, v82, v83
	v_cvt_pk_bf16_f32 v83, v88, v89
	global_store_dwordx4 v[92:93], v[80:83], off offset:256
	s_nop 1
	v_or_b32_e32 v80, 48, v140
	v_ashrrev_i32_e32 v81, 31, v80
	v_lshl_add_u64 v[82:83], v[80:81], 2, s[46:47]
	s_nop 1
	v_mov_b32_e32 v81, v203
	v_fmamk_f32 v81, v81, 0x3b800000, v150
	v_cmp_gt_f32_e32 vcc, s9, v81
	v_mul_f32_e32 v82, 0x4f800000, v81
	s_nop 0
	v_cndmask_b32_e32 v81, v81, v82, vcc
	v_sqrt_f32_e32 v82, v81
	s_nop 0
	v_add_u32_e32 v83, -1, v82
	v_fma_f32 v84, -v83, v82, v81
	v_cmp_ge_f32_e64 s[0:1], 0, v84
	v_add_u32_e32 v84, 1, v82
	s_nop 0
	v_cndmask_b32_e64 v83, v82, v83, s[0:1]
	v_fma_f32 v82, -v84, v82, v81
	v_cmp_lt_f32_e64 s[0:1], 0, v82
	s_nop 1
	v_cndmask_b32_e64 v82, v83, v84, s[0:1]
	v_mul_f32_e32 v83, 0x37800000, v82
	v_cndmask_b32_e32 v82, v82, v83, vcc
	v_cmp_class_f32_e32 vcc, v81, v151
	s_nop 1
	v_cndmask_b32_e32 v81, v82, v81, vcc
	v_div_scale_f32 v82, s[0:1], v81, v81, 1.0
	v_rcp_f32_e32 v83, v82
	s_nop 0
	v_fma_f32 v84, -v82, v83, 1.0
	v_fmac_f32_e32 v83, v84, v83
	v_div_scale_f32 v84, vcc, 1.0, v81, 1.0
	v_mul_f32_e32 v85, v84, v83
	v_fma_f32 v86, -v82, v85, v84
	v_fmac_f32_e32 v85, v86, v83
	v_fma_f32 v82, -v82, v85, v84
	v_div_fmas_f32 v82, v82, v83, v85
	v_div_fixup_f32 v82, v82, v81, 1.0
	v_pk_mul_f32 v[76:77], v[76:77], v[82:83] op_sel_hi:[1,0]
	v_pk_mul_f32 v[84:85], v[74:75], v[82:83] op_sel_hi:[1,0]
	v_pk_mul_f32 v[74:75], v[72:73], v[82:83] op_sel_hi:[1,0]
	v_cvt_pk_bf16_f32 v72, v76, v77
	v_mad_i64_i32 v[76:77], s[0:1], v80, s10, v[120:121]
	v_pk_mul_f32 v[78:79], v[78:79], v[82:83] op_sel_hi:[1,0]
	v_lshl_add_u64 v[76:77], v[76:77], 0, v[122:123]
	v_cvt_pk_bf16_f32 v73, v78, v79
	v_cvt_pk_bf16_f32 v74, v74, v75
	v_cvt_pk_bf16_f32 v75, v84, v85
	global_store_dwordx4 v[76:77], v[72:75], off
	v_pk_mul_f32 v[70:71], v[70:71], v[82:83] op_sel_hi:[1,0]
	v_pk_mul_f32 v[68:69], v[68:69], v[82:83] op_sel_hi:[1,0]
	v_pk_mul_f32 v[72:73], v[66:67], v[82:83] op_sel_hi:[1,0]
	v_pk_mul_f32 v[66:67], v[64:65], v[82:83] op_sel_hi:[1,0]
	v_cvt_pk_bf16_f32 v64, v68, v69
	v_cvt_pk_bf16_f32 v65, v70, v71
	s_nop 0
	v_cvt_pk_bf16_f32 v66, v66, v67
	v_cvt_pk_bf16_f32 v67, v72, v73
	global_store_dwordx4 v[76:77], v[64:67], off offset:256
	s_nop 1
	s_nop 0
	v_add_u32_e32 v65, 0x80, v140
	v_mov_b32_e32 v64, v204
	v_fmamk_f32 v64, v64, 0x3b800000, v150
	v_cmp_gt_f32_e32 vcc, s9, v64
	v_mul_f32_e32 v66, 0x4f800000, v64
	s_nop 0
	v_cndmask_b32_e32 v64, v64, v66, vcc
	v_sqrt_f32_e32 v66, v64
	s_nop 0
	v_add_u32_e32 v67, -1, v66
	v_fma_f32 v68, -v67, v66, v64
	v_cmp_ge_f32_e64 s[0:1], 0, v68
	v_add_u32_e32 v68, 1, v66
	s_nop 0
	v_cndmask_b32_e64 v67, v66, v67, s[0:1]
	v_fma_f32 v66, -v68, v66, v64
	v_cmp_lt_f32_e64 s[0:1], 0, v66
	s_nop 1
	v_cndmask_b32_e64 v66, v67, v68, s[0:1]
	v_mul_f32_e32 v67, 0x37800000, v66
	v_cndmask_b32_e32 v66, v66, v67, vcc
	v_cmp_class_f32_e32 vcc, v64, v151
	s_nop 1
	v_cndmask_b32_e32 v64, v66, v64, vcc
	v_div_scale_f32 v66, s[0:1], v64, v64, 1.0
	v_rcp_f32_e32 v67, v66
	s_nop 0
	v_fma_f32 v68, -v66, v67, 1.0
	v_fmac_f32_e32 v67, v68, v67
	v_div_scale_f32 v68, vcc, 1.0, v64, 1.0
	v_mul_f32_e32 v69, v68, v67
	v_fma_f32 v70, -v66, v69, v68
	v_fmac_f32_e32 v69, v70, v67
	v_fma_f32 v66, -v66, v69, v68
	v_div_fmas_f32 v66, v66, v67, v69
	v_div_fixup_f32 v64, v66, v64, 1.0
	v_pk_mul_f32 v[60:61], v[60:61], v[64:65] op_sel_hi:[1,0]
	v_pk_mul_f32 v[66:67], v[58:59], v[64:65] op_sel_hi:[1,0]
	v_pk_mul_f32 v[58:59], v[56:57], v[64:65] op_sel_hi:[1,0]
	v_cvt_pk_bf16_f32 v56, v60, v61
	v_mad_i64_i32 v[60:61], s[0:1], v65, s10, v[120:121]
	v_pk_mul_f32 v[62:63], v[62:63], v[64:65] op_sel_hi:[1,0]
	v_lshl_add_u64 v[60:61], v[60:61], 0, v[122:123]
	v_cvt_pk_bf16_f32 v57, v62, v63
	v_cvt_pk_bf16_f32 v58, v58, v59
	v_cvt_pk_bf16_f32 v59, v66, v67
	global_store_dwordx4 v[60:61], v[56:59], off
	v_pk_mul_f32 v[54:55], v[54:55], v[64:65] op_sel_hi:[1,0]
	v_pk_mul_f32 v[52:53], v[52:53], v[64:65] op_sel_hi:[1,0]
	v_pk_mul_f32 v[56:57], v[50:51], v[64:65] op_sel_hi:[1,0]
	v_pk_mul_f32 v[50:51], v[48:49], v[64:65] op_sel_hi:[1,0]
	v_cvt_pk_bf16_f32 v48, v52, v53
	v_cvt_pk_bf16_f32 v49, v54, v55
	s_nop 0
	v_cvt_pk_bf16_f32 v50, v50, v51
	v_cvt_pk_bf16_f32 v51, v56, v57
; #define PG8_BAR __builtin_amdgcn_s_barrier()
; __device__ __forceinline__ u32x4 pack8(f32x4 a, f32x4 b) { u32x4 o; o.x = cvt_pk(a.x, a.y); o.y = cvt_pk(a.z, a.w); o.z = cvt_pk(b.x, b.y); o.w = cvt_pk(b.z, b.w); return o; }
; template <class Epi, class Sched, bool ALIGN_EPI = false, bool SP2 = false, bool ABLK = false>
; __device__ __forceinline__ void gemm_phase(PG8_LAS unsigned char* lds, const Gemm g, const Sched& S, const Epi& E) {
;     ...
;         if (!has_next) break;
; #pragma unroll
;         for (int a = 0; a < 2; ++a)
; #pragma unroll
;             for (int b = 0; b < 2; ++b)
; #pragma unroll
;                 for (int m = 0; m < 4; ++m)
; #pragma unroll
;                     for (int n = 0; n < 2; ++n) acc[a][b][m][n] = (f32x4){0.f, 0.f, 0.f, 0.f};
;         cur = nxt; cA = nA; cB = nB; ++ui;
;         if constexpr (ALIGN_EPI) { if (wr == 1) PG8_BAR; }
; __device__ __forceinline__ float rstd_of(const float* SS, int row, float invw) { return 1.0f / sqrtf(SS[row] * invw + EPS); }
;     __device__ __forceinline__ void operator()(const f32x4 (&acc)[2][2][4][2], const pg8::Unit& u, int wr, int wc, int fr, int fq) const {
;     ...
; #pragma unroll
;         for (int ai = 0; ai < 2; ++ai)
; #pragma unroll
;             for (int m = 0; m < 4; ++m) {
;                 const int row = row0 + ai * 128 + m * 16; const float r = rstd_of(SS, row, invw);
; #pragma unroll
;                 for (int bj = 0; bj < 2; ++bj)
;                     *(u32x4*)(O + (size_t)row * ldc + col0 + bj * 128) = pack8(acc[ai][bj][m][0] * r, acc[ai][bj][m][1] * r);
;             }
	global_store_dwordx4 v[60:61], v[48:51], off offset:256
	s_nop 1
	s_nop 0
	v_add_u32_e32 v49, 0x90, v140
	v_mov_b32_e32 v48, v205
	v_fmamk_f32 v48, v48, 0x3b800000, v150
	v_cmp_gt_f32_e32 vcc, s9, v48
	v_mul_f32_e32 v50, 0x4f800000, v48
	s_nop 0
	v_cndmask_b32_e32 v48, v48, v50, vcc
	v_sqrt_f32_e32 v50, v48
	s_nop 0
	v_add_u32_e32 v51, -1, v50
	v_fma_f32 v52, -v51, v50, v48
	v_cmp_ge_f32_e64 s[0:1], 0, v52
	v_add_u32_e32 v52, 1, v50
	s_nop 0
	v_cndmask_b32_e64 v51, v50, v51, s[0:1]
	v_fma_f32 v50, -v52, v50, v48
	v_cmp_lt_f32_e64 s[0:1], 0, v50
	s_nop 1
	v_cndmask_b32_e64 v50, v51, v52, s[0:1]
	v_mul_f32_e32 v51, 0x37800000, v50
	v_cndmask_b32_e32 v50, v50, v51, vcc
	v_cmp_class_f32_e32 vcc, v48, v151
	s_nop 1
	v_cndmask_b32_e32 v48, v50, v48, vcc
	v_div_scale_f32 v50, s[0:1], v48, v48, 1.0
	v_rcp_f32_e32 v51, v50
	s_nop 0
	v_fma_f32 v52, -v50, v51, 1.0
	v_fmac_f32_e32 v51, v52, v51
	v_div_scale_f32 v52, vcc, 1.0, v48, 1.0
	v_mul_f32_e32 v53, v52, v51
	v_fma_f32 v54, -v50, v53, v52
	v_fmac_f32_e32 v53, v54, v51
	v_fma_f32 v50, -v50, v53, v52
	v_div_fmas_f32 v50, v50, v51, v53
	v_div_fixup_f32 v48, v50, v48, 1.0
	v_pk_mul_f32 v[44:45], v[44:45], v[48:49] op_sel_hi:[1,0]
	v_pk_mul_f32 v[50:51], v[42:43], v[48:49] op_sel_hi:[1,0]
	v_pk_mul_f32 v[42:43], v[40:41], v[48:49] op_sel_hi:[1,0]
	v_cvt_pk_bf16_f32 v40, v44, v45
	v_mad_i64_i32 v[44:45], s[0:1], v49, s10, v[120:121]
	v_pk_mul_f32 v[46:47], v[46:47], v[48:49] op_sel_hi:[1,0]
	v_lshl_add_u64 v[44:45], v[44:45], 0, v[122:123]
	v_cvt_pk_bf16_f32 v41, v46, v47
	v_cvt_pk_bf16_f32 v42, v42, v43
	v_cvt_pk_bf16_f32 v43, v50, v51
	global_store_dwordx4 v[44:45], v[40:43], off
	v_pk_mul_f32 v[38:39], v[38:39], v[48:49] op_sel_hi:[1,0]
	v_pk_mul_f32 v[36:37], v[36:37], v[48:49] op_sel_hi:[1,0]
	v_pk_mul_f32 v[40:41], v[34:35], v[48:49] op_sel_hi:[1,0]
	v_pk_mul_f32 v[34:35], v[32:33], v[48:49] op_sel_hi:[1,0]
	v_cvt_pk_bf16_f32 v32, v36, v37
	v_cvt_pk_bf16_f32 v33, v38, v39
	s_nop 0
	v_cvt_pk_bf16_f32 v34, v34, v35
	v_cvt_pk_bf16_f32 v35, v40, v41
	global_store_dwordx4 v[44:45], v[32:35], off offset:256
	s_nop 1
	s_nop 0
	v_add_u32_e32 v33, 0xa0, v140
	v_mov_b32_e32 v32, v206
	v_fmamk_f32 v32, v32, 0x3b800000, v150
	v_cmp_gt_f32_e32 vcc, s9, v32
	v_mul_f32_e32 v34, 0x4f800000, v32
	s_nop 0
	v_cndmask_b32_e32 v32, v32, v34, vcc
	v_sqrt_f32_e32 v34, v32
	s_nop 0
	v_add_u32_e32 v35, -1, v34
	v_fma_f32 v36, -v35, v34, v32
	v_cmp_ge_f32_e64 s[0:1], 0, v36
	v_add_u32_e32 v36, 1, v34
	s_nop 0
	v_cndmask_b32_e64 v35, v34, v35, s[0:1]
	v_fma_f32 v34, -v36, v34, v32
	v_cmp_lt_f32_e64 s[0:1], 0, v34
	s_nop 1
	v_cndmask_b32_e64 v34, v35, v36, s[0:1]
	v_mul_f32_e32 v35, 0x37800000, v34
	v_cndmask_b32_e32 v34, v34, v35, vcc
	v_cmp_class_f32_e32 vcc, v32, v151
	s_nop 1
	v_cndmask_b32_e32 v32, v34, v32, vcc
	v_div_scale_f32 v34, s[0:1], v32, v32, 1.0
	v_rcp_f32_e32 v35, v34
	s_nop 0
	v_fma_f32 v36, -v34, v35, 1.0
	v_fmac_f32_e32 v35, v36, v35
	v_div_scale_f32 v36, vcc, 1.0, v32, 1.0
	v_mul_f32_e32 v37, v36, v35
	v_fma_f32 v38, -v34, v37, v36
	v_fmac_f32_e32 v37, v38, v35
	v_fma_f32 v34, -v34, v37, v36
	v_div_fmas_f32 v34, v34, v35, v37
	v_div_fixup_f32 v32, v34, v32, 1.0
	v_pk_mul_f32 v[28:29], v[28:29], v[32:33] op_sel_hi:[1,0]
	v_pk_mul_f32 v[34:35], v[26:27], v[32:33] op_sel_hi:[1,0]
	v_pk_mul_f32 v[26:27], v[24:25], v[32:33] op_sel_hi:[1,0]
	v_cvt_pk_bf16_f32 v24, v28, v29
	v_mad_i64_i32 v[28:29], s[0:1], v33, s10, v[120:121]
	v_pk_mul_f32 v[30:31], v[30:31], v[32:33] op_sel_hi:[1,0]
	v_lshl_add_u64 v[28:29], v[28:29], 0, v[122:123]
	v_cvt_pk_bf16_f32 v25, v30, v31
	v_cvt_pk_bf16_f32 v26, v26, v27
	v_cvt_pk_bf16_f32 v27, v34, v35
	global_store_dwordx4 v[28:29], v[24:27], off
	v_pk_mul_f32 v[22:23], v[22:23], v[32:33] op_sel_hi:[1,0]
	v_pk_mul_f32 v[20:21], v[20:21], v[32:33] op_sel_hi:[1,0]
	v_pk_mul_f32 v[24:25], v[18:19], v[32:33] op_sel_hi:[1,0]
	v_pk_mul_f32 v[18:19], v[16:17], v[32:33] op_sel_hi:[1,0]
	v_cvt_pk_bf16_f32 v16, v20, v21
	v_cvt_pk_bf16_f32 v17, v22, v23
	s_nop 0
	v_cvt_pk_bf16_f32 v18, v18, v19
	v_cvt_pk_bf16_f32 v19, v24, v25
	global_store_dwordx4 v[28:29], v[16:19], off offset:256
	s_nop 1
	s_nop 0
	v_add_u32_e32 v17, 0xb0, v140
	v_mov_b32_e32 v16, v207
	v_fmamk_f32 v16, v16, 0x3b800000, v150
	v_cmp_gt_f32_e32 vcc, s9, v16
	v_mul_f32_e32 v18, 0x4f800000, v16
	s_nop 0
	v_cndmask_b32_e32 v16, v16, v18, vcc
	v_sqrt_f32_e32 v18, v16
	s_nop 0
	v_add_u32_e32 v19, -1, v18
	v_fma_f32 v20, -v19, v18, v16
	v_cmp_ge_f32_e64 s[0:1], 0, v20
	v_add_u32_e32 v20, 1, v18
	s_nop 0
	v_cndmask_b32_e64 v19, v18, v19, s[0:1]
	v_fma_f32 v18, -v20, v18, v16
	v_cmp_lt_f32_e64 s[0:1], 0, v18
	s_nop 1
	v_cndmask_b32_e64 v18, v19, v20, s[0:1]
	v_mul_f32_e32 v19, 0x37800000, v18
	v_cndmask_b32_e32 v18, v18, v19, vcc
	v_cmp_class_f32_e32 vcc, v16, v151
	s_nop 1
	v_cndmask_b32_e32 v16, v18, v16, vcc
	v_div_scale_f32 v18, s[0:1], v16, v16, 1.0
	v_rcp_f32_e32 v19, v18
	s_nop 0
	v_fma_f32 v20, -v18, v19, 1.0
	v_fmac_f32_e32 v19, v20, v19
	v_div_scale_f32 v20, vcc, 1.0, v16, 1.0
	v_mul_f32_e32 v21, v20, v19
	v_fma_f32 v22, -v18, v21, v20
	v_fmac_f32_e32 v21, v22, v19
	v_fma_f32 v18, -v18, v21, v20
	v_div_fmas_f32 v18, v18, v19, v21
	v_div_fixup_f32 v16, v18, v16, 1.0
	v_pk_mul_f32 v[12:13], v[12:13], v[16:17] op_sel_hi:[1,0]
	v_pk_mul_f32 v[18:19], v[10:11], v[16:17] op_sel_hi:[1,0]
	v_pk_mul_f32 v[10:11], v[8:9], v[16:17] op_sel_hi:[1,0]
	v_cvt_pk_bf16_f32 v8, v12, v13
	v_mad_i64_i32 v[12:13], s[0:1], v17, s10, v[120:121]
	v_pk_mul_f32 v[14:15], v[14:15], v[16:17] op_sel_hi:[1,0]
	v_lshl_add_u64 v[12:13], v[12:13], 0, v[122:123]
	v_cvt_pk_bf16_f32 v9, v14, v15
	v_cvt_pk_bf16_f32 v10, v10, v11
	v_cvt_pk_bf16_f32 v11, v18, v19
	global_store_dwordx4 v[12:13], v[8:11], off
	s_mov_b64 s[0:1], -1
	s_andn2_b64 vcc, exec, s[38:39]
	v_pk_mul_f32 v[8:9], v[2:3], v[16:17] op_sel_hi:[1,0]
	v_pk_mul_f32 v[2:3], v[0:1], v[16:17] op_sel_hi:[1,0]
	v_pk_mul_f32 v[6:7], v[6:7], v[16:17] op_sel_hi:[1,0]
	v_pk_mul_f32 v[4:5], v[4:5], v[16:17] op_sel_hi:[1,0]
	s_nop 0
	v_cvt_pk_bf16_f32 v0, v4, v5
	v_cvt_pk_bf16_f32 v1, v6, v7
	v_cvt_pk_bf16_f32 v2, v2, v3
	v_cvt_pk_bf16_f32 v3, v8, v9
	global_store_dwordx4 v[12:13], v[0:3], off offset:256
	s_cbranch_vccnz .LBB0_468
	s_andn2_b64 vcc, exec, s[30:31]
	s_cbranch_vccnz .LBB0_467
	s_barrier
	s_branch .LBB0_467

; __device__ __forceinline__ u32x4 pack8(f32x4 a, f32x4 b) { u32x4 o; o.x = cvt_pk(a.x, a.y); o.y = cvt_pk(a.z, a.w); o.z = cvt_pk(b.x, b.y); o.w = cvt_pk(b.z, b.w); return o; }
; __device__ __forceinline__ float rstd_of(const float* SS, int row, float invw) { return 1.0f / sqrtf(SS[row] * invw + EPS); }
;     __device__ __forceinline__ void operator()(const f32x4 (&acc)[2][2][4][2], const pg8::Unit& u, int wr, int wc, int fr, int fq) const {
;     ...
; #pragma unroll
;         for (int ai = 0; ai < 2; ++ai)
; #pragma unroll
;             for (int m = 0; m < 4; ++m) {
;                 const int row = row0 + ai * 128 + m * 16; const float r = rstd_of(SS, row, invw);
; #pragma unroll
;                 for (int bj = 0; bj < 2; ++bj)
;                     *(u32x4*)(O + (size_t)row * ldc + col0 + bj * 128) = pack8(acc[ai][bj][m][0] * r, acc[ai][bj][m][1] * r);
;             }
.LBB0_493:
	v_lshl_add_u32 v142, s0, 8, v144
	v_ashrrev_i32_e32 v143, 31, v142
	v_lshl_add_u64 v[140:141], v[142:143], 2, s[44:45]
	global_load_dword v200, v[140:141], off
	global_load_dword v201, v[140:141], off offset:64
	global_load_dword v202, v[140:141], off offset:128
	global_load_dword v203, v[140:141], off offset:192
	global_load_dword v204, v[140:141], off offset:512
	global_load_dword v205, v[140:141], off offset:576
	global_load_dword v206, v[140:141], off offset:640
	global_load_dword v207, v[140:141], off offset:704
	v_lshl_or_b32 v152, s1, 8, v146
	v_ashrrev_i32_e32 v153, 31, v152
	s_waitcnt vmcnt(0)
	v_mov_b32_e32 v154, v200
	v_fmamk_f32 v154, v154, 0x3c000000, v150
	v_cmp_gt_f32_e32 vcc, s6, v154
	v_mul_f32_e32 v155, 0x4f800000, v154
	s_nop 0
	v_cndmask_b32_e32 v154, v154, v155, vcc
	v_sqrt_f32_e32 v155, v154
	s_nop 0
	v_add_u32_e32 v156, -1, v155
	v_fma_f32 v157, -v156, v155, v154
	v_cmp_ge_f32_e64 s[0:1], 0, v157
	v_add_u32_e32 v157, 1, v155
	s_nop 0
	v_cndmask_b32_e64 v156, v155, v156, s[0:1]
	v_fma_f32 v155, -v157, v155, v154
	v_cmp_lt_f32_e64 s[0:1], 0, v155
	s_nop 1
	v_cndmask_b32_e64 v155, v156, v157, s[0:1]
	v_mul_f32_e32 v156, 0x37800000, v155
	v_cndmask_b32_e32 v155, v155, v156, vcc
	v_cmp_class_f32_e32 vcc, v154, v151
	s_nop 1
	v_cndmask_b32_e32 v154, v155, v154, vcc
	v_div_scale_f32 v155, s[0:1], v154, v154, 1.0
	v_rcp_f32_e32 v156, v155
	s_nop 0
	v_fma_f32 v157, -v155, v156, 1.0
	v_fmac_f32_e32 v156, v157, v156
	v_div_scale_f32 v157, vcc, 1.0, v154, 1.0
	v_mul_f32_e32 v158, v157, v156
	v_fma_f32 v159, -v155, v158, v157
	v_fmac_f32_e32 v158, v159, v156
	v_fma_f32 v155, -v155, v158, v157
	v_div_fmas_f32 v155, v155, v156, v158
	v_div_fixup_f32 v154, v155, v154, 1.0
	v_pk_mul_f32 v[112:113], v[112:113], v[154:155] op_sel_hi:[1,0]
	v_pk_mul_f32 v[114:115], v[114:115], v[154:155] op_sel_hi:[1,0]
	v_pk_mul_f32 v[156:157], v[118:119], v[154:155] op_sel_hi:[1,0]
	v_pk_mul_f32 v[118:119], v[116:117], v[154:155] op_sel_hi:[1,0]
	v_cvt_pk_bf16_f32 v116, v112, v113
	v_lshlrev_b64 v[112:113], 11, v[142:143]
	v_cvt_pk_bf16_f32 v117, v114, v115
	v_lshl_add_u64 v[112:113], s[12:13], 0, v[112:113]
	v_lshlrev_b64 v[114:115], 1, v[152:153]
	v_lshl_add_u64 v[112:113], v[112:113], 0, v[114:115]
	v_cvt_pk_bf16_f32 v118, v118, v119
	v_cvt_pk_bf16_f32 v119, v156, v157
	global_store_dwordx4 v[112:113], v[116:119], off
	s_nop 1
	v_pk_mul_f32 v[116:117], v[120:121], v[154:155] op_sel_hi:[1,0]
	v_pk_mul_f32 v[118:119], v[122:123], v[154:155] op_sel_hi:[1,0]
	v_cvt_pk_bf16_f32 v116, v116, v117
	v_pk_mul_f32 v[120:121], v[126:127], v[154:155] op_sel_hi:[1,0]
	v_pk_mul_f32 v[122:123], v[124:125], v[154:155] op_sel_hi:[1,0]
	v_cvt_pk_bf16_f32 v117, v118, v119
	s_nop 0
	v_cvt_pk_bf16_f32 v118, v122, v123
	v_cvt_pk_bf16_f32 v119, v120, v121
	global_store_dwordx4 v[112:113], v[116:119], off offset:256
	s_nop 1
	v_or_b32_e32 v116, 16, v142
	v_ashrrev_i32_e32 v117, 31, v116
	v_lshl_add_u64 v[118:119], v[116:117], 2, s[44:45]
	s_nop 1
	v_mov_b32_e32 v118, v201
	v_fmamk_f32 v118, v118, 0x3c000000, v150
	v_cmp_gt_f32_e32 vcc, s6, v118
	v_mul_f32_e32 v119, 0x4f800000, v118
	s_nop 0
	v_cndmask_b32_e32 v118, v118, v119, vcc
	v_sqrt_f32_e32 v119, v118
	s_nop 0
	v_add_u32_e32 v120, -1, v119
	v_fma_f32 v121, -v120, v119, v118
	v_cmp_ge_f32_e64 s[0:1], 0, v121
	v_add_u32_e32 v121, 1, v119
	s_nop 0
	v_cndmask_b32_e64 v120, v119, v120, s[0:1]
	v_fma_f32 v119, -v121, v119, v118
	v_cmp_lt_f32_e64 s[0:1], 0, v119
	s_nop 1
	v_cndmask_b32_e64 v119, v120, v121, s[0:1]
	v_mul_f32_e32 v120, 0x37800000, v119
	v_cndmask_b32_e32 v119, v119, v120, vcc
	v_cmp_class_f32_e32 vcc, v118, v151
	s_nop 1
	v_cndmask_b32_e32 v118, v119, v118, vcc
	v_div_scale_f32 v119, s[0:1], v118, v118, 1.0
	v_rcp_f32_e32 v120, v119
	s_nop 0
	v_fma_f32 v121, -v119, v120, 1.0
	v_fmac_f32_e32 v120, v121, v120
	v_div_scale_f32 v121, vcc, 1.0, v118, 1.0
	v_mul_f32_e32 v122, v121, v120
	v_fma_f32 v123, -v119, v122, v121
	v_fmac_f32_e32 v122, v123, v120
	v_fma_f32 v119, -v119, v122, v121
	v_div_fmas_f32 v119, v119, v120, v122
	v_div_fixup_f32 v118, v119, v118, 1.0
	v_pk_mul_f32 v[98:99], v[98:99], v[118:119] op_sel_hi:[1,0]
	v_pk_mul_f32 v[96:97], v[96:97], v[118:119] op_sel_hi:[1,0]
	v_pk_mul_f32 v[100:101], v[100:101], v[118:119] op_sel_hi:[1,0]
	v_cvt_pk_bf16_f32 v96, v96, v97
	v_cvt_pk_bf16_f32 v97, v98, v99
	v_pk_mul_f32 v[102:103], v[102:103], v[118:119] op_sel_hi:[1,0]
	v_cvt_pk_bf16_f32 v98, v100, v101
	v_lshlrev_b64 v[100:101], 11, v[116:117]
	v_lshl_add_u64 v[100:101], s[12:13], 0, v[100:101]
	v_lshl_add_u64 v[100:101], v[100:101], 0, v[114:115]
	v_cvt_pk_bf16_f32 v99, v102, v103
	global_store_dwordx4 v[100:101], v[96:99], off
	v_pk_mul_f32 v[102:103], v[110:111], v[118:119] op_sel_hi:[1,0]
	s_nop 0
	v_pk_mul_f32 v[96:97], v[104:105], v[118:119] op_sel_hi:[1,0]
	v_pk_mul_f32 v[98:99], v[106:107], v[118:119] op_sel_hi:[1,0]
	v_cvt_pk_bf16_f32 v96, v96, v97
	v_pk_mul_f32 v[104:105], v[108:109], v[118:119] op_sel_hi:[1,0]
	v_cvt_pk_bf16_f32 v97, v98, v99
	s_nop 0
	v_cvt_pk_bf16_f32 v98, v104, v105
	v_cvt_pk_bf16_f32 v99, v102, v103
	global_store_dwordx4 v[100:101], v[96:99], off offset:256
	s_nop 1
	v_or_b32_e32 v96, 32, v142
	v_ashrrev_i32_e32 v97, 31, v96
	v_lshl_add_u64 v[98:99], v[96:97], 2, s[44:45]
	s_nop 1
	v_mov_b32_e32 v98, v202
	v_fmamk_f32 v98, v98, 0x3c000000, v150
	v_cmp_gt_f32_e32 vcc, s6, v98
	v_mul_f32_e32 v99, 0x4f800000, v98
	s_nop 0
	v_cndmask_b32_e32 v98, v98, v99, vcc
	v_sqrt_f32_e32 v99, v98
	s_nop 0
	v_add_u32_e32 v100, -1, v99
	v_fma_f32 v101, -v100, v99, v98
	v_cmp_ge_f32_e64 s[0:1], 0, v101
	v_add_u32_e32 v101, 1, v99
	s_nop 0
	v_cndmask_b32_e64 v100, v99, v100, s[0:1]
; __device__ __forceinline__ u32x4 pack8(f32x4 a, f32x4 b) { u32x4 o; o.x = cvt_pk(a.x, a.y); o.y = cvt_pk(a.z, a.w); o.z = cvt_pk(b.x, b.y); o.w = cvt_pk(b.z, b.w); return o; }
; __device__ __forceinline__ float rstd_of(const float* SS, int row, float invw) { return 1.0f / sqrtf(SS[row] * invw + EPS); }
;     __device__ __forceinline__ void operator()(const f32x4 (&acc)[2][2][4][2], const pg8::Unit& u, int wr, int wc, int fr, int fq) const {
;     ...
; #pragma unroll
;         for (int ai = 0; ai < 2; ++ai)
; #pragma unroll
;             for (int m = 0; m < 4; ++m) {
;                 const int row = row0 + ai * 128 + m * 16; const float r = rstd_of(SS, row, invw);
; #pragma unroll
;                 for (int bj = 0; bj < 2; ++bj)
;                     *(u32x4*)(O + (size_t)row * ldc + col0 + bj * 128) = pack8(acc[ai][bj][m][0] * r, acc[ai][bj][m][1] * r);
;             }
	v_fma_f32 v99, -v101, v99, v98
	v_cmp_lt_f32_e64 s[0:1], 0, v99
	s_nop 1
	v_cndmask_b32_e64 v99, v100, v101, s[0:1]
	v_mul_f32_e32 v100, 0x37800000, v99
	v_cndmask_b32_e32 v99, v99, v100, vcc
	v_cmp_class_f32_e32 vcc, v98, v151
	s_nop 1
	v_cndmask_b32_e32 v98, v99, v98, vcc
	v_div_scale_f32 v99, s[0:1], v98, v98, 1.0
	v_rcp_f32_e32 v100, v99
	s_nop 0
	v_fma_f32 v101, -v99, v100, 1.0
	v_fmac_f32_e32 v100, v101, v100
	v_div_scale_f32 v101, vcc, 1.0, v98, 1.0
	v_mul_f32_e32 v102, v101, v100
	v_fma_f32 v103, -v99, v102, v101
	v_fmac_f32_e32 v102, v103, v100
	v_fma_f32 v99, -v99, v102, v101
	v_div_fmas_f32 v99, v99, v100, v102
	v_div_fixup_f32 v98, v99, v98, 1.0
	v_pk_mul_f32 v[82:83], v[82:83], v[98:99] op_sel_hi:[1,0]
	v_pk_mul_f32 v[80:81], v[80:81], v[98:99] op_sel_hi:[1,0]
	v_pk_mul_f32 v[84:85], v[84:85], v[98:99] op_sel_hi:[1,0]
	v_cvt_pk_bf16_f32 v80, v80, v81
	v_cvt_pk_bf16_f32 v81, v82, v83
	v_pk_mul_f32 v[86:87], v[86:87], v[98:99] op_sel_hi:[1,0]
	v_cvt_pk_bf16_f32 v82, v84, v85
	v_lshlrev_b64 v[84:85], 11, v[96:97]
	v_lshl_add_u64 v[84:85], s[12:13], 0, v[84:85]
	v_lshl_add_u64 v[84:85], v[84:85], 0, v[114:115]
	v_cvt_pk_bf16_f32 v83, v86, v87
	global_store_dwordx4 v[84:85], v[80:83], off
	v_pk_mul_f32 v[86:87], v[94:95], v[98:99] op_sel_hi:[1,0]
	s_nop 0
	v_pk_mul_f32 v[80:81], v[88:89], v[98:99] op_sel_hi:[1,0]
	v_pk_mul_f32 v[82:83], v[90:91], v[98:99] op_sel_hi:[1,0]
	v_cvt_pk_bf16_f32 v80, v80, v81
	v_pk_mul_f32 v[88:89], v[92:93], v[98:99] op_sel_hi:[1,0]
	v_cvt_pk_bf16_f32 v81, v82, v83
	s_nop 0
	v_cvt_pk_bf16_f32 v82, v88, v89
	v_cvt_pk_bf16_f32 v83, v86, v87
	global_store_dwordx4 v[84:85], v[80:83], off offset:256
	s_nop 1
	v_or_b32_e32 v80, 48, v142
	v_ashrrev_i32_e32 v81, 31, v80
	v_lshl_add_u64 v[82:83], v[80:81], 2, s[44:45]
	s_nop 1
	v_mov_b32_e32 v82, v203
	v_fmamk_f32 v82, v82, 0x3c000000, v150
	v_cmp_gt_f32_e32 vcc, s6, v82
	v_mul_f32_e32 v83, 0x4f800000, v82
	s_nop 0
	v_cndmask_b32_e32 v82, v82, v83, vcc
	v_sqrt_f32_e32 v83, v82
	s_nop 0
	v_add_u32_e32 v84, -1, v83
	v_fma_f32 v85, -v84, v83, v82
	v_cmp_ge_f32_e64 s[0:1], 0, v85
	v_add_u32_e32 v85, 1, v83
	s_nop 0
	v_cndmask_b32_e64 v84, v83, v84, s[0:1]
	v_fma_f32 v83, -v85, v83, v82
	v_cmp_lt_f32_e64 s[0:1], 0, v83
	s_nop 1
	v_cndmask_b32_e64 v83, v84, v85, s[0:1]
	v_mul_f32_e32 v84, 0x37800000, v83
	v_cndmask_b32_e32 v83, v83, v84, vcc
	v_cmp_class_f32_e32 vcc, v82, v151
	s_nop 1
	v_cndmask_b32_e32 v82, v83, v82, vcc
	v_div_scale_f32 v83, s[0:1], v82, v82, 1.0
	v_rcp_f32_e32 v84, v83
	s_nop 0
	v_fma_f32 v85, -v83, v84, 1.0
	v_fmac_f32_e32 v84, v85, v84
	v_div_scale_f32 v85, vcc, 1.0, v82, 1.0
	v_mul_f32_e32 v86, v85, v84
	v_fma_f32 v87, -v83, v86, v85
	v_fmac_f32_e32 v86, v87, v84
	v_fma_f32 v83, -v83, v86, v85
	v_div_fmas_f32 v83, v83, v84, v86
	v_div_fixup_f32 v82, v83, v82, 1.0
	v_pk_mul_f32 v[74:75], v[74:75], v[82:83] op_sel_hi:[1,0]
	v_pk_mul_f32 v[72:73], v[72:73], v[82:83] op_sel_hi:[1,0]
	v_pk_mul_f32 v[76:77], v[76:77], v[82:83] op_sel_hi:[1,0]
	v_cvt_pk_bf16_f32 v72, v72, v73
	v_cvt_pk_bf16_f32 v73, v74, v75
	v_pk_mul_f32 v[78:79], v[78:79], v[82:83] op_sel_hi:[1,0]
	v_cvt_pk_bf16_f32 v74, v76, v77
	v_lshlrev_b64 v[76:77], 11, v[80:81]
	v_lshl_add_u64 v[76:77], s[12:13], 0, v[76:77]
	v_lshl_add_u64 v[76:77], v[76:77], 0, v[114:115]
	v_cvt_pk_bf16_f32 v75, v78, v79
	global_store_dwordx4 v[76:77], v[72:75], off
	v_pk_mul_f32 v[70:71], v[70:71], v[82:83] op_sel_hi:[1,0]
	v_pk_mul_f32 v[68:69], v[68:69], v[82:83] op_sel_hi:[1,0]
	v_pk_mul_f32 v[72:73], v[66:67], v[82:83] op_sel_hi:[1,0]
	v_pk_mul_f32 v[66:67], v[64:65], v[82:83] op_sel_hi:[1,0]
	v_cvt_pk_bf16_f32 v64, v68, v69
	v_cvt_pk_bf16_f32 v65, v70, v71
	s_nop 0
	v_cvt_pk_bf16_f32 v66, v66, v67
	v_cvt_pk_bf16_f32 v67, v72, v73
	global_store_dwordx4 v[76:77], v[64:67], off offset:256
	s_nop 1
	v_mov_b32_e32 v64, v204
	v_fmamk_f32 v64, v64, 0x3c000000, v150
	v_cmp_gt_f32_e32 vcc, s6, v64
	v_mul_f32_e32 v65, 0x4f800000, v64
	s_nop 0
	v_cndmask_b32_e32 v64, v64, v65, vcc
	v_sqrt_f32_e32 v65, v64
	s_nop 0
	v_add_u32_e32 v66, -1, v65
	v_fma_f32 v67, -v66, v65, v64
	v_cmp_ge_f32_e64 s[0:1], 0, v67
	v_add_u32_e32 v67, 1, v65
	s_nop 0
	v_cndmask_b32_e64 v66, v65, v66, s[0:1]
	v_fma_f32 v65, -v67, v65, v64
	v_cmp_lt_f32_e64 s[0:1], 0, v65
	s_nop 1
	v_cndmask_b32_e64 v65, v66, v67, s[0:1]
	v_mul_f32_e32 v66, 0x37800000, v65
	v_cndmask_b32_e32 v65, v65, v66, vcc
	v_cmp_class_f32_e32 vcc, v64, v151
	s_nop 1
	v_cndmask_b32_e32 v64, v65, v64, vcc
	v_div_scale_f32 v65, s[0:1], v64, v64, 1.0
	v_rcp_f32_e32 v66, v65
	s_mov_b64 s[0:1], 0x40000
	v_fma_f32 v67, -v65, v66, 1.0
	v_fmac_f32_e32 v66, v67, v66
	v_div_scale_f32 v67, vcc, 1.0, v64, 1.0
	v_mul_f32_e32 v68, v67, v66
	v_fma_f32 v69, -v65, v68, v67
	v_fmac_f32_e32 v68, v69, v66
	v_fma_f32 v65, -v65, v68, v67
	v_div_fmas_f32 v65, v65, v66, v68
	v_div_fixup_f32 v64, v65, v64, 1.0
	v_pk_mul_f32 v[56:57], v[56:57], v[64:65] op_sel_hi:[1,0]
	v_pk_mul_f32 v[66:67], v[58:59], v[64:65] op_sel_hi:[1,0]
	v_pk_mul_f32 v[62:63], v[62:63], v[64:65] op_sel_hi:[1,0]
	v_pk_mul_f32 v[60:61], v[60:61], v[64:65] op_sel_hi:[1,0]
	v_cvt_pk_bf16_f32 v58, v56, v57
	v_lshl_add_u64 v[56:57], v[112:113], 0, s[0:1]
	s_mov_b32 s0, 0x40000
	v_cvt_pk_bf16_f32 v59, v66, v67
	v_cvt_pk_bf16_f32 v60, v60, v61
	v_cvt_pk_bf16_f32 v61, v62, v63
	v_add_co_u32_e32 v62, vcc, s0, v112
	v_pk_mul_f32 v[54:55], v[54:55], v[64:65] op_sel_hi:[1,0]
	s_nop 0
	v_addc_co_u32_e32 v63, vcc, 0, v113, vcc
	global_store_dwordx4 v[62:63], v[58:61], off
	v_pk_mul_f32 v[52:53], v[52:53], v[64:65] op_sel_hi:[1,0]
	s_nop 0
	v_pk_mul_f32 v[58:59], v[50:51], v[64:65] op_sel_hi:[1,0]
	v_pk_mul_f32 v[50:51], v[48:49], v[64:65] op_sel_hi:[1,0]
; #define PG8_BAR __builtin_amdgcn_s_barrier()
; __device__ __forceinline__ u32x4 pack8(f32x4 a, f32x4 b) { u32x4 o; o.x = cvt_pk(a.x, a.y); o.y = cvt_pk(a.z, a.w); o.z = cvt_pk(b.x, b.y); o.w = cvt_pk(b.z, b.w); return o; }
; template <class Epi, class Sched, bool ALIGN_EPI = false, bool SP2 = false, bool ABLK = false>
; __device__ __forceinline__ void gemm_phase(PG8_LAS unsigned char* lds, const Gemm g, const Sched& S, const Epi& E) {
;     ...
;         if (!has_next) break;
; #pragma unroll
;         for (int a = 0; a < 2; ++a)
; #pragma unroll
;             for (int b = 0; b < 2; ++b)
; #pragma unroll
;                 for (int m = 0; m < 4; ++m)
; #pragma unroll
;                     for (int n = 0; n < 2; ++n) acc[a][b][m][n] = (f32x4){0.f, 0.f, 0.f, 0.f};
;         cur = nxt; cA = nA; cB = nB; ++ui;
;         if constexpr (ALIGN_EPI) { if (wr == 1) PG8_BAR; }
; __device__ __forceinline__ float rstd_of(const float* SS, int row, float invw) { return 1.0f / sqrtf(SS[row] * invw + EPS); }
;     __device__ __forceinline__ void operator()(const f32x4 (&acc)[2][2][4][2], const pg8::Unit& u, int wr, int wc, int fr, int fq) const {
;     ...
; #pragma unroll
;         for (int ai = 0; ai < 2; ++ai)
; #pragma unroll
;             for (int m = 0; m < 4; ++m) {
;                 const int row = row0 + ai * 128 + m * 16; const float r = rstd_of(SS, row, invw);
; #pragma unroll
;                 for (int bj = 0; bj < 2; ++bj)
;                     *(u32x4*)(O + (size_t)row * ldc + col0 + bj * 128) = pack8(acc[ai][bj][m][0] * r, acc[ai][bj][m][1] * r);
;             }
	v_cvt_pk_bf16_f32 v48, v52, v53
	v_cvt_pk_bf16_f32 v49, v54, v55
	s_nop 0
	v_cvt_pk_bf16_f32 v50, v50, v51
	v_cvt_pk_bf16_f32 v51, v58, v59
	global_store_dwordx4 v[56:57], v[48:51], off offset:256
	s_nop 1
	v_mov_b32_e32 v48, v205
	v_fmamk_f32 v48, v48, 0x3c000000, v150
	v_cmp_gt_f32_e32 vcc, s6, v48
	v_mul_f32_e32 v49, 0x4f800000, v48
	s_nop 0
	v_cndmask_b32_e32 v48, v48, v49, vcc
	v_sqrt_f32_e32 v49, v48
	s_nop 0
	v_add_u32_e32 v50, -1, v49
	v_fma_f32 v51, -v50, v49, v48
	v_cmp_ge_f32_e64 s[0:1], 0, v51
	v_add_u32_e32 v51, 1, v49
	s_nop 0
	v_cndmask_b32_e64 v50, v49, v50, s[0:1]
	v_fma_f32 v49, -v51, v49, v48
	v_cmp_lt_f32_e64 s[0:1], 0, v49
	s_nop 1
	v_cndmask_b32_e64 v49, v50, v51, s[0:1]
	v_mul_f32_e32 v50, 0x37800000, v49
	v_cndmask_b32_e32 v49, v49, v50, vcc
	v_cmp_class_f32_e32 vcc, v48, v151
	s_nop 1
	v_cndmask_b32_e32 v48, v49, v48, vcc
	v_div_scale_f32 v49, s[0:1], v48, v48, 1.0
	v_rcp_f32_e32 v50, v49
	s_mov_b64 s[0:1], 0x48000
	v_fma_f32 v51, -v49, v50, 1.0
	v_fmac_f32_e32 v50, v51, v50
	v_div_scale_f32 v51, vcc, 1.0, v48, 1.0
	v_mul_f32_e32 v52, v51, v50
	v_fma_f32 v53, -v49, v52, v51
	v_fmac_f32_e32 v52, v53, v50
	v_fma_f32 v49, -v49, v52, v51
	v_div_fmas_f32 v49, v49, v50, v52
	v_div_fixup_f32 v48, v49, v48, 1.0
	v_pk_mul_f32 v[40:41], v[40:41], v[48:49] op_sel_hi:[1,0]
	v_pk_mul_f32 v[50:51], v[42:43], v[48:49] op_sel_hi:[1,0]
	v_pk_mul_f32 v[46:47], v[46:47], v[48:49] op_sel_hi:[1,0]
	v_pk_mul_f32 v[44:45], v[44:45], v[48:49] op_sel_hi:[1,0]
	v_cvt_pk_bf16_f32 v42, v40, v41
	v_lshl_add_u64 v[40:41], v[112:113], 0, s[0:1]
	s_mov_b32 s0, 0x48000
	v_cvt_pk_bf16_f32 v43, v50, v51
	v_cvt_pk_bf16_f32 v44, v44, v45
	v_cvt_pk_bf16_f32 v45, v46, v47
	v_add_co_u32_e32 v46, vcc, s0, v112
	v_pk_mul_f32 v[38:39], v[38:39], v[48:49] op_sel_hi:[1,0]
	s_nop 0
	v_addc_co_u32_e32 v47, vcc, 0, v113, vcc
	global_store_dwordx4 v[46:47], v[42:45], off
	v_pk_mul_f32 v[36:37], v[36:37], v[48:49] op_sel_hi:[1,0]
	s_nop 0
	v_pk_mul_f32 v[42:43], v[34:35], v[48:49] op_sel_hi:[1,0]
	v_pk_mul_f32 v[34:35], v[32:33], v[48:49] op_sel_hi:[1,0]
	v_cvt_pk_bf16_f32 v32, v36, v37
	v_cvt_pk_bf16_f32 v33, v38, v39
	s_nop 0
	v_cvt_pk_bf16_f32 v34, v34, v35
	v_cvt_pk_bf16_f32 v35, v42, v43
	global_store_dwordx4 v[40:41], v[32:35], off offset:256
	s_nop 1
	v_mov_b32_e32 v32, v206
	v_fmamk_f32 v32, v32, 0x3c000000, v150
	v_cmp_gt_f32_e32 vcc, s6, v32
	v_mul_f32_e32 v33, 0x4f800000, v32
	s_nop 0
	v_cndmask_b32_e32 v32, v32, v33, vcc
	v_sqrt_f32_e32 v33, v32
	s_nop 0
	v_add_u32_e32 v34, -1, v33
	v_fma_f32 v35, -v34, v33, v32
	v_cmp_ge_f32_e64 s[0:1], 0, v35
	v_add_u32_e32 v35, 1, v33
	s_nop 0
	v_cndmask_b32_e64 v34, v33, v34, s[0:1]
	v_fma_f32 v33, -v35, v33, v32
	v_cmp_lt_f32_e64 s[0:1], 0, v33
	s_nop 1
	v_cndmask_b32_e64 v33, v34, v35, s[0:1]
	v_mul_f32_e32 v34, 0x37800000, v33
	v_cndmask_b32_e32 v33, v33, v34, vcc
	v_cmp_class_f32_e32 vcc, v32, v151
	s_nop 1
	v_cndmask_b32_e32 v32, v33, v32, vcc
	v_div_scale_f32 v33, s[0:1], v32, v32, 1.0
	v_rcp_f32_e32 v34, v33
	s_mov_b64 s[0:1], 0x50000
	v_fma_f32 v35, -v33, v34, 1.0
	v_fmac_f32_e32 v34, v35, v34
	v_div_scale_f32 v35, vcc, 1.0, v32, 1.0
	v_mul_f32_e32 v36, v35, v34
	v_fma_f32 v37, -v33, v36, v35
	v_fmac_f32_e32 v36, v37, v34
	v_fma_f32 v33, -v33, v36, v35
	v_div_fmas_f32 v33, v33, v34, v36
	v_div_fixup_f32 v32, v33, v32, 1.0
	v_pk_mul_f32 v[24:25], v[24:25], v[32:33] op_sel_hi:[1,0]
	v_pk_mul_f32 v[34:35], v[26:27], v[32:33] op_sel_hi:[1,0]
	v_pk_mul_f32 v[30:31], v[30:31], v[32:33] op_sel_hi:[1,0]
	v_pk_mul_f32 v[28:29], v[28:29], v[32:33] op_sel_hi:[1,0]
	v_cvt_pk_bf16_f32 v26, v24, v25
	v_lshl_add_u64 v[24:25], v[112:113], 0, s[0:1]
	s_mov_b32 s0, 0x50000
	v_cvt_pk_bf16_f32 v27, v34, v35
	v_cvt_pk_bf16_f32 v28, v28, v29
	v_cvt_pk_bf16_f32 v29, v30, v31
	v_add_co_u32_e32 v30, vcc, s0, v112
	v_pk_mul_f32 v[22:23], v[22:23], v[32:33] op_sel_hi:[1,0]
	s_nop 0
	v_addc_co_u32_e32 v31, vcc, 0, v113, vcc
	global_store_dwordx4 v[30:31], v[26:29], off
	v_pk_mul_f32 v[20:21], v[20:21], v[32:33] op_sel_hi:[1,0]
	s_nop 0
	v_pk_mul_f32 v[26:27], v[18:19], v[32:33] op_sel_hi:[1,0]
	v_pk_mul_f32 v[18:19], v[16:17], v[32:33] op_sel_hi:[1,0]
	v_cvt_pk_bf16_f32 v16, v20, v21
	v_cvt_pk_bf16_f32 v17, v22, v23
	s_nop 0
	v_cvt_pk_bf16_f32 v18, v18, v19
	v_cvt_pk_bf16_f32 v19, v26, v27
	global_store_dwordx4 v[24:25], v[16:19], off offset:256
	s_nop 1
	v_mov_b32_e32 v16, v207
	v_fmamk_f32 v16, v16, 0x3c000000, v150
	v_cmp_gt_f32_e32 vcc, s6, v16
	v_mul_f32_e32 v17, 0x4f800000, v16
	s_nop 0
	v_cndmask_b32_e32 v16, v16, v17, vcc
	v_sqrt_f32_e32 v17, v16
	s_nop 0
	v_add_u32_e32 v18, -1, v17
	v_fma_f32 v19, -v18, v17, v16
	v_cmp_ge_f32_e64 s[0:1], 0, v19
	v_add_u32_e32 v19, 1, v17
	s_nop 0
	v_cndmask_b32_e64 v18, v17, v18, s[0:1]
	v_fma_f32 v17, -v19, v17, v16
	v_cmp_lt_f32_e64 s[0:1], 0, v17
	s_nop 1
	v_cndmask_b32_e64 v17, v18, v19, s[0:1]
	v_mul_f32_e32 v18, 0x37800000, v17
	v_cndmask_b32_e32 v17, v17, v18, vcc
	v_cmp_class_f32_e32 vcc, v16, v151
	s_nop 1
	v_cndmask_b32_e32 v16, v17, v16, vcc
	v_div_scale_f32 v17, s[0:1], v16, v16, 1.0
	v_rcp_f32_e32 v18, v17
	s_mov_b64 s[0:1], 0x58000
	v_fma_f32 v19, -v17, v18, 1.0
	v_fmac_f32_e32 v18, v19, v18
	v_div_scale_f32 v19, vcc, 1.0, v16, 1.0
	v_mul_f32_e32 v20, v19, v18
	v_fma_f32 v21, -v17, v20, v19
	v_fmac_f32_e32 v20, v21, v18
	v_fma_f32 v17, -v17, v20, v19
	v_div_fmas_f32 v17, v17, v18, v20
	v_div_fixup_f32 v16, v17, v16, 1.0
	v_pk_mul_f32 v[10:11], v[10:11], v[16:17] op_sel_hi:[1,0]
	v_pk_mul_f32 v[8:9], v[8:9], v[16:17] op_sel_hi:[1,0]
	v_pk_mul_f32 v[12:13], v[12:13], v[16:17] op_sel_hi:[1,0]
	v_pk_mul_f32 v[14:15], v[14:15], v[16:17] op_sel_hi:[1,0]
	v_cvt_pk_bf16_f32 v8, v8, v9
	v_cvt_pk_bf16_f32 v9, v10, v11
	v_cvt_pk_bf16_f32 v10, v12, v13
	v_lshl_add_u64 v[12:13], v[112:113], 0, s[0:1]
	s_mov_b32 s0, 0x58000
	v_cvt_pk_bf16_f32 v11, v14, v15
	v_add_co_u32_e32 v14, vcc, s0, v112
	v_pk_mul_f32 v[2:3], v[2:3], v[16:17] op_sel_hi:[1,0]
	s_nop 0
	v_addc_co_u32_e32 v15, vcc, 0, v113, vcc
	v_pk_mul_f32 v[0:1], v[0:1], v[16:17] op_sel_hi:[1,0]
	s_mov_b64 s[0:1], -1
	s_andn2_b64 vcc, exec, s[38:39]
	global_store_dwordx4 v[14:15], v[8:11], off
	v_pk_mul_f32 v[6:7], v[6:7], v[16:17] op_sel_hi:[1,0]
	v_pk_mul_f32 v[4:5], v[4:5], v[16:17] op_sel_hi:[1,0]
	v_cvt_pk_bf16_f32 v0, v0, v1
	v_cvt_pk_bf16_f32 v1, v2, v3
	s_nop 0
	v_cvt_pk_bf16_f32 v2, v4, v5
	v_cvt_pk_bf16_f32 v3, v6, v7
	global_store_dwordx4 v[12:13], v[0:3], off offset:256
	s_cbranch_vccnz .LBB0_484
	s_andn2_b64 vcc, exec, s[30:31]
	s_cbranch_vccnz .LBB0_483
	s_barrier
	s_branch .LBB0_483

; __device__ __forceinline__ u32x4 pack8(f32x4 a, f32x4 b) { u32x4 o; o.x = cvt_pk(a.x, a.y); o.y = cvt_pk(a.z, a.w); o.z = cvt_pk(b.x, b.y); o.w = cvt_pk(b.z, b.w); return o; }
; __device__ __forceinline__ float silu_f(float g) { return g * __builtin_amdgcn_rcpf(1.f + __builtin_amdgcn_exp2f(-1.4426950408889634f * g)); }
; __device__ __forceinline__ float rstd_of(const float* SS, int row, float invw) { return 1.0f / sqrtf(SS[row] * invw + EPS); }
;     __device__ __forceinline__ void operator()(const f32x4 (&acc)[2][2][4][2], const pg8::Unit& u, int wr, int wc, int fr, int fq) const {
;     ...
; #pragma unroll
;         for (int ai = 0; ai < 2; ++ai)
; #pragma unroll
;             for (int m = 0; m < 4; ++m) {
;                 const int row = row0 + ai * 128 + m * 16;
;                 const float r = SCALE ? rstd_of(SS, row, 1.f / 1024.f) : 1.f;
;                 const f32x4 g0 = acc[ai][0][m][0] * r, g1 = acc[ai][0][m][1] * r, u0 = acc[ai][1][m][0] * r, u1 = acc[ai][1][m][1] * r;
;                 f32x4 h0, h1;
;                 h0.x = silu_f(g0.x) * u0.x; h0.y = silu_f(g0.y) * u0.y; h0.z = silu_f(g0.z) * u0.z; h0.w = silu_f(g0.w) * u0.w;
;                 h1.x = silu_f(g1.x) * u1.x; h1.y = silu_f(g1.y) * u1.y; h1.z = silu_f(g1.z) * u1.z; h1.w = silu_f(g1.w) * u1.w;
;                 *(u32x4*)(hb + (wr * 64 + fr + ai * 128 + m * 16) * 64) = pack8(h0, h1);
;             }
.LBB0_827:
	v_lshl_add_u32 v158, s0, 8, v160
	v_ashrrev_i32_e32 v159, 31, v158
	v_lshl_add_u64 v[158:159], v[158:159], 2, s[44:45]
	global_load_dword v200, v[158:159], off
	global_load_dword v201, v[158:159], off offset:64
	global_load_dword v202, v[158:159], off offset:128
	global_load_dword v203, v[158:159], off offset:192
	global_load_dword v204, v[158:159], off offset:512
	global_load_dword v205, v[158:159], off offset:576
	global_load_dword v206, v[158:159], off offset:640
	global_load_dword v207, v[158:159], off offset:704
	s_lshl_b32 s1, s1, 7
	s_or_b32 s1, s1, s67
	s_mul_hi_i32 s4, s0, 0x160000
	s_mul_i32 s0, s0, 0x160000
	s_add_u32 s5, s64, s0
	s_addc_u32 s4, s65, s4
	s_ashr_i32 s0, s1, 6
	s_ashr_i32 s1, s0, 31
	s_lshl_b64 s[0:1], s[0:1], 15
	s_add_u32 s0, s5, s0
	s_addc_u32 s1, s4, s1
	v_lshl_add_u64 v[156:157], s[0:1], 0, v[136:137]
	s_waitcnt vmcnt(0)
	v_mov_b32_e32 v168, v200
	v_fmamk_f32 v168, v168, 0x3a800000, v165
	v_cmp_gt_f32_e32 vcc, s72, v168
	v_mul_f32_e32 v169, 0x4f800000, v168
	s_nop 0
	v_cndmask_b32_e32 v168, v168, v169, vcc
	v_sqrt_f32_e32 v169, v168
	s_nop 0
	v_add_u32_e32 v170, -1, v169
	v_fma_f32 v171, -v170, v169, v168
	v_cmp_ge_f32_e64 s[0:1], 0, v171
	v_add_u32_e32 v171, 1, v169
	s_nop 0
	v_cndmask_b32_e64 v170, v169, v170, s[0:1]
	v_fma_f32 v169, -v171, v169, v168
	v_cmp_lt_f32_e64 s[0:1], 0, v169
	s_nop 1
	v_cndmask_b32_e64 v169, v170, v171, s[0:1]
	v_mul_f32_e32 v170, 0x37800000, v169
	v_cndmask_b32_e32 v169, v169, v170, vcc
	v_cmp_class_f32_e32 vcc, v168, v167
	s_nop 1
	v_cndmask_b32_e32 v168, v169, v168, vcc
	v_div_scale_f32 v169, s[0:1], v168, v168, 1.0
	v_rcp_f32_e32 v170, v169
	s_nop 0
	v_fma_f32 v171, -v169, v170, 1.0
	v_fmac_f32_e32 v170, v171, v170
	v_div_scale_f32 v171, vcc, 1.0, v168, 1.0
	v_mul_f32_e32 v172, v171, v170
	v_fma_f32 v173, -v169, v172, v171
	v_fmac_f32_e32 v172, v173, v170
	v_fma_f32 v169, -v169, v172, v171
	v_div_fmas_f32 v169, v169, v170, v172
	v_div_fixup_f32 v168, v169, v168, 1.0
	v_pk_mul_f32 v[124:125], v[124:125], v[168:169] op_sel_hi:[1,0]
	v_pk_mul_f32 v[126:127], v[126:127], v[168:169] op_sel_hi:[1,0]
	v_pk_mul_f32 v[122:123], v[122:123], v[168:169] op_sel_hi:[1,0]
	v_pk_mul_f32 v[120:121], v[120:121], v[168:169] op_sel_hi:[1,0]
	v_pk_mul_f32 v[118:119], v[118:119], v[168:169] op_sel_hi:[1,0]
	v_pk_mul_f32 v[116:117], v[116:117], v[168:169] op_sel_hi:[1,0]
	v_pk_mul_f32 v[114:115], v[114:115], v[168:169] op_sel_hi:[1,0]
	v_pk_mul_f32 v[112:113], v[112:113], v[168:169] op_sel_hi:[1,0]
	v_mul_f32_e32 v168, 0xbfb8aa3b, v124
	v_exp_f32_e32 v168, v168
	s_nop 0
	v_add_f32_e32 v168, 1.0, v168
	v_rcp_f32_e32 v168, v168
	s_nop 0
	v_mul_f32_e32 v124, v124, v168
	v_mul_f32_e32 v116, v116, v124
	v_mul_f32_e32 v124, 0xbfb8aa3b, v125
	v_exp_f32_e32 v124, v124
	s_nop 0
	v_add_f32_e32 v124, 1.0, v124
	v_rcp_f32_e32 v124, v124
	s_nop 0
	v_mul_f32_e32 v124, v125, v124
	v_mul_f32_e32 v117, v117, v124
	v_mul_f32_e32 v124, 0xbfb8aa3b, v126
	v_exp_f32_e32 v124, v124
	s_nop 0
	v_add_f32_e32 v124, 1.0, v124
	v_rcp_f32_e32 v124, v124
	s_nop 0
	v_mul_f32_e32 v124, v126, v124
	v_mul_f32_e32 v118, v118, v124
	v_mul_f32_e32 v124, 0xbfb8aa3b, v127
	v_exp_f32_e32 v124, v124
	s_nop 0
	v_add_f32_e32 v124, 1.0, v124
	v_rcp_f32_e32 v124, v124
	s_nop 0
	v_mul_f32_e32 v124, v127, v124
	v_mul_f32_e32 v119, v119, v124
	v_mul_f32_e32 v124, 0xbfb8aa3b, v120
	v_exp_f32_e32 v124, v124
	s_nop 0
	v_add_f32_e32 v124, 1.0, v124
	v_rcp_f32_e32 v124, v124
	s_nop 0
	v_mul_f32_e32 v120, v120, v124
	v_mul_f32_e32 v120, v112, v120
	v_mul_f32_e32 v112, 0xbfb8aa3b, v121
	v_exp_f32_e32 v112, v112
	s_nop 0
	v_add_f32_e32 v112, 1.0, v112
	v_rcp_f32_e32 v112, v112
	s_nop 0
	v_mul_f32_e32 v112, v121, v112
	v_mul_f32_e32 v121, v113, v112
	v_mul_f32_e32 v112, 0xbfb8aa3b, v122
	v_exp_f32_e32 v112, v112
	s_nop 0
	v_add_f32_e32 v112, 1.0, v112
	v_rcp_f32_e32 v112, v112
	s_nop 0
	v_mul_f32_e32 v112, v122, v112
	v_mul_f32_e32 v122, v114, v112
	v_mul_f32_e32 v112, 0xbfb8aa3b, v123
	v_exp_f32_e32 v112, v112
	s_nop 0
	v_add_f32_e32 v112, 1.0, v112
	v_rcp_f32_e32 v112, v112
	s_nop 0
	v_mul_f32_e32 v112, v123, v112
	v_mul_f32_e32 v115, v115, v112
	v_cvt_pk_bf16_f32 v112, v116, v117
	v_lshl_add_u64 v[116:117], v[138:139], 1, v[156:157]
	v_cvt_pk_bf16_f32 v113, v118, v119
	v_cvt_pk_bf16_f32 v114, v120, v121
	v_cvt_pk_bf16_f32 v115, v122, v115
	global_store_dwordx4 v[116:117], v[112:115], off
	s_nop 1
	v_mov_b32_e32 v112, v201
	v_fmamk_f32 v112, v112, 0x3a800000, v165
	v_cmp_gt_f32_e32 vcc, s72, v112
	v_mul_f32_e32 v113, 0x4f800000, v112
	s_nop 0
	v_cndmask_b32_e32 v112, v112, v113, vcc
	v_sqrt_f32_e32 v113, v112
	s_nop 0
	v_add_u32_e32 v114, -1, v113
	v_fma_f32 v115, -v114, v113, v112
	v_cmp_ge_f32_e64 s[0:1], 0, v115
	v_add_u32_e32 v115, 1, v113
	s_nop 0
	v_cndmask_b32_e64 v114, v113, v114, s[0:1]
	v_fma_f32 v113, -v115, v113, v112
	v_cmp_lt_f32_e64 s[0:1], 0, v113
	s_nop 1
	v_cndmask_b32_e64 v113, v114, v115, s[0:1]
	v_mul_f32_e32 v114, 0x37800000, v113
	v_cndmask_b32_e32 v113, v113, v114, vcc
	v_cmp_class_f32_e32 vcc, v112, v167
	s_nop 1
	v_cndmask_b32_e32 v112, v113, v112, vcc
	v_div_scale_f32 v113, s[0:1], v112, v112, 1.0
	v_rcp_f32_e32 v114, v113
	s_nop 0
	v_fma_f32 v115, -v113, v114, 1.0
	v_fmac_f32_e32 v114, v115, v114
	v_div_scale_f32 v115, vcc, 1.0, v112, 1.0
	v_mul_f32_e32 v118, v115, v114
	v_fma_f32 v119, -v113, v118, v115
	v_fmac_f32_e32 v118, v119, v114
	v_fma_f32 v113, -v113, v118, v115
	v_div_fmas_f32 v113, v113, v114, v118
	v_div_fixup_f32 v112, v113, v112, 1.0
	v_pk_mul_f32 v[108:109], v[108:109], v[112:113] op_sel_hi:[1,0]
	v_pk_mul_f32 v[110:111], v[110:111], v[112:113] op_sel_hi:[1,0]
	v_pk_mul_f32 v[106:107], v[106:107], v[112:113] op_sel_hi:[1,0]
; __device__ __forceinline__ u32x4 pack8(f32x4 a, f32x4 b) { u32x4 o; o.x = cvt_pk(a.x, a.y); o.y = cvt_pk(a.z, a.w); o.z = cvt_pk(b.x, b.y); o.w = cvt_pk(b.z, b.w); return o; }
; __device__ __forceinline__ float silu_f(float g) { return g * __builtin_amdgcn_rcpf(1.f + __builtin_amdgcn_exp2f(-1.4426950408889634f * g)); }
; __device__ __forceinline__ float rstd_of(const float* SS, int row, float invw) { return 1.0f / sqrtf(SS[row] * invw + EPS); }
;     __device__ __forceinline__ void operator()(const f32x4 (&acc)[2][2][4][2], const pg8::Unit& u, int wr, int wc, int fr, int fq) const {
;     ...
; #pragma unroll
;         for (int ai = 0; ai < 2; ++ai)
; #pragma unroll
;             for (int m = 0; m < 4; ++m) {
;                 const int row = row0 + ai * 128 + m * 16;
;                 const float r = SCALE ? rstd_of(SS, row, 1.f / 1024.f) : 1.f;
;                 const f32x4 g0 = acc[ai][0][m][0] * r, g1 = acc[ai][0][m][1] * r, u0 = acc[ai][1][m][0] * r, u1 = acc[ai][1][m][1] * r;
;                 f32x4 h0, h1;
;                 h0.x = silu_f(g0.x) * u0.x; h0.y = silu_f(g0.y) * u0.y; h0.z = silu_f(g0.z) * u0.z; h0.w = silu_f(g0.w) * u0.w;
;                 h1.x = silu_f(g1.x) * u1.x; h1.y = silu_f(g1.y) * u1.y; h1.z = silu_f(g1.z) * u1.z; h1.w = silu_f(g1.w) * u1.w;
;                 *(u32x4*)(hb + (wr * 64 + fr + ai * 128 + m * 16) * 64) = pack8(h0, h1);
;             }
	v_pk_mul_f32 v[104:105], v[104:105], v[112:113] op_sel_hi:[1,0]
	v_pk_mul_f32 v[102:103], v[102:103], v[112:113] op_sel_hi:[1,0]
	v_pk_mul_f32 v[100:101], v[100:101], v[112:113] op_sel_hi:[1,0]
	v_pk_mul_f32 v[98:99], v[98:99], v[112:113] op_sel_hi:[1,0]
	v_pk_mul_f32 v[96:97], v[96:97], v[112:113] op_sel_hi:[1,0]
	v_mul_f32_e32 v112, 0xbfb8aa3b, v108
	v_exp_f32_e32 v112, v112
	s_nop 0
	v_add_f32_e32 v112, 1.0, v112
	v_rcp_f32_e32 v112, v112
	s_nop 0
	v_mul_f32_e32 v108, v108, v112
	v_mul_f32_e32 v100, v100, v108
	v_mul_f32_e32 v108, 0xbfb8aa3b, v109
	v_exp_f32_e32 v108, v108
	s_nop 0
	v_add_f32_e32 v108, 1.0, v108
	v_rcp_f32_e32 v108, v108
	s_nop 0
	v_mul_f32_e32 v108, v109, v108
	v_mul_f32_e32 v101, v101, v108
	v_mul_f32_e32 v108, 0xbfb8aa3b, v110
	v_exp_f32_e32 v108, v108
	s_nop 0
	v_add_f32_e32 v108, 1.0, v108
	v_rcp_f32_e32 v108, v108
	s_nop 0
	v_mul_f32_e32 v108, v110, v108
	v_mul_f32_e32 v102, v102, v108
	v_mul_f32_e32 v108, 0xbfb8aa3b, v111
	v_exp_f32_e32 v108, v108
	s_nop 0
	v_add_f32_e32 v108, 1.0, v108
	v_rcp_f32_e32 v108, v108
	s_nop 0
	v_mul_f32_e32 v108, v111, v108
	v_mul_f32_e32 v103, v103, v108
	v_mul_f32_e32 v108, 0xbfb8aa3b, v104
	v_exp_f32_e32 v108, v108
	s_nop 0
	v_add_f32_e32 v108, 1.0, v108
	v_rcp_f32_e32 v108, v108
	s_nop 0
	v_mul_f32_e32 v104, v104, v108
	v_mul_f32_e32 v104, v96, v104
	v_mul_f32_e32 v96, 0xbfb8aa3b, v105
	v_exp_f32_e32 v96, v96
	s_nop 0
	v_add_f32_e32 v96, 1.0, v96
	v_rcp_f32_e32 v96, v96
	s_nop 0
	v_mul_f32_e32 v96, v105, v96
	v_mul_f32_e32 v105, v97, v96
	v_mul_f32_e32 v96, 0xbfb8aa3b, v106
	v_exp_f32_e32 v96, v96
	s_nop 0
	v_add_f32_e32 v96, 1.0, v96
	v_rcp_f32_e32 v96, v96
	s_nop 0
	v_mul_f32_e32 v96, v106, v96
	v_mul_f32_e32 v106, v98, v96
	v_mul_f32_e32 v96, 0xbfb8aa3b, v107
	v_exp_f32_e32 v96, v96
	s_nop 0
	v_add_f32_e32 v96, 1.0, v96
	v_rcp_f32_e32 v96, v96
	s_nop 0
	v_mul_f32_e32 v96, v107, v96
	v_mul_f32_e32 v99, v99, v96
	v_cvt_pk_bf16_f32 v96, v100, v101
	v_cvt_pk_bf16_f32 v97, v102, v103
	v_cvt_pk_bf16_f32 v98, v104, v105
	v_cvt_pk_bf16_f32 v99, v106, v99
	global_store_dwordx4 v[116:117], v[96:99], off offset:2048
	s_nop 1
	v_mov_b32_e32 v96, v202
	v_fmamk_f32 v96, v96, 0x3a800000, v165
	v_cmp_gt_f32_e32 vcc, s72, v96
	v_mul_f32_e32 v97, 0x4f800000, v96
	s_nop 0
	v_cndmask_b32_e32 v96, v96, v97, vcc
	v_sqrt_f32_e32 v97, v96
	s_nop 0
	v_add_u32_e32 v98, -1, v97
	v_fma_f32 v99, -v98, v97, v96
	v_cmp_ge_f32_e64 s[0:1], 0, v99
	v_add_u32_e32 v99, 1, v97
	s_nop 0
	v_cndmask_b32_e64 v98, v97, v98, s[0:1]
	v_fma_f32 v97, -v99, v97, v96
	v_cmp_lt_f32_e64 s[0:1], 0, v97
	s_nop 1
	v_cndmask_b32_e64 v97, v98, v99, s[0:1]
	v_mul_f32_e32 v98, 0x37800000, v97
	v_cndmask_b32_e32 v97, v97, v98, vcc
	v_cmp_class_f32_e32 vcc, v96, v167
	s_nop 1
	v_cndmask_b32_e32 v96, v97, v96, vcc
	v_div_scale_f32 v97, s[0:1], v96, v96, 1.0
	v_rcp_f32_e32 v98, v97
	s_movk_i32 s0, 0x1000
	v_fma_f32 v99, -v97, v98, 1.0
	v_fmac_f32_e32 v98, v99, v98
	v_div_scale_f32 v99, vcc, 1.0, v96, 1.0
	v_mul_f32_e32 v100, v99, v98
	v_fma_f32 v101, -v97, v100, v99
	v_fmac_f32_e32 v100, v101, v98
	v_fma_f32 v97, -v97, v100, v99
	v_div_fmas_f32 v97, v97, v98, v100
	v_div_fixup_f32 v96, v97, v96, 1.0
	v_pk_mul_f32 v[92:93], v[92:93], v[96:97] op_sel_hi:[1,0]
	v_pk_mul_f32 v[94:95], v[94:95], v[96:97] op_sel_hi:[1,0]
	v_pk_mul_f32 v[90:91], v[90:91], v[96:97] op_sel_hi:[1,0]
	v_pk_mul_f32 v[88:89], v[88:89], v[96:97] op_sel_hi:[1,0]
	v_pk_mul_f32 v[86:87], v[86:87], v[96:97] op_sel_hi:[1,0]
	v_pk_mul_f32 v[84:85], v[84:85], v[96:97] op_sel_hi:[1,0]
	v_pk_mul_f32 v[82:83], v[82:83], v[96:97] op_sel_hi:[1,0]
	v_pk_mul_f32 v[80:81], v[80:81], v[96:97] op_sel_hi:[1,0]
	v_mul_f32_e32 v96, 0xbfb8aa3b, v92
	v_exp_f32_e32 v96, v96
	s_nop 0
	v_add_f32_e32 v96, 1.0, v96
	v_rcp_f32_e32 v96, v96
	s_nop 0
	v_mul_f32_e32 v92, v92, v96
	v_mul_f32_e32 v84, v84, v92
	v_mul_f32_e32 v92, 0xbfb8aa3b, v93
	v_exp_f32_e32 v92, v92
	s_nop 0
	v_add_f32_e32 v92, 1.0, v92
	v_rcp_f32_e32 v92, v92
	s_nop 0
	v_mul_f32_e32 v92, v93, v92
	v_mul_f32_e32 v85, v85, v92
	v_mul_f32_e32 v92, 0xbfb8aa3b, v94
	v_exp_f32_e32 v92, v92
	s_nop 0
	v_add_f32_e32 v92, 1.0, v92
	v_rcp_f32_e32 v92, v92
	s_nop 0
	v_mul_f32_e32 v92, v94, v92
	v_mul_f32_e32 v86, v86, v92
	v_mul_f32_e32 v92, 0xbfb8aa3b, v95
	v_exp_f32_e32 v92, v92
	s_nop 0
	v_add_f32_e32 v92, 1.0, v92
	v_rcp_f32_e32 v92, v92
	s_nop 0
	v_mul_f32_e32 v92, v95, v92
	v_mul_f32_e32 v87, v87, v92
	v_mul_f32_e32 v92, 0xbfb8aa3b, v88
	v_exp_f32_e32 v92, v92
	s_nop 0
	v_add_f32_e32 v92, 1.0, v92
	v_rcp_f32_e32 v92, v92
	s_nop 0
	v_mul_f32_e32 v88, v88, v92
	v_mul_f32_e32 v88, v80, v88
	v_mul_f32_e32 v80, 0xbfb8aa3b, v89
	v_exp_f32_e32 v80, v80
	s_nop 0
	v_add_f32_e32 v80, 1.0, v80
	v_rcp_f32_e32 v80, v80
	s_nop 0
	v_mul_f32_e32 v80, v89, v80
	v_mul_f32_e32 v89, v81, v80
	v_mul_f32_e32 v80, 0xbfb8aa3b, v90
	v_exp_f32_e32 v80, v80
	s_nop 0
	v_add_f32_e32 v80, 1.0, v80
	v_rcp_f32_e32 v80, v80
	s_nop 0
	v_mul_f32_e32 v80, v90, v80
	v_mul_f32_e32 v90, v82, v80
	v_mul_f32_e32 v80, 0xbfb8aa3b, v91
	v_exp_f32_e32 v80, v80
	s_nop 0
	v_add_f32_e32 v80, 1.0, v80
	v_rcp_f32_e32 v80, v80
	s_nop 0
	v_mul_f32_e32 v80, v91, v80
	v_mul_f32_e32 v83, v83, v80
	v_cvt_pk_bf16_f32 v80, v84, v85
	v_add_co_u32_e32 v84, vcc, s0, v116
	v_cvt_pk_bf16_f32 v81, v86, v87
	v_cvt_pk_bf16_f32 v82, v88, v89
	v_cvt_pk_bf16_f32 v83, v90, v83
	s_nop 1
	v_addc_co_u32_e32 v85, vcc, 0, v117, vcc
	global_store_dwordx4 v[84:85], v[80:83], off
	s_nop 1
	v_mov_b32_e32 v80, v203
	v_fmamk_f32 v80, v80, 0x3a800000, v165
	v_cmp_gt_f32_e32 vcc, s72, v80
	v_mul_f32_e32 v81, 0x4f800000, v80
	s_nop 0
	v_cndmask_b32_e32 v80, v80, v81, vcc
	v_sqrt_f32_e32 v81, v80
	s_nop 0
; __device__ __forceinline__ u32x4 pack8(f32x4 a, f32x4 b) { u32x4 o; o.x = cvt_pk(a.x, a.y); o.y = cvt_pk(a.z, a.w); o.z = cvt_pk(b.x, b.y); o.w = cvt_pk(b.z, b.w); return o; }
; __device__ __forceinline__ float silu_f(float g) { return g * __builtin_amdgcn_rcpf(1.f + __builtin_amdgcn_exp2f(-1.4426950408889634f * g)); }
; __device__ __forceinline__ float rstd_of(const float* SS, int row, float invw) { return 1.0f / sqrtf(SS[row] * invw + EPS); }
;     __device__ __forceinline__ void operator()(const f32x4 (&acc)[2][2][4][2], const pg8::Unit& u, int wr, int wc, int fr, int fq) const {
;     ...
; #pragma unroll
;         for (int ai = 0; ai < 2; ++ai)
; #pragma unroll
;             for (int m = 0; m < 4; ++m) {
;                 const int row = row0 + ai * 128 + m * 16;
;                 const float r = SCALE ? rstd_of(SS, row, 1.f / 1024.f) : 1.f;
;                 const f32x4 g0 = acc[ai][0][m][0] * r, g1 = acc[ai][0][m][1] * r, u0 = acc[ai][1][m][0] * r, u1 = acc[ai][1][m][1] * r;
;                 f32x4 h0, h1;
;                 h0.x = silu_f(g0.x) * u0.x; h0.y = silu_f(g0.y) * u0.y; h0.z = silu_f(g0.z) * u0.z; h0.w = silu_f(g0.w) * u0.w;
;                 h1.x = silu_f(g1.x) * u1.x; h1.y = silu_f(g1.y) * u1.y; h1.z = silu_f(g1.z) * u1.z; h1.w = silu_f(g1.w) * u1.w;
;                 *(u32x4*)(hb + (wr * 64 + fr + ai * 128 + m * 16) * 64) = pack8(h0, h1);
;             }
	v_add_u32_e32 v82, -1, v81
	v_fma_f32 v83, -v82, v81, v80
	v_cmp_ge_f32_e64 s[0:1], 0, v83
	v_add_u32_e32 v83, 1, v81
	s_nop 0
	v_cndmask_b32_e64 v82, v81, v82, s[0:1]
	v_fma_f32 v81, -v83, v81, v80
	v_cmp_lt_f32_e64 s[0:1], 0, v81
	s_nop 1
	v_cndmask_b32_e64 v81, v82, v83, s[0:1]
	v_mul_f32_e32 v82, 0x37800000, v81
	v_cndmask_b32_e32 v81, v81, v82, vcc
	v_cmp_class_f32_e32 vcc, v80, v167
	s_nop 1
	v_cndmask_b32_e32 v80, v81, v80, vcc
	v_div_scale_f32 v81, s[0:1], v80, v80, 1.0
	v_rcp_f32_e32 v82, v81
	s_nop 0
	v_fma_f32 v83, -v81, v82, 1.0
	v_fmac_f32_e32 v82, v83, v82
	v_div_scale_f32 v83, vcc, 1.0, v80, 1.0
	v_mul_f32_e32 v86, v83, v82
	v_fma_f32 v87, -v81, v86, v83
	v_fmac_f32_e32 v86, v87, v82
	v_fma_f32 v81, -v81, v86, v83
	v_div_fmas_f32 v81, v81, v82, v86
	v_div_fixup_f32 v80, v81, v80, 1.0
	v_pk_mul_f32 v[76:77], v[76:77], v[80:81] op_sel_hi:[1,0]
	v_pk_mul_f32 v[78:79], v[78:79], v[80:81] op_sel_hi:[1,0]
	v_pk_mul_f32 v[74:75], v[74:75], v[80:81] op_sel_hi:[1,0]
	v_pk_mul_f32 v[72:73], v[72:73], v[80:81] op_sel_hi:[1,0]
	v_pk_mul_f32 v[70:71], v[70:71], v[80:81] op_sel_hi:[1,0]
	v_pk_mul_f32 v[68:69], v[68:69], v[80:81] op_sel_hi:[1,0]
	v_pk_mul_f32 v[66:67], v[66:67], v[80:81] op_sel_hi:[1,0]
	v_pk_mul_f32 v[64:65], v[64:65], v[80:81] op_sel_hi:[1,0]
	v_mul_f32_e32 v80, 0xbfb8aa3b, v76
	v_exp_f32_e32 v80, v80
	s_nop 0
	v_add_f32_e32 v80, 1.0, v80
	v_rcp_f32_e32 v80, v80
	s_nop 0
	v_mul_f32_e32 v76, v76, v80
	v_mul_f32_e32 v68, v68, v76
	v_mul_f32_e32 v76, 0xbfb8aa3b, v77
	v_exp_f32_e32 v76, v76
	s_nop 0
	v_add_f32_e32 v76, 1.0, v76
	v_rcp_f32_e32 v76, v76
	s_nop 0
	v_mul_f32_e32 v76, v77, v76
	v_mul_f32_e32 v69, v69, v76
	v_mul_f32_e32 v76, 0xbfb8aa3b, v78
	v_exp_f32_e32 v76, v76
	s_nop 0
	v_add_f32_e32 v76, 1.0, v76
	v_rcp_f32_e32 v76, v76
	s_nop 0
	v_mul_f32_e32 v76, v78, v76
	v_mul_f32_e32 v70, v70, v76
	v_mul_f32_e32 v76, 0xbfb8aa3b, v79
	v_exp_f32_e32 v76, v76
	s_nop 0
	v_add_f32_e32 v76, 1.0, v76
	v_rcp_f32_e32 v76, v76
	s_nop 0
	v_mul_f32_e32 v76, v79, v76
	v_mul_f32_e32 v71, v71, v76
	v_mul_f32_e32 v76, 0xbfb8aa3b, v72
	v_exp_f32_e32 v76, v76
	s_nop 0
	v_add_f32_e32 v76, 1.0, v76
	v_rcp_f32_e32 v76, v76
	s_nop 0
	v_mul_f32_e32 v72, v72, v76
	v_mul_f32_e32 v72, v64, v72
	v_mul_f32_e32 v64, 0xbfb8aa3b, v73
	v_exp_f32_e32 v64, v64
	s_nop 0
	v_add_f32_e32 v64, 1.0, v64
	v_rcp_f32_e32 v64, v64
	s_nop 0
	v_mul_f32_e32 v64, v73, v64
	v_mul_f32_e32 v73, v65, v64
	v_mul_f32_e32 v64, 0xbfb8aa3b, v74
	v_exp_f32_e32 v64, v64
	s_nop 0
	v_add_f32_e32 v64, 1.0, v64
	v_rcp_f32_e32 v64, v64
	s_nop 0
	v_mul_f32_e32 v64, v74, v64
	v_mul_f32_e32 v74, v66, v64
	v_mul_f32_e32 v64, 0xbfb8aa3b, v75
	v_exp_f32_e32 v64, v64
	s_nop 0
	v_add_f32_e32 v64, 1.0, v64
	v_rcp_f32_e32 v64, v64
	s_nop 0
	v_mul_f32_e32 v64, v75, v64
	v_mul_f32_e32 v67, v67, v64
	v_cvt_pk_bf16_f32 v64, v68, v69
	v_cvt_pk_bf16_f32 v65, v70, v71
	v_cvt_pk_bf16_f32 v66, v72, v73
	v_cvt_pk_bf16_f32 v67, v74, v67
	global_store_dwordx4 v[84:85], v[64:67], off offset:2048
	s_nop 1
	v_mov_b32_e32 v64, v204
	v_fmamk_f32 v64, v64, 0x3a800000, v165
	v_cmp_gt_f32_e32 vcc, s72, v64
	v_mul_f32_e32 v65, 0x4f800000, v64
	s_nop 0
	v_cndmask_b32_e32 v64, v64, v65, vcc
	v_sqrt_f32_e32 v65, v64
	s_nop 0
	v_add_u32_e32 v66, -1, v65
	v_fma_f32 v67, -v66, v65, v64
	v_cmp_ge_f32_e64 s[0:1], 0, v67
	v_add_u32_e32 v67, 1, v65
	s_nop 0
	v_cndmask_b32_e64 v66, v65, v66, s[0:1]
	v_fma_f32 v65, -v67, v65, v64
	v_cmp_lt_f32_e64 s[0:1], 0, v65
	s_nop 1
	v_cndmask_b32_e64 v65, v66, v67, s[0:1]
	v_mul_f32_e32 v66, 0x37800000, v65
	v_cndmask_b32_e32 v65, v65, v66, vcc
	v_cmp_class_f32_e32 vcc, v64, v167
	s_nop 1
	v_cndmask_b32_e32 v64, v65, v64, vcc
	v_div_scale_f32 v65, s[0:1], v64, v64, 1.0
	v_rcp_f32_e32 v66, v65
	s_nop 0
	v_fma_f32 v67, -v65, v66, 1.0
	v_fmac_f32_e32 v66, v67, v66
	v_div_scale_f32 v67, vcc, 1.0, v64, 1.0
	v_mul_f32_e32 v68, v67, v66
	v_fma_f32 v69, -v65, v68, v67
	v_fmac_f32_e32 v68, v69, v66
	v_fma_f32 v65, -v65, v68, v67
	v_div_fmas_f32 v65, v65, v66, v68
	v_div_fixup_f32 v64, v65, v64, 1.0
	v_pk_mul_f32 v[60:61], v[60:61], v[64:65] op_sel_hi:[1,0]
	v_pk_mul_f32 v[62:63], v[62:63], v[64:65] op_sel_hi:[1,0]
	v_pk_mul_f32 v[58:59], v[58:59], v[64:65] op_sel_hi:[1,0]
	v_pk_mul_f32 v[56:57], v[56:57], v[64:65] op_sel_hi:[1,0]
	v_pk_mul_f32 v[54:55], v[54:55], v[64:65] op_sel_hi:[1,0]
	v_pk_mul_f32 v[52:53], v[52:53], v[64:65] op_sel_hi:[1,0]
	v_pk_mul_f32 v[50:51], v[50:51], v[64:65] op_sel_hi:[1,0]
	v_pk_mul_f32 v[48:49], v[48:49], v[64:65] op_sel_hi:[1,0]
	v_mul_f32_e32 v64, 0xbfb8aa3b, v60
	v_exp_f32_e32 v64, v64
	s_nop 0
	v_add_f32_e32 v64, 1.0, v64
	v_rcp_f32_e32 v64, v64
	s_nop 0
	v_mul_f32_e32 v60, v60, v64
	v_mul_f32_e32 v52, v52, v60
	v_mul_f32_e32 v60, 0xbfb8aa3b, v61
	v_exp_f32_e32 v60, v60
	s_nop 0
	v_add_f32_e32 v60, 1.0, v60
	v_rcp_f32_e32 v60, v60
	s_nop 0
	v_mul_f32_e32 v60, v61, v60
	v_mul_f32_e32 v53, v53, v60
	v_mul_f32_e32 v60, 0xbfb8aa3b, v62
	v_exp_f32_e32 v60, v60
	s_nop 0
	v_add_f32_e32 v60, 1.0, v60
	v_rcp_f32_e32 v60, v60
	s_nop 0
	v_mul_f32_e32 v60, v62, v60
	v_mul_f32_e32 v54, v54, v60
	v_mul_f32_e32 v60, 0xbfb8aa3b, v63
	v_exp_f32_e32 v60, v60
	s_nop 0
	v_add_f32_e32 v60, 1.0, v60
	v_rcp_f32_e32 v60, v60
	s_nop 0
	v_mul_f32_e32 v60, v63, v60
	v_mul_f32_e32 v55, v55, v60
	v_mul_f32_e32 v60, 0xbfb8aa3b, v56
	v_exp_f32_e32 v60, v60
	s_nop 0
	v_add_f32_e32 v60, 1.0, v60
	v_rcp_f32_e32 v60, v60
	s_nop 0
	v_mul_f32_e32 v56, v56, v60
	v_mul_f32_e32 v56, v48, v56
	v_mul_f32_e32 v48, 0xbfb8aa3b, v57
	v_exp_f32_e32 v48, v48
	s_nop 0
	v_add_f32_e32 v48, 1.0, v48
	v_rcp_f32_e32 v48, v48
	s_nop 0
	v_mul_f32_e32 v48, v57, v48
	v_mul_f32_e32 v57, v49, v48
; __device__ __forceinline__ u32x4 pack8(f32x4 a, f32x4 b) { u32x4 o; o.x = cvt_pk(a.x, a.y); o.y = cvt_pk(a.z, a.w); o.z = cvt_pk(b.x, b.y); o.w = cvt_pk(b.z, b.w); return o; }
; __device__ __forceinline__ float silu_f(float g) { return g * __builtin_amdgcn_rcpf(1.f + __builtin_amdgcn_exp2f(-1.4426950408889634f * g)); }
; __device__ __forceinline__ float rstd_of(const float* SS, int row, float invw) { return 1.0f / sqrtf(SS[row] * invw + EPS); }
;     __device__ __forceinline__ void operator()(const f32x4 (&acc)[2][2][4][2], const pg8::Unit& u, int wr, int wc, int fr, int fq) const {
;     ...
; #pragma unroll
;         for (int ai = 0; ai < 2; ++ai)
; #pragma unroll
;             for (int m = 0; m < 4; ++m) {
;                 const int row = row0 + ai * 128 + m * 16;
;                 const float r = SCALE ? rstd_of(SS, row, 1.f / 1024.f) : 1.f;
;                 const f32x4 g0 = acc[ai][0][m][0] * r, g1 = acc[ai][0][m][1] * r, u0 = acc[ai][1][m][0] * r, u1 = acc[ai][1][m][1] * r;
;                 f32x4 h0, h1;
;                 h0.x = silu_f(g0.x) * u0.x; h0.y = silu_f(g0.y) * u0.y; h0.z = silu_f(g0.z) * u0.z; h0.w = silu_f(g0.w) * u0.w;
;                 h1.x = silu_f(g1.x) * u1.x; h1.y = silu_f(g1.y) * u1.y; h1.z = silu_f(g1.z) * u1.z; h1.w = silu_f(g1.w) * u1.w;
;                 *(u32x4*)(hb + (wr * 64 + fr + ai * 128 + m * 16) * 64) = pack8(h0, h1);
;             }
	v_mul_f32_e32 v48, 0xbfb8aa3b, v58
	v_exp_f32_e32 v48, v48
	s_nop 0
	v_add_f32_e32 v48, 1.0, v48
	v_rcp_f32_e32 v48, v48
	s_nop 0
	v_mul_f32_e32 v48, v58, v48
	v_mul_f32_e32 v58, v50, v48
	v_mul_f32_e32 v48, 0xbfb8aa3b, v59
	v_exp_f32_e32 v48, v48
	s_nop 0
	v_add_f32_e32 v48, 1.0, v48
	v_rcp_f32_e32 v48, v48
	s_nop 0
	v_mul_f32_e32 v48, v59, v48
	v_mul_f32_e32 v51, v51, v48
	v_cvt_pk_bf16_f32 v48, v52, v53
	v_lshl_add_u64 v[52:53], v[140:141], 1, v[156:157]
	v_cvt_pk_bf16_f32 v49, v54, v55
	v_cvt_pk_bf16_f32 v50, v56, v57
	v_cvt_pk_bf16_f32 v51, v58, v51
	global_store_dwordx4 v[52:53], v[48:51], off
	s_nop 1
	v_mov_b32_e32 v48, v205
	v_fmamk_f32 v48, v48, 0x3a800000, v165
	v_cmp_gt_f32_e32 vcc, s72, v48
	v_mul_f32_e32 v49, 0x4f800000, v48
	s_nop 0
	v_cndmask_b32_e32 v48, v48, v49, vcc
	v_sqrt_f32_e32 v49, v48
	s_nop 0
	v_add_u32_e32 v50, -1, v49
	v_fma_f32 v51, -v50, v49, v48
	v_cmp_ge_f32_e64 s[0:1], 0, v51
	v_add_u32_e32 v51, 1, v49
	s_nop 0
	v_cndmask_b32_e64 v50, v49, v50, s[0:1]
	v_fma_f32 v49, -v51, v49, v48
	v_cmp_lt_f32_e64 s[0:1], 0, v49
	s_nop 1
	v_cndmask_b32_e64 v49, v50, v51, s[0:1]
	v_mul_f32_e32 v50, 0x37800000, v49
	v_cndmask_b32_e32 v49, v49, v50, vcc
	v_cmp_class_f32_e32 vcc, v48, v167
	s_nop 1
	v_cndmask_b32_e32 v48, v49, v48, vcc
	v_div_scale_f32 v49, s[0:1], v48, v48, 1.0
	v_rcp_f32_e32 v50, v49
	s_nop 0
	v_fma_f32 v51, -v49, v50, 1.0
	v_fmac_f32_e32 v50, v51, v50
	v_div_scale_f32 v51, vcc, 1.0, v48, 1.0
	v_mul_f32_e32 v52, v51, v50
	v_fma_f32 v53, -v49, v52, v51
	v_fmac_f32_e32 v52, v53, v50
	v_fma_f32 v49, -v49, v52, v51
	v_div_fmas_f32 v49, v49, v50, v52
	v_div_fixup_f32 v48, v49, v48, 1.0
	v_pk_mul_f32 v[44:45], v[44:45], v[48:49] op_sel_hi:[1,0]
	v_pk_mul_f32 v[46:47], v[46:47], v[48:49] op_sel_hi:[1,0]
	v_pk_mul_f32 v[42:43], v[42:43], v[48:49] op_sel_hi:[1,0]
	v_pk_mul_f32 v[40:41], v[40:41], v[48:49] op_sel_hi:[1,0]
	v_pk_mul_f32 v[38:39], v[38:39], v[48:49] op_sel_hi:[1,0]
	v_pk_mul_f32 v[36:37], v[36:37], v[48:49] op_sel_hi:[1,0]
	v_pk_mul_f32 v[34:35], v[34:35], v[48:49] op_sel_hi:[1,0]
	v_pk_mul_f32 v[32:33], v[32:33], v[48:49] op_sel_hi:[1,0]
	v_mul_f32_e32 v48, 0xbfb8aa3b, v44
	v_exp_f32_e32 v48, v48
	s_nop 0
	v_add_f32_e32 v48, 1.0, v48
	v_rcp_f32_e32 v48, v48
	s_nop 0
	v_mul_f32_e32 v44, v44, v48
	v_mul_f32_e32 v36, v36, v44
	v_mul_f32_e32 v44, 0xbfb8aa3b, v45
	v_exp_f32_e32 v44, v44
	s_nop 0
	v_add_f32_e32 v44, 1.0, v44
	v_rcp_f32_e32 v44, v44
	s_nop 0
	v_mul_f32_e32 v44, v45, v44
	v_mul_f32_e32 v37, v37, v44
	v_mul_f32_e32 v44, 0xbfb8aa3b, v46
	v_exp_f32_e32 v44, v44
	s_nop 0
	v_add_f32_e32 v44, 1.0, v44
	v_rcp_f32_e32 v44, v44
	s_nop 0
	v_mul_f32_e32 v44, v46, v44
	v_mul_f32_e32 v38, v38, v44
	v_mul_f32_e32 v44, 0xbfb8aa3b, v47
	v_exp_f32_e32 v44, v44
	s_nop 0
	v_add_f32_e32 v44, 1.0, v44
	v_rcp_f32_e32 v44, v44
	s_nop 0
	v_mul_f32_e32 v44, v47, v44
	v_mul_f32_e32 v39, v39, v44
	v_mul_f32_e32 v44, 0xbfb8aa3b, v40
	v_exp_f32_e32 v44, v44
	s_nop 0
	v_add_f32_e32 v44, 1.0, v44
	v_rcp_f32_e32 v44, v44
	s_nop 0
	v_mul_f32_e32 v40, v40, v44
	v_mul_f32_e32 v40, v32, v40
	v_mul_f32_e32 v32, 0xbfb8aa3b, v41
	v_exp_f32_e32 v32, v32
	s_nop 0
	v_add_f32_e32 v32, 1.0, v32
	v_rcp_f32_e32 v32, v32
	s_nop 0
	v_mul_f32_e32 v32, v41, v32
	v_mul_f32_e32 v41, v33, v32
	v_mul_f32_e32 v32, 0xbfb8aa3b, v42
	v_exp_f32_e32 v32, v32
	s_nop 0
	v_add_f32_e32 v32, 1.0, v32
	v_rcp_f32_e32 v32, v32
	s_nop 0
	v_mul_f32_e32 v32, v42, v32
	v_mul_f32_e32 v42, v34, v32
	v_mul_f32_e32 v32, 0xbfb8aa3b, v43
	v_exp_f32_e32 v32, v32
	s_nop 0
	v_add_f32_e32 v32, 1.0, v32
	v_rcp_f32_e32 v32, v32
	s_nop 0
	v_mul_f32_e32 v32, v43, v32
	v_mul_f32_e32 v35, v35, v32
	v_cvt_pk_bf16_f32 v32, v36, v37
	v_lshl_add_u64 v[36:37], v[142:143], 1, v[156:157]
	v_cvt_pk_bf16_f32 v33, v38, v39
	v_cvt_pk_bf16_f32 v34, v40, v41
	v_cvt_pk_bf16_f32 v35, v42, v35
	global_store_dwordx4 v[36:37], v[32:35], off
	s_nop 1
	v_mov_b32_e32 v32, v206
	v_fmamk_f32 v32, v32, 0x3a800000, v165
	v_cmp_gt_f32_e32 vcc, s72, v32
	v_mul_f32_e32 v33, 0x4f800000, v32
	s_nop 0
	v_cndmask_b32_e32 v32, v32, v33, vcc
	v_sqrt_f32_e32 v33, v32
	s_nop 0
	v_add_u32_e32 v34, -1, v33
	v_fma_f32 v35, -v34, v33, v32
	v_cmp_ge_f32_e64 s[0:1], 0, v35
	v_add_u32_e32 v35, 1, v33
	s_nop 0
	v_cndmask_b32_e64 v34, v33, v34, s[0:1]
	v_fma_f32 v33, -v35, v33, v32
	v_cmp_lt_f32_e64 s[0:1], 0, v33
	s_nop 1
	v_cndmask_b32_e64 v33, v34, v35, s[0:1]
	v_mul_f32_e32 v34, 0x37800000, v33
	v_cndmask_b32_e32 v33, v33, v34, vcc
	v_cmp_class_f32_e32 vcc, v32, v167
	s_nop 1
	v_cndmask_b32_e32 v32, v33, v32, vcc
	v_div_scale_f32 v33, s[0:1], v32, v32, 1.0
	v_rcp_f32_e32 v34, v33
	s_nop 0
	v_fma_f32 v35, -v33, v34, 1.0
	v_fmac_f32_e32 v34, v35, v34
	v_div_scale_f32 v35, vcc, 1.0, v32, 1.0
	v_mul_f32_e32 v36, v35, v34
	v_fma_f32 v37, -v33, v36, v35
	v_fmac_f32_e32 v36, v37, v34
	v_fma_f32 v33, -v33, v36, v35
	v_div_fmas_f32 v33, v33, v34, v36
	v_div_fixup_f32 v32, v33, v32, 1.0
	v_pk_mul_f32 v[28:29], v[28:29], v[32:33] op_sel_hi:[1,0]
	v_pk_mul_f32 v[30:31], v[30:31], v[32:33] op_sel_hi:[1,0]
	v_pk_mul_f32 v[26:27], v[26:27], v[32:33] op_sel_hi:[1,0]
	v_pk_mul_f32 v[24:25], v[24:25], v[32:33] op_sel_hi:[1,0]
	v_pk_mul_f32 v[22:23], v[22:23], v[32:33] op_sel_hi:[1,0]
; #define PG8_BAR __builtin_amdgcn_s_barrier()
; __device__ __forceinline__ u32x4 pack8(f32x4 a, f32x4 b) { u32x4 o; o.x = cvt_pk(a.x, a.y); o.y = cvt_pk(a.z, a.w); o.z = cvt_pk(b.x, b.y); o.w = cvt_pk(b.z, b.w); return o; }
; template <class Epi, class Sched, bool ALIGN_EPI = false, bool SP2 = false, bool ABLK = false>
; __device__ __forceinline__ void gemm_phase(PG8_LAS unsigned char* lds, const Gemm g, const Sched& S, const Epi& E) {
;     ...
;         if (!has_next) break;
; #pragma unroll
;         for (int a = 0; a < 2; ++a)
; #pragma unroll
;             for (int b = 0; b < 2; ++b)
; #pragma unroll
;                 for (int m = 0; m < 4; ++m)
; #pragma unroll
;                     for (int n = 0; n < 2; ++n) acc[a][b][m][n] = (f32x4){0.f, 0.f, 0.f, 0.f};
;         cur = nxt; cA = nA; cB = nB; ++ui;
;         if constexpr (ALIGN_EPI) { if (wr == 1) PG8_BAR; }
; __device__ __forceinline__ float silu_f(float g) { return g * __builtin_amdgcn_rcpf(1.f + __builtin_amdgcn_exp2f(-1.4426950408889634f * g)); }
; __device__ __forceinline__ float rstd_of(const float* SS, int row, float invw) { return 1.0f / sqrtf(SS[row] * invw + EPS); }
;     __device__ __forceinline__ void operator()(const f32x4 (&acc)[2][2][4][2], const pg8::Unit& u, int wr, int wc, int fr, int fq) const {
;     ...
; #pragma unroll
;         for (int ai = 0; ai < 2; ++ai)
; #pragma unroll
;             for (int m = 0; m < 4; ++m) {
;                 const int row = row0 + ai * 128 + m * 16;
;                 const float r = SCALE ? rstd_of(SS, row, 1.f / 1024.f) : 1.f;
;                 const f32x4 g0 = acc[ai][0][m][0] * r, g1 = acc[ai][0][m][1] * r, u0 = acc[ai][1][m][0] * r, u1 = acc[ai][1][m][1] * r;
;                 f32x4 h0, h1;
;                 h0.x = silu_f(g0.x) * u0.x; h0.y = silu_f(g0.y) * u0.y; h0.z = silu_f(g0.z) * u0.z; h0.w = silu_f(g0.w) * u0.w;
;                 h1.x = silu_f(g1.x) * u1.x; h1.y = silu_f(g1.y) * u1.y; h1.z = silu_f(g1.z) * u1.z; h1.w = silu_f(g1.w) * u1.w;
;                 *(u32x4*)(hb + (wr * 64 + fr + ai * 128 + m * 16) * 64) = pack8(h0, h1);
;             }
	v_pk_mul_f32 v[20:21], v[20:21], v[32:33] op_sel_hi:[1,0]
	v_pk_mul_f32 v[18:19], v[18:19], v[32:33] op_sel_hi:[1,0]
	v_pk_mul_f32 v[16:17], v[16:17], v[32:33] op_sel_hi:[1,0]
	v_mul_f32_e32 v32, 0xbfb8aa3b, v28
	v_exp_f32_e32 v32, v32
	s_nop 0
	v_add_f32_e32 v32, 1.0, v32
	v_rcp_f32_e32 v32, v32
	s_nop 0
	v_mul_f32_e32 v28, v28, v32
	v_mul_f32_e32 v20, v20, v28
	v_mul_f32_e32 v28, 0xbfb8aa3b, v29
	v_exp_f32_e32 v28, v28
	s_nop 0
	v_add_f32_e32 v28, 1.0, v28
	v_rcp_f32_e32 v28, v28
	s_nop 0
	v_mul_f32_e32 v28, v29, v28
	v_mul_f32_e32 v21, v21, v28
	v_mul_f32_e32 v28, 0xbfb8aa3b, v30
	v_exp_f32_e32 v28, v28
	s_nop 0
	v_add_f32_e32 v28, 1.0, v28
	v_rcp_f32_e32 v28, v28
	s_nop 0
	v_mul_f32_e32 v28, v30, v28
	v_mul_f32_e32 v22, v22, v28
	v_mul_f32_e32 v28, 0xbfb8aa3b, v31
	v_exp_f32_e32 v28, v28
	s_nop 0
	v_add_f32_e32 v28, 1.0, v28
	v_rcp_f32_e32 v28, v28
	s_nop 0
	v_mul_f32_e32 v28, v31, v28
	v_mul_f32_e32 v23, v23, v28
	v_mul_f32_e32 v28, 0xbfb8aa3b, v24
	v_exp_f32_e32 v28, v28
	s_nop 0
	v_add_f32_e32 v28, 1.0, v28
	v_rcp_f32_e32 v28, v28
	s_nop 0
	v_mul_f32_e32 v24, v24, v28
	v_mul_f32_e32 v24, v16, v24
	v_mul_f32_e32 v16, 0xbfb8aa3b, v25
	v_exp_f32_e32 v16, v16
	s_nop 0
	v_add_f32_e32 v16, 1.0, v16
	v_rcp_f32_e32 v16, v16
	s_nop 0
	v_mul_f32_e32 v16, v25, v16
	v_mul_f32_e32 v25, v17, v16
	v_mul_f32_e32 v16, 0xbfb8aa3b, v26
	v_exp_f32_e32 v16, v16
	s_nop 0
	v_add_f32_e32 v16, 1.0, v16
	v_rcp_f32_e32 v16, v16
	s_nop 0
	v_mul_f32_e32 v16, v26, v16
	v_mul_f32_e32 v26, v18, v16
	v_mul_f32_e32 v16, 0xbfb8aa3b, v27
	v_exp_f32_e32 v16, v16
	s_nop 0
	v_add_f32_e32 v16, 1.0, v16
	v_rcp_f32_e32 v16, v16
	s_nop 0
	v_mul_f32_e32 v16, v27, v16
	v_mul_f32_e32 v19, v19, v16
	v_cvt_pk_bf16_f32 v16, v20, v21
	v_lshl_add_u64 v[20:21], v[144:145], 1, v[156:157]
	v_cvt_pk_bf16_f32 v17, v22, v23
	v_cvt_pk_bf16_f32 v18, v24, v25
	v_cvt_pk_bf16_f32 v19, v26, v19
	global_store_dwordx4 v[20:21], v[16:19], off
	s_nop 1
	v_mov_b32_e32 v16, v207
	v_fmamk_f32 v16, v16, 0x3a800000, v165
	v_cmp_gt_f32_e32 vcc, s72, v16
	v_mul_f32_e32 v17, 0x4f800000, v16
	s_nop 0
	v_cndmask_b32_e32 v16, v16, v17, vcc
	v_sqrt_f32_e32 v17, v16
	s_nop 0
	v_add_u32_e32 v18, -1, v17
	v_fma_f32 v19, -v18, v17, v16
	v_cmp_ge_f32_e64 s[0:1], 0, v19
	v_add_u32_e32 v19, 1, v17
	s_nop 0
	v_cndmask_b32_e64 v18, v17, v18, s[0:1]
	v_fma_f32 v17, -v19, v17, v16
	v_cmp_lt_f32_e64 s[0:1], 0, v17
	s_nop 1
	v_cndmask_b32_e64 v17, v18, v19, s[0:1]
	v_mul_f32_e32 v18, 0x37800000, v17
	v_cndmask_b32_e32 v17, v17, v18, vcc
	v_cmp_class_f32_e32 vcc, v16, v167
	s_nop 1
	v_cndmask_b32_e32 v16, v17, v16, vcc
	v_div_scale_f32 v17, s[0:1], v16, v16, 1.0
	v_rcp_f32_e32 v18, v17
	s_mov_b64 s[0:1], -1
	v_fma_f32 v19, -v17, v18, 1.0
	v_fmac_f32_e32 v18, v19, v18
	v_div_scale_f32 v19, vcc, 1.0, v16, 1.0
	v_mul_f32_e32 v20, v19, v18
	v_fma_f32 v21, -v17, v20, v19
	v_fmac_f32_e32 v20, v21, v18
	v_fma_f32 v17, -v17, v20, v19
	v_div_fmas_f32 v17, v17, v18, v20
	v_div_fixup_f32 v16, v17, v16, 1.0
	v_pk_mul_f32 v[12:13], v[12:13], v[16:17] op_sel_hi:[1,0]
	v_pk_mul_f32 v[14:15], v[14:15], v[16:17] op_sel_hi:[1,0]
	v_pk_mul_f32 v[10:11], v[10:11], v[16:17] op_sel_hi:[1,0]
	v_pk_mul_f32 v[8:9], v[8:9], v[16:17] op_sel_hi:[1,0]
	v_pk_mul_f32 v[6:7], v[6:7], v[16:17] op_sel_hi:[1,0]
	v_pk_mul_f32 v[4:5], v[4:5], v[16:17] op_sel_hi:[1,0]
	v_pk_mul_f32 v[2:3], v[2:3], v[16:17] op_sel_hi:[1,0]
	v_pk_mul_f32 v[0:1], v[0:1], v[16:17] op_sel_hi:[1,0]
	v_mul_f32_e32 v16, 0xbfb8aa3b, v12
	v_exp_f32_e32 v16, v16
	s_andn2_b64 vcc, exec, s[38:39]
	v_add_f32_e32 v16, 1.0, v16
	v_rcp_f32_e32 v16, v16
	s_nop 0
	v_mul_f32_e32 v12, v12, v16
	v_mul_f32_e32 v4, v4, v12
	v_mul_f32_e32 v12, 0xbfb8aa3b, v13
	v_exp_f32_e32 v12, v12
	s_nop 0
	v_add_f32_e32 v12, 1.0, v12
	v_rcp_f32_e32 v12, v12
	s_nop 0
	v_mul_f32_e32 v12, v13, v12
	v_mul_f32_e32 v5, v5, v12
	v_mul_f32_e32 v12, 0xbfb8aa3b, v14
	v_exp_f32_e32 v12, v12
	s_nop 0
	v_add_f32_e32 v12, 1.0, v12
	v_rcp_f32_e32 v12, v12
	s_nop 0
	v_mul_f32_e32 v12, v14, v12
	v_mul_f32_e32 v6, v6, v12
	v_mul_f32_e32 v12, 0xbfb8aa3b, v15
	v_exp_f32_e32 v12, v12
	s_nop 0
	v_add_f32_e32 v12, 1.0, v12
	v_rcp_f32_e32 v12, v12
	s_nop 0
	v_mul_f32_e32 v12, v15, v12
	v_mul_f32_e32 v7, v7, v12
	v_mul_f32_e32 v12, 0xbfb8aa3b, v8
	v_exp_f32_e32 v12, v12
	s_nop 0
	v_add_f32_e32 v12, 1.0, v12
	v_rcp_f32_e32 v12, v12
	s_nop 0
	v_mul_f32_e32 v8, v8, v12
	v_mul_f32_e32 v8, v0, v8
	v_mul_f32_e32 v0, 0xbfb8aa3b, v9
	v_exp_f32_e32 v0, v0
	s_nop 0
	v_add_f32_e32 v0, 1.0, v0
	v_rcp_f32_e32 v0, v0
	s_nop 0
	v_mul_f32_e32 v0, v9, v0
	v_mul_f32_e32 v9, v1, v0
	v_mul_f32_e32 v0, 0xbfb8aa3b, v10
	v_exp_f32_e32 v0, v0
	s_nop 0
	v_add_f32_e32 v0, 1.0, v0
	v_rcp_f32_e32 v0, v0
	s_nop 0
	v_mul_f32_e32 v0, v10, v0
	v_mul_f32_e32 v10, v2, v0
	v_mul_f32_e32 v0, 0xbfb8aa3b, v11
	v_exp_f32_e32 v0, v0
	s_nop 0
	v_add_f32_e32 v0, 1.0, v0
	v_rcp_f32_e32 v0, v0
	s_nop 0
	v_mul_f32_e32 v0, v11, v0
	v_mul_f32_e32 v3, v3, v0
	v_cvt_pk_bf16_f32 v0, v4, v5
	v_lshl_add_u64 v[4:5], v[146:147], 1, v[156:157]
	v_cvt_pk_bf16_f32 v1, v6, v7
	v_cvt_pk_bf16_f32 v2, v8, v9
	v_cvt_pk_bf16_f32 v3, v10, v3
	global_store_dwordx4 v[4:5], v[0:3], off
	s_cbranch_vccnz .LBB0_820
	s_andn2_b64 vcc, exec, s[28:29]
	s_cbranch_vccnz .LBB0_819
	s_barrier
	s_branch .LBB0_819
